# v29 + attention unit: all 8 K/V window loads and 14 Q loads issued up front, counted vmcnt drain (was 4 serial load-wait-write round trips, Q after the barrier)
# baseline (speedup 1.0000x reference)
.LBB0_916:
	s_or_b64 exec, exec, s[4:5]
	s_ashr_i32 s19, s19, 2
	s_and_b32 s22, s19, -16
	v_or_b32_e32 v70, s22, v113
	v_add_u32_e32 v66, s18, v70
	s_and_b32 s18, s19, 0xffffffe0
	v_add_u32_e32 v70, 0x80, v70
	v_or_b32_e32 v71, s18, v110
	v_mov_b64_e32 v[234:235], s[6:7]
	s_lshl_b32 s80, s15, 10
	v_mad_i64_i32 v[234:235], s[4:5], v66, s73, v[234:235]
	v_lshl_add_u64 v[234:235], v[234:235], 0, s[80:81]
	v_lshl_add_u64 v[234:235], v[234:235], 0, v[222:223]
	global_load_dwordx4 v[62:65], v[234:235], off
	global_load_dwordx4 v[58:61], v[234:235], off offset:64
	global_load_dwordx4 v[54:57], v[234:235], off offset:128
	global_load_dwordx4 v[50:53], v[234:235], off offset:192
	global_load_dwordx4 v[46:49], v[234:235], off offset:256
	global_load_dwordx4 v[42:45], v[234:235], off offset:320
	global_load_dwordx4 v[38:41], v[234:235], off offset:384
	global_load_dwordx4 v[34:37], v[234:235], off offset:448
	global_load_dwordx4 v[30:33], v[234:235], off offset:512
	global_load_dwordx4 v[26:29], v[234:235], off offset:576
	global_load_dwordx4 v[22:25], v[234:235], off offset:640
	global_load_dwordx4 v[18:21], v[234:235], off offset:704
	global_load_dwordx4 v[14:17], v[234:235], off offset:768
	global_load_dwordx4 v[10:13], v[234:235], off offset:832
	s_waitcnt vmcnt(21)
	ds_write_b128 v124, v[200:203]
	s_waitcnt vmcnt(20)
	ds_write_b128 v124, v[204:207] offset:36864
	s_waitcnt vmcnt(19)
	ds_write_b128 v125, v[208:211]
	s_waitcnt vmcnt(18)
	ds_write_b128 v125, v[212:215] offset:36864
	s_waitcnt vmcnt(17)
	ds_write_b128 v126, v[226:229]
	s_waitcnt vmcnt(16)
	ds_write_b128 v126, v[230:233] offset:36864
	s_waitcnt vmcnt(15)
	ds_write_b128 v127, v[6:9]
	s_waitcnt vmcnt(14)
	ds_write_b128 v127, v[2:5] offset:36864
	global_load_dwordx4 v[6:9], v[234:235], off offset:896
	global_load_dwordx4 v[2:5], v[234:235], off offset:960
	v_sub_u32_e32 v72, v70, v71
	s_cmp_gt_i32 s14, 0
	v_cmp_gt_u32_e32 vcc, s86, v72
	v_cvt_f32_i32_e32 v72, v72
	s_cselect_b64 s[14:15], -1, 0
	v_cmp_lt_i32_e64 s[4:5], s25, v71
	s_or_b64 s[4:5], s[14:15], s[4:5]
	s_and_b64 vcc, vcc, s[4:5]
	v_cndmask_b32_e32 v129, v248, v72, vcc
	v_xad_u32 v72, v71, -1, v70
	v_cmp_gt_u32_e32 vcc, s86, v72
	v_cvt_f32_i32_e32 v72, v72
	v_cmp_lt_i32_e64 s[4:5], s74, v71
	s_or_b64 s[4:5], s[14:15], s[4:5]
	s_and_b64 vcc, vcc, s[4:5]
	v_cndmask_b32_e32 v130, v248, v72, vcc
	v_or_b32_e32 v72, 2, v71
	v_sub_u32_e32 v73, v70, v72
	v_cmp_lt_i32_e64 s[4:5], s25, v72
	v_cvt_f32_i32_e32 v72, v73
	v_cmp_gt_u32_e32 vcc, s86, v73
	s_or_b64 s[4:5], s[14:15], s[4:5]
	s_and_b64 vcc, vcc, s[4:5]
	v_or_b32_e32 v71, 3, v71
	v_cndmask_b32_e32 v131, v248, v72, vcc
	v_sub_u32_e32 v72, v70, v71
	v_cmp_lt_i32_e64 s[4:5], s25, v71
	v_cvt_f32_i32_e32 v71, v72
	v_cmp_gt_u32_e32 vcc, s86, v72
	s_or_b64 s[4:5], s[14:15], s[4:5]
	s_and_b64 vcc, vcc, s[4:5]
	v_cndmask_b32_e32 v132, v248, v71, vcc
	v_or_b32_e32 v71, s22, v110
	v_or_b32_e32 v72, 16, v71
	v_sub_u32_e32 v73, v70, v72
	v_cmp_lt_i32_e64 s[4:5], s25, v72
	v_cvt_f32_i32_e32 v72, v73
	v_cmp_gt_u32_e32 vcc, s86, v73
	s_or_b64 s[4:5], s[14:15], s[4:5]
	s_and_b64 vcc, vcc, s[4:5]
	v_cndmask_b32_e32 v133, v248, v72, vcc
	v_or_b32_e32 v72, 17, v71
	v_sub_u32_e32 v73, v70, v72
	v_cmp_lt_i32_e64 s[4:5], s25, v72
	v_cvt_f32_i32_e32 v72, v73
	v_cmp_gt_u32_e32 vcc, s86, v73
	s_or_b64 s[4:5], s[14:15], s[4:5]
	s_and_b64 vcc, vcc, s[4:5]
	v_cndmask_b32_e32 v134, v248, v72, vcc
	v_or_b32_e32 v72, 18, v71
	v_sub_u32_e32 v73, v70, v72
	v_cmp_lt_i32_e64 s[4:5], s25, v72
	v_cvt_f32_i32_e32 v72, v73
	v_cmp_gt_u32_e32 vcc, s86, v73
	s_or_b64 s[4:5], s[14:15], s[4:5]
	s_and_b64 vcc, vcc, s[4:5]
	v_or_b32_e32 v71, 19, v71
	v_cndmask_b32_e32 v135, v248, v72, vcc
	v_sub_u32_e32 v72, v70, v71
	v_cmp_lt_i32_e64 s[4:5], s25, v71
	v_cvt_f32_i32_e32 v71, v72
	v_cmp_gt_u32_e32 vcc, s86, v72
	s_or_b64 s[4:5], s[14:15], s[4:5]
	s_and_b64 vcc, vcc, s[4:5]
	v_cndmask_b32_e32 v136, v248, v71, vcc
	v_add_u32_e32 v71, s18, v114
	v_sub_u32_e32 v72, v70, v71
	v_cmp_gt_u32_e32 vcc, s86, v72
	v_cvt_f32_i32_e32 v72, v72
	v_cmp_lt_i32_e64 s[4:5], s25, v71
	s_or_b64 s[4:5], s[14:15], s[4:5]
	s_and_b64 vcc, vcc, s[4:5]
	v_cndmask_b32_e32 v137, v248, v72, vcc
	v_xad_u32 v72, v71, -1, v70
	v_cmp_gt_u32_e32 vcc, s86, v72
	v_cvt_f32_i32_e32 v72, v72
	v_cmp_lt_i32_e64 s[4:5], s74, v71
	s_or_b64 s[4:5], s[14:15], s[4:5]
	s_and_b64 vcc, vcc, s[4:5]
	v_cndmask_b32_e32 v138, v248, v72, vcc
	v_or_b32_e32 v72, 2, v71
	v_sub_u32_e32 v73, v70, v72
	v_cmp_lt_i32_e64 s[4:5], s25, v72
	v_cvt_f32_i32_e32 v72, v73
	v_cmp_gt_u32_e32 vcc, s86, v73
	s_or_b64 s[4:5], s[14:15], s[4:5]
	s_and_b64 vcc, vcc, s[4:5]
	v_or_b32_e32 v71, 3, v71
	v_cndmask_b32_e32 v139, v248, v72, vcc
	v_sub_u32_e32 v72, v70, v71
	v_cmp_lt_i32_e64 s[4:5], s25, v71
	v_cvt_f32_i32_e32 v71, v72
	v_cmp_gt_u32_e32 vcc, s86, v72
	s_or_b64 s[4:5], s[14:15], s[4:5]
	s_and_b64 vcc, vcc, s[4:5]
	v_cndmask_b32_e32 v140, v248, v71, vcc
	v_add_u32_e32 v71, s18, v115
	v_sub_u32_e32 v72, v70, v71
	v_cmp_gt_u32_e32 vcc, s86, v72
	v_cvt_f32_i32_e32 v72, v72
	v_cmp_lt_i32_e64 s[4:5], s25, v71
	s_or_b64 s[4:5], s[14:15], s[4:5]
	s_and_b64 vcc, vcc, s[4:5]
	v_cndmask_b32_e32 v141, v248, v72, vcc
	v_xad_u32 v72, v71, -1, v70
	v_cmp_gt_u32_e32 vcc, s86, v72
	v_cvt_f32_i32_e32 v72, v72
	v_cmp_lt_i32_e64 s[4:5], s74, v71
	s_or_b64 s[4:5], s[14:15], s[4:5]
	s_and_b64 vcc, vcc, s[4:5]
	v_cndmask_b32_e32 v142, v248, v72, vcc
	v_or_b32_e32 v72, 2, v71
	v_sub_u32_e32 v73, v70, v72
	v_cmp_lt_i32_e64 s[4:5], s25, v72
	v_cvt_f32_i32_e32 v72, v73
	v_cmp_gt_u32_e32 vcc, s86, v73
	s_or_b64 s[4:5], s[14:15], s[4:5]
	s_and_b64 vcc, vcc, s[4:5]
	v_or_b32_e32 v71, 3, v71
	v_cndmask_b32_e32 v143, v248, v72, vcc
	v_sub_u32_e32 v72, v70, v71
	v_cmp_lt_i32_e64 s[4:5], s25, v71
	v_cvt_f32_i32_e32 v71, v72
	v_cmp_gt_u32_e32 vcc, s86, v72
	s_or_b64 s[4:5], s[14:15], s[4:5]
	s_and_b64 vcc, vcc, s[4:5]
	v_cndmask_b32_e32 v144, v248, v71, vcc
	v_add_u32_e32 v71, s18, v116
	v_sub_u32_e32 v72, v70, v71
	v_cmp_gt_u32_e32 vcc, s86, v72
	v_cvt_f32_i32_e32 v72, v72
	v_cmp_lt_i32_e64 s[4:5], s25, v71
	s_or_b64 s[4:5], s[14:15], s[4:5]
	s_and_b64 vcc, vcc, s[4:5]
	v_cndmask_b32_e32 v145, v248, v72, vcc
	v_xad_u32 v72, v71, -1, v70
	v_cmp_gt_u32_e32 vcc, s86, v72
	v_cvt_f32_i32_e32 v72, v72
	v_cmp_lt_i32_e64 s[4:5], s74, v71
	s_or_b64 s[4:5], s[14:15], s[4:5]
	s_and_b64 vcc, vcc, s[4:5]
	v_cndmask_b32_e32 v146, v248, v72, vcc
	v_or_b32_e32 v72, 2, v71
	v_sub_u32_e32 v73, v70, v72
	v_cmp_lt_i32_e64 s[4:5], s25, v72
	v_cvt_f32_i32_e32 v72, v73
	v_cmp_gt_u32_e32 vcc, s86, v73
	s_or_b64 s[4:5], s[14:15], s[4:5]
	s_and_b64 vcc, vcc, s[4:5]
	v_or_b32_e32 v71, 3, v71
	v_cndmask_b32_e32 v147, v248, v72, vcc
	v_sub_u32_e32 v72, v70, v71
	v_cmp_lt_i32_e64 s[4:5], s25, v71
	v_cvt_f32_i32_e32 v71, v72
	v_cmp_gt_u32_e32 vcc, s86, v72
	s_or_b64 s[4:5], s[14:15], s[4:5]
	s_and_b64 vcc, vcc, s[4:5]
	v_cndmask_b32_e32 v148, v248, v71, vcc
	v_add_u32_e32 v71, s18, v117
	v_sub_u32_e32 v72, v70, v71
	v_cmp_gt_u32_e32 vcc, s86, v72
	v_cvt_f32_i32_e32 v72, v72
	v_cmp_lt_i32_e64 s[4:5], s25, v71
	s_or_b64 s[4:5], s[14:15], s[4:5]
	s_and_b64 vcc, vcc, s[4:5]
	v_cndmask_b32_e32 v149, v248, v72, vcc
	v_xad_u32 v72, v71, -1, v70
	v_cmp_gt_u32_e32 vcc, s86, v72
	v_cvt_f32_i32_e32 v72, v72
	v_cmp_lt_i32_e64 s[4:5], s74, v71
	s_or_b64 s[4:5], s[14:15], s[4:5]
	s_and_b64 vcc, vcc, s[4:5]
	v_cndmask_b32_e32 v150, v248, v72, vcc
	v_or_b32_e32 v72, 2, v71
	v_sub_u32_e32 v73, v70, v72
	v_cmp_lt_i32_e64 s[4:5], s25, v72
	v_cvt_f32_i32_e32 v72, v73
	v_cmp_gt_u32_e32 vcc, s86, v73
	s_or_b64 s[4:5], s[14:15], s[4:5]
	s_and_b64 vcc, vcc, s[4:5]
	v_or_b32_e32 v71, 3, v71
	v_cndmask_b32_e32 v151, v248, v72, vcc
	v_sub_u32_e32 v72, v70, v71
	v_cmp_lt_i32_e64 s[4:5], s25, v71
	v_cvt_f32_i32_e32 v71, v72
	v_cmp_gt_u32_e32 vcc, s86, v72
	s_or_b64 s[4:5], s[14:15], s[4:5]
	s_and_b64 vcc, vcc, s[4:5]
	v_cndmask_b32_e32 v152, v248, v71, vcc
	v_add_u32_e32 v71, s18, v118
	v_sub_u32_e32 v72, v70, v71
	v_cmp_gt_u32_e32 vcc, s86, v72
	v_cvt_f32_i32_e32 v72, v72
	v_cmp_lt_i32_e64 s[4:5], s25, v71
	s_or_b64 s[4:5], s[14:15], s[4:5]
	s_and_b64 vcc, vcc, s[4:5]
	v_cndmask_b32_e32 v153, v248, v72, vcc
	v_xad_u32 v72, v71, -1, v70
	v_cmp_gt_u32_e32 vcc, s86, v72
	v_cvt_f32_i32_e32 v72, v72
	v_cmp_lt_i32_e64 s[4:5], s74, v71
	s_or_b64 s[4:5], s[14:15], s[4:5]
	s_and_b64 vcc, vcc, s[4:5]
	v_cndmask_b32_e32 v154, v248, v72, vcc
	v_or_b32_e32 v72, 2, v71
	v_sub_u32_e32 v73, v70, v72
	v_cmp_lt_i32_e64 s[4:5], s25, v72
	v_cvt_f32_i32_e32 v72, v73
	v_cmp_gt_u32_e32 vcc, s86, v73
	s_or_b64 s[4:5], s[14:15], s[4:5]
	s_and_b64 vcc, vcc, s[4:5]
	v_or_b32_e32 v71, 3, v71
	v_cndmask_b32_e32 v155, v248, v72, vcc
	v_sub_u32_e32 v72, v70, v71
	v_cmp_lt_i32_e64 s[4:5], s25, v71
	v_cvt_f32_i32_e32 v71, v72
	v_cmp_gt_u32_e32 vcc, s86, v72
	s_or_b64 s[4:5], s[14:15], s[4:5]
	s_and_b64 vcc, vcc, s[4:5]
	v_cndmask_b32_e32 v156, v248, v71, vcc
	v_add_u32_e32 v71, s18, v119
	v_sub_u32_e32 v72, v70, v71
	v_cmp_gt_u32_e32 vcc, s86, v72
	v_cvt_f32_i32_e32 v72, v72
	v_cmp_lt_i32_e64 s[4:5], s25, v71
	s_or_b64 s[4:5], s[14:15], s[4:5]
	s_waitcnt lgkmcnt(0)
	s_barrier
	s_and_b64 vcc, vcc, s[4:5]
	v_cndmask_b32_e32 v157, v248, v72, vcc
	v_xad_u32 v72, v71, -1, v70
	v_cmp_gt_u32_e32 vcc, s86, v72
	v_cvt_f32_i32_e32 v72, v72
	v_cmp_lt_i32_e64 s[4:5], s74, v71
	s_or_b64 s[4:5], s[14:15], s[4:5]
	s_and_b64 vcc, vcc, s[4:5]
	v_cndmask_b32_e32 v158, v248, v72, vcc
	v_or_b32_e32 v72, 2, v71
	v_sub_u32_e32 v73, v70, v72
	v_cmp_lt_i32_e64 s[4:5], s25, v72
	v_cvt_f32_i32_e32 v72, v73
	v_cmp_gt_u32_e32 vcc, s86, v73
	s_or_b64 s[4:5], s[14:15], s[4:5]
	s_and_b64 vcc, vcc, s[4:5]
	v_or_b32_e32 v71, 3, v71
	v_cndmask_b32_e32 v159, v248, v72, vcc
	v_sub_u32_e32 v72, v70, v71
	v_cmp_lt_i32_e64 s[4:5], s25, v71
	v_cvt_f32_i32_e32 v71, v72
	v_cmp_gt_u32_e32 vcc, s86, v72
	s_or_b64 s[4:5], s[14:15], s[4:5]
	s_and_b64 vcc, vcc, s[4:5]
	v_cndmask_b32_e32 v160, v248, v71, vcc
	v_add_u32_e32 v71, s18, v120
	v_sub_u32_e32 v72, v70, v71
	v_cmp_gt_u32_e32 vcc, s86, v72
	v_cvt_f32_i32_e32 v72, v72
	v_cmp_lt_i32_e64 s[4:5], s25, v71
	s_or_b64 s[4:5], s[14:15], s[4:5]
	s_and_b64 vcc, vcc, s[4:5]
	v_cndmask_b32_e32 v161, v248, v72, vcc
	v_xad_u32 v72, v71, -1, v70
	v_cmp_gt_u32_e32 vcc, s86, v72
	v_cvt_f32_i32_e32 v72, v72
	v_cmp_lt_i32_e64 s[4:5], s74, v71
	s_or_b64 s[4:5], s[14:15], s[4:5]
	s_and_b64 vcc, vcc, s[4:5]
	v_cndmask_b32_e32 v162, v248, v72, vcc
	v_or_b32_e32 v72, 2, v71
	v_sub_u32_e32 v73, v70, v72
	v_cmp_lt_i32_e64 s[4:5], s25, v72
	v_cvt_f32_i32_e32 v72, v73
	v_cmp_gt_u32_e32 vcc, s86, v73
	s_or_b64 s[4:5], s[14:15], s[4:5]
	s_and_b64 vcc, vcc, s[4:5]
	v_or_b32_e32 v71, 3, v71
	v_cndmask_b32_e32 v163, v248, v72, vcc
	v_sub_u32_e32 v72, v70, v71
	v_cmp_lt_i32_e64 s[4:5], s25, v71
	v_cvt_f32_i32_e32 v71, v72
	v_cmp_gt_u32_e32 vcc, s86, v72
	s_or_b64 s[4:5], s[14:15], s[4:5]
	s_and_b64 vcc, vcc, s[4:5]
	v_cndmask_b32_e32 v164, v248, v71, vcc
	v_add_u32_e32 v71, s18, v121
	v_sub_u32_e32 v72, v70, v71
	v_cmp_gt_u32_e32 vcc, s86, v72
	v_cvt_f32_i32_e32 v72, v72
	v_cmp_lt_i32_e64 s[4:5], s25, v71
	s_or_b64 s[4:5], s[14:15], s[4:5]
	s_and_b64 vcc, vcc, s[4:5]
	v_cndmask_b32_e32 v165, v248, v72, vcc
	v_xad_u32 v72, v71, -1, v70
	v_cmp_gt_u32_e32 vcc, s86, v72
	v_cvt_f32_i32_e32 v72, v72
	v_cmp_lt_i32_e64 s[4:5], s74, v71
	s_or_b64 s[4:5], s[14:15], s[4:5]
	s_and_b64 vcc, vcc, s[4:5]
	v_cndmask_b32_e32 v166, v248, v72, vcc
	v_or_b32_e32 v72, 2, v71
	v_sub_u32_e32 v73, v70, v72
	v_cmp_lt_i32_e64 s[4:5], s25, v72
	v_cvt_f32_i32_e32 v72, v73
	v_cmp_gt_u32_e32 vcc, s86, v73
	s_or_b64 s[4:5], s[14:15], s[4:5]
	v_or_b32_e32 v71, 3, v71
	s_and_b64 vcc, vcc, s[4:5]
	v_sub_u32_e32 v70, v70, v71
	v_cmp_lt_i32_e64 s[4:5], s25, v71
	v_or_b32_e32 v68, s18, v113
	v_or_b32_e32 v69, s18, v111
	v_cndmask_b32_e32 v167, v248, v72, vcc
	v_cmp_gt_u32_e32 vcc, s86, v70
	s_or_b64 s[4:5], s[14:15], s[4:5]
	v_ashrrev_i32_e32 v67, 31, v66
	s_and_b64 vcc, vcc, s[4:5]
	v_cvt_f32_i32_e32 v70, v70
	v_mad_u64_u32 v[100:101], s[4:5], v68, s88, v[92:93]
	v_mad_u64_u32 v[98:99], s[4:5], v69, s88, v[94:95]
	v_lshlrev_b64 v[66:67], 12, v[66:67]
	s_or_b32 s4, s17, 1
	v_lshl_add_u64 v[102:103], v[96:97], 0, v[66:67]
	v_cvt_f32_ubyte0_e32 v66, s4
	v_mul_f32_e32 v66, -0.5, v66
	v_cndmask_b32_e32 v168, v248, v70, vcc
	v_exp_f32_e32 v99, v66
	ds_read_b128 v[66:69], v100
	ds_read_b128 v[70:73], v100 offset:64
	s_waitcnt vmcnt(15) lgkmcnt(1)
	v_mfma_f32_16x16x32_bf16 v[66:69], v[66:69], v[62:65], 0
	v_readlane_b32 s4, v128, 0
	s_add_i32 s9, s9, s16
	s_waitcnt vmcnt(14) lgkmcnt(0)
	v_mfma_f32_16x16x32_bf16 v[66:69], v[70:73], v[58:61], v[66:69]
	ds_read_b128 v[70:73], v100 offset:2304
	ds_read_b128 v[74:77], v100 offset:2368
	s_waitcnt lgkmcnt(1)
	v_mfma_f32_16x16x32_bf16 v[70:73], v[70:73], v[62:65], 0
	s_waitcnt lgkmcnt(0)
	v_mfma_f32_16x16x32_bf16 v[70:73], v[74:77], v[58:61], v[70:73]
	ds_read_b128 v[74:77], v100 offset:4608
	ds_read_b128 v[78:81], v100 offset:4672
	s_waitcnt lgkmcnt(1)
	v_mfma_f32_16x16x32_bf16 v[74:77], v[74:77], v[62:65], 0
	s_waitcnt lgkmcnt(0)
	v_mfma_f32_16x16x32_bf16 v[74:77], v[78:81], v[58:61], v[74:77]
	ds_read_b128 v[78:81], v100 offset:6912
	ds_read_b128 v[82:85], v100 offset:6976
	s_waitcnt lgkmcnt(1)
	v_mfma_f32_16x16x32_bf16 v[78:81], v[78:81], v[62:65], 0
	s_waitcnt lgkmcnt(0)
	v_mfma_f32_16x16x32_bf16 v[78:81], v[82:85], v[58:61], v[78:81]
	ds_read_b128 v[82:85], v100 offset:9216
	ds_read_b128 v[86:89], v100 offset:9280
	s_waitcnt lgkmcnt(1)
	v_mfma_f32_16x16x32_bf16 v[82:85], v[82:85], v[62:65], 0
	s_waitcnt lgkmcnt(0)
	v_mfma_f32_16x16x32_bf16 v[82:85], v[86:89], v[58:61], v[82:85]
	ds_read_b128 v[86:89], v100 offset:11520
	ds_read_b128 v[170:173], v100 offset:11584
	s_waitcnt lgkmcnt(1)
	v_mfma_f32_16x16x32_bf16 v[86:89], v[86:89], v[62:65], 0
	s_waitcnt lgkmcnt(0)
	v_mfma_f32_16x16x32_bf16 v[86:89], v[170:173], v[58:61], v[86:89]
	ds_read_b128 v[170:173], v100 offset:13824
	ds_read_b128 v[174:177], v100 offset:13888
	s_waitcnt lgkmcnt(1)
	v_mfma_f32_16x16x32_bf16 v[170:173], v[170:173], v[62:65], 0
	s_waitcnt lgkmcnt(0)
	v_mfma_f32_16x16x32_bf16 v[170:173], v[174:177], v[58:61], v[170:173]
	ds_read_b128 v[174:177], v100 offset:16128
	ds_read_b128 v[178:181], v100 offset:16192
	s_waitcnt lgkmcnt(1)
	v_mfma_f32_16x16x32_bf16 v[174:177], v[174:177], v[62:65], 0
	s_nop 3
	v_mul_f32_e32 v101, 0x3e38aa3b, v172
	v_mul_f32_e32 v169, 0x3e38aa3b, v173
	s_waitcnt lgkmcnt(0)
	v_mfma_f32_16x16x32_bf16 v[174:177], v[178:181], v[58:61], v[174:177]
	ds_read_b128 v[178:181], v100 offset:18432
	ds_read_b128 v[182:185], v100 offset:18496
	s_waitcnt lgkmcnt(1)
	v_mfma_f32_16x16x32_bf16 v[178:181], v[178:181], v[62:65], 0
	s_nop 3
	v_mul_f32_e32 v172, 0x3e38aa3b, v176
	v_mul_f32_e32 v173, 0x3e38aa3b, v177
	s_waitcnt lgkmcnt(0)
	v_mfma_f32_16x16x32_bf16 v[178:181], v[182:185], v[58:61], v[178:181]
	ds_read_b128 v[182:185], v100 offset:20736
	ds_read_b128 v[186:189], v100 offset:20800
	s_waitcnt lgkmcnt(1)
	v_mfma_f32_16x16x32_bf16 v[62:65], v[182:185], v[62:65], 0
	s_nop 3
	v_mul_f32_e32 v176, 0x3e38aa3b, v180
	v_mul_f32_e32 v177, 0x3e38aa3b, v181
	s_waitcnt lgkmcnt(0)
	v_mfma_f32_16x16x32_bf16 v[58:61], v[186:189], v[58:61], v[62:65]
	s_nop 2
	v_mul_f32_e32 v62, 0xbfb8aa3b, v99
	v_mul_f32_e32 v63, 0x3e38aa3b, v66
	v_mul_f32_e32 v64, 0x3e38aa3b, v67
	v_fmac_f32_e32 v63, v129, v62
	v_fmac_f32_e32 v64, v130, v62
	v_mul_f32_e32 v66, 0x3e38aa3b, v68
	v_mul_f32_e32 v67, 0x3e38aa3b, v69
	v_max3_f32 v65, v63, s75, v64
	v_fmac_f32_e32 v66, v131, v62
	v_fmac_f32_e32 v67, v132, v62
	v_mul_f32_e32 v68, 0x3e38aa3b, v70
	v_mul_f32_e32 v69, 0x3e38aa3b, v71
	v_max3_f32 v65, v65, v66, v67
	v_fmac_f32_e32 v68, v133, v62
	v_fmac_f32_e32 v69, v134, v62
	v_mul_f32_e32 v70, 0x3e38aa3b, v72
	v_mul_f32_e32 v71, 0x3e38aa3b, v73
	v_max3_f32 v65, v65, v68, v69
	v_fmac_f32_e32 v70, v135, v62
	v_fmac_f32_e32 v71, v136, v62
	v_mul_f32_e32 v72, 0x3e38aa3b, v74
	v_mul_f32_e32 v73, 0x3e38aa3b, v75
	v_max3_f32 v65, v65, v70, v71
	v_fmac_f32_e32 v72, v137, v62
	v_fmac_f32_e32 v73, v138, v62
	v_mul_f32_e32 v74, 0x3e38aa3b, v76
	v_mul_f32_e32 v75, 0x3e38aa3b, v77
	v_max3_f32 v65, v65, v72, v73
	v_fmac_f32_e32 v74, v139, v62
	v_fmac_f32_e32 v75, v140, v62
	v_mul_f32_e32 v77, 0x3e38aa3b, v78
	v_mul_f32_e32 v78, 0x3e38aa3b, v79
	v_max3_f32 v65, v65, v74, v75
	v_fmac_f32_e32 v77, v141, v62
	v_fmac_f32_e32 v78, v142, v62
	v_mul_f32_e32 v79, 0x3e38aa3b, v80
	v_mul_f32_e32 v80, 0x3e38aa3b, v81
	v_max3_f32 v65, v65, v77, v78
	v_fmac_f32_e32 v79, v143, v62
	v_fmac_f32_e32 v80, v144, v62
	v_mul_f32_e32 v81, 0x3e38aa3b, v82
	v_mul_f32_e32 v82, 0x3e38aa3b, v83
	v_max3_f32 v65, v65, v79, v80
	v_fmac_f32_e32 v81, v145, v62
	v_fmac_f32_e32 v82, v146, v62
	v_mul_f32_e32 v83, 0x3e38aa3b, v84
	v_mul_f32_e32 v84, 0x3e38aa3b, v85
	v_max3_f32 v65, v65, v81, v82
	v_fmac_f32_e32 v83, v147, v62
	v_fmac_f32_e32 v84, v148, v62
	v_mul_f32_e32 v85, 0x3e38aa3b, v86
	v_mul_f32_e32 v86, 0x3e38aa3b, v87
	v_max3_f32 v65, v65, v83, v84
	v_fmac_f32_e32 v85, v149, v62
	v_fmac_f32_e32 v86, v150, v62
	v_mul_f32_e32 v87, 0x3e38aa3b, v88
	v_mul_f32_e32 v88, 0x3e38aa3b, v89
	v_max3_f32 v65, v65, v85, v86
	v_fmac_f32_e32 v87, v151, v62
	v_fmac_f32_e32 v88, v152, v62
	v_mul_f32_e32 v89, 0x3e38aa3b, v170
	v_mul_f32_e32 v99, 0x3e38aa3b, v171
	v_max3_f32 v65, v65, v87, v88
	v_fmac_f32_e32 v89, v153, v62
	v_fmac_f32_e32 v99, v154, v62
	v_max3_f32 v65, v65, v89, v99
	v_fmac_f32_e32 v101, v155, v62
	v_fmac_f32_e32 v169, v156, v62
	v_mul_f32_e32 v170, 0x3e38aa3b, v174
	v_mul_f32_e32 v171, 0x3e38aa3b, v175
	v_max3_f32 v65, v65, v101, v169
	v_fmac_f32_e32 v170, v157, v62
	v_fmac_f32_e32 v171, v158, v62
	v_max3_f32 v65, v65, v170, v171
	v_fmac_f32_e32 v172, v159, v62
	v_fmac_f32_e32 v173, v160, v62
	v_mul_f32_e32 v174, 0x3e38aa3b, v178
	v_mul_f32_e32 v175, 0x3e38aa3b, v179
	v_max3_f32 v65, v65, v172, v173
	v_fmac_f32_e32 v174, v161, v62
	v_fmac_f32_e32 v175, v162, v62
	v_max3_f32 v65, v65, v174, v175
	v_fmac_f32_e32 v176, v163, v62
	v_fmac_f32_e32 v177, v164, v62
	v_mul_f32_e32 v58, 0x3e38aa3b, v58
	v_mul_f32_e32 v178, 0x3e38aa3b, v59
	v_max3_f32 v65, v65, v176, v177
	v_fmac_f32_e32 v58, v165, v62
	v_fmac_f32_e32 v178, v166, v62
	v_max3_f32 v59, v65, v58, v178
	v_mul_f32_e32 v65, 0x3e38aa3b, v60
	v_mul_f32_e32 v179, 0x3e38aa3b, v61
	v_fmac_f32_e32 v65, v167, v62
	v_fmac_f32_e32 v179, v168, v62
	v_max3_f32 v59, v59, v65, v179
	v_mov_b32_e32 v61, v59
	s_nop 1
	v_permlane16_swap_b32_e32 v61, v59
	v_mul_f32_e32 v60, s4, v249
	s_waitcnt lgkmcnt(0)
	v_max_f32_e32 v61, v61, v61
	v_max_f32_e32 v59, v59, v61
	v_mov_b32_e32 v61, v59
	s_nop 1
	v_permlane32_swap_b32_e32 v61, v59
	s_waitcnt lgkmcnt(0)
	v_max3_f32 v180, v59, v61, v60
	v_sub_f32_e32 v59, v63, v180
	v_exp_f32_e32 v181, v59
	v_sub_f32_e32 v60, v64, v180
	v_exp_f32_e32 v182, v60
	v_sub_f32_e32 v60, v66, v180
	v_exp_f32_e32 v183, v60
	v_sub_f32_e32 v60, v67, v180
	v_exp_f32_e32 v184, v60
	v_sub_f32_e32 v60, v68, v180
	v_add_f32_e32 v59, 0, v181
	v_exp_f32_e32 v185, v60
	v_sub_f32_e32 v60, v69, v180
	v_add_f32_e32 v59, v182, v59
	v_exp_f32_e32 v186, v60
	v_sub_f32_e32 v60, v70, v180
	v_add_f32_e32 v59, v183, v59
	v_exp_f32_e32 v187, v60
	v_sub_f32_e32 v60, v71, v180
	v_add_f32_e32 v59, v184, v59
	v_exp_f32_e32 v188, v60
	v_sub_f32_e32 v60, v72, v180
	v_add_f32_e32 v59, v185, v59
	v_exp_f32_e32 v76, v60
	v_sub_f32_e32 v60, v73, v180
	v_add_f32_e32 v59, v186, v59
	v_exp_f32_e32 v189, v60
	v_sub_f32_e32 v60, v74, v180
	v_add_f32_e32 v59, v187, v59
	v_exp_f32_e32 v190, v60
	v_sub_f32_e32 v60, v75, v180
	v_add_f32_e32 v59, v188, v59
	v_exp_f32_e32 v191, v60
	v_sub_f32_e32 v60, v77, v180
	v_add_f32_e32 v59, v76, v59
	v_exp_f32_e32 v192, v60
	v_sub_f32_e32 v60, v78, v180
	v_add_f32_e32 v59, v189, v59
	v_exp_f32_e32 v193, v60
	v_sub_f32_e32 v60, v79, v180
	v_add_f32_e32 v59, v190, v59
	v_exp_f32_e32 v194, v60
	v_sub_f32_e32 v60, v80, v180
	v_add_f32_e32 v59, v191, v59
	v_exp_f32_e32 v195, v60
	v_sub_f32_e32 v60, v81, v180
	v_add_f32_e32 v59, v192, v59
	v_exp_f32_e32 v70, v60
	v_sub_f32_e32 v60, v82, v180
	v_add_f32_e32 v59, v193, v59
	v_exp_f32_e32 v72, v60
	v_sub_f32_e32 v60, v83, v180
	v_add_f32_e32 v59, v194, v59
	v_exp_f32_e32 v75, v60
	v_sub_f32_e32 v60, v84, v180
	v_add_f32_e32 v59, v195, v59
	v_exp_f32_e32 v78, v60
	v_sub_f32_e32 v60, v85, v180
	v_add_f32_e32 v59, v70, v59
	v_exp_f32_e32 v196, v60
	v_sub_f32_e32 v60, v86, v180
	v_add_f32_e32 v59, v72, v59
	v_exp_f32_e32 v197, v60
	v_sub_f32_e32 v60, v87, v180
	v_add_f32_e32 v59, v75, v59
	v_exp_f32_e32 v198, v60
	v_sub_f32_e32 v60, v88, v180
	v_add_f32_e32 v59, v78, v59
	v_exp_f32_e32 v88, v60
	v_sub_f32_e32 v60, v89, v180
	v_add_f32_e32 v59, v196, v59
	v_exp_f32_e32 v67, v60
	v_sub_f32_e32 v60, v99, v180
	v_add_f32_e32 v59, v197, v59
	v_exp_f32_e32 v68, v60
	v_sub_f32_e32 v60, v101, v180
	v_add_f32_e32 v59, v198, v59
	v_exp_f32_e32 v69, v60
	v_sub_f32_e32 v60, v169, v180
	v_add_f32_e32 v59, v88, v59
	v_exp_f32_e32 v71, v60
	v_sub_f32_e32 v60, v170, v180
	v_add_f32_e32 v59, v67, v59
	v_exp_f32_e32 v73, v60
	v_sub_f32_e32 v60, v171, v180
	v_add_f32_e32 v59, v68, v59
	v_exp_f32_e32 v74, v60
	v_sub_f32_e32 v60, v172, v180
	v_add_f32_e32 v59, v69, v59
	v_exp_f32_e32 v77, v60
	v_sub_f32_e32 v60, v173, v180
	v_add_f32_e32 v59, v71, v59
	v_exp_f32_e32 v79, v60
	v_add_f32_e32 v59, v73, v59
	v_add_f32_e32 v59, v74, v59
	v_add_f32_e32 v59, v77, v59
	v_add_f32_e32 v60, v79, v59
	v_sub_f32_e32 v59, v174, v180
	v_exp_f32_e32 v59, v59
	v_sub_f32_e32 v58, v58, v180
	v_sub_f32_e32 v65, v65, v180
	v_exp_f32_e32 v65, v65
	v_add_f32_e32 v61, v59, v60
	v_sub_f32_e32 v60, v175, v180
	v_exp_f32_e32 v60, v60
	v_sub_f32_e32 v66, v179, v180
	v_exp_f32_e32 v66, v66
	v_add_f32_e32 v62, v60, v61
	v_sub_f32_e32 v61, v176, v180
	v_exp_f32_e32 v61, v61
	s_nop 0
	v_add_f32_e32 v63, v61, v62
	v_sub_f32_e32 v62, v177, v180
	v_exp_f32_e32 v62, v62
	s_nop 0
	v_add_f32_e32 v64, v62, v63
	v_exp_f32_e32 v63, v58
	s_nop 0
	v_add_f32_e32 v58, v63, v64
	v_sub_f32_e32 v64, v178, v180
	v_exp_f32_e32 v64, v64
	s_nop 0
	v_add_f32_e32 v58, v64, v58
	v_add_f32_e32 v58, v65, v58
	v_add_f32_e32 v58, v66, v58
	v_mov_b32_e32 v80, v58
	s_nop 1
	v_permlane16_swap_b32_e32 v80, v58
	s_waitcnt lgkmcnt(0)
	v_add_f32_e32 v58, v58, v80
	v_mov_b32_e32 v80, v58
	s_nop 1
	v_permlane32_swap_b32_e32 v80, v58
	s_waitcnt lgkmcnt(0)
	v_add_f32_e32 v58, v58, v80
	v_fma_f32 v80, s4, v249, -v180
	v_exp_f32_e32 v80, v80
	s_nop 0
	v_add_f32_e32 v58, v80, v58
	v_cvt_pk_bf16_f32 v80, v181, v182
	v_cvt_pk_bf16_f32 v81, v183, v184
	v_cvt_pk_bf16_f32 v82, v185, v186
	v_cvt_pk_bf16_f32 v83, v187, v188
	ds_read_b64_tr_b16 v[86:87], v98 offset:39168
	ds_read_b64_tr_b16 v[84:85], v98 offset:36864
	ds_read_b64_tr_b16 v[170:171], v98 offset:36896
	ds_read_b64_tr_b16 v[172:173], v98 offset:39200
	ds_read_b64_tr_b16 v[174:175], v98 offset:36928
	ds_read_b64_tr_b16 v[176:177], v98 offset:39232
	ds_read_b64_tr_b16 v[178:179], v98 offset:36960
	ds_read_b64_tr_b16 v[180:181], v98 offset:39264
	s_waitcnt lgkmcnt(6)
	v_mfma_f32_16x16x32_bf16 v[84:87], v[84:87], v[80:83], 0
	s_waitcnt lgkmcnt(4)
	v_mfma_f32_16x16x32_bf16 v[170:173], v[170:173], v[80:83], 0
	s_waitcnt lgkmcnt(2)
	v_mfma_f32_16x16x32_bf16 v[174:177], v[174:177], v[80:83], 0
	s_waitcnt lgkmcnt(0)
	v_mfma_f32_16x16x32_bf16 v[80:83], v[178:181], v[80:83], 0
	v_cvt_pk_bf16_f32 v178, v76, v189
	v_cvt_pk_bf16_f32 v179, v190, v191
	v_cvt_pk_bf16_f32 v180, v192, v193
	v_cvt_pk_bf16_f32 v181, v194, v195
	ds_read_b64_tr_b16 v[184:185], v98 offset:43776
	ds_read_b64_tr_b16 v[182:183], v98 offset:41472
	ds_read_b64_tr_b16 v[186:187], v98 offset:41504
	s_waitcnt lgkmcnt(1)
	v_mfma_f32_16x16x32_bf16 v[84:87], v[182:185], v[178:181], v[84:87]
	ds_read_b64_tr_b16 v[188:189], v98 offset:43808
	ds_read_b64_tr_b16 v[182:183], v98 offset:41536
	ds_read_b64_tr_b16 v[184:185], v98 offset:43840
	s_waitcnt lgkmcnt(0)
	v_mfma_f32_16x16x32_bf16 v[174:177], v[182:185], v[178:181], v[174:177]
	ds_read_b64_tr_b16 v[182:183], v98 offset:41568
	ds_read_b64_tr_b16 v[184:185], v98 offset:43872
	v_mfma_f32_16x16x32_bf16 v[170:173], v[186:189], v[178:181], v[170:173]
	s_waitcnt lgkmcnt(0)
	v_mfma_f32_16x16x32_bf16 v[80:83], v[182:185], v[178:181], v[80:83]
	v_cvt_pk_bf16_f32 v178, v70, v72
	v_cvt_pk_bf16_f32 v179, v75, v78
	v_cvt_pk_bf16_f32 v180, v196, v197
	v_cvt_pk_bf16_f32 v181, v198, v88
	ds_read_b64_tr_b16 v[184:185], v98 offset:48384
	ds_read_b64_tr_b16 v[182:183], v98 offset:46080
	ds_read_b64_tr_b16 v[186:187], v98 offset:46112
	s_waitcnt lgkmcnt(1)
	v_mfma_f32_16x16x32_bf16 v[84:87], v[182:185], v[178:181], v[84:87]
	ds_read_b64_tr_b16 v[188:189], v98 offset:48416
	ds_read_b64_tr_b16 v[182:183], v98 offset:46144
	ds_read_b64_tr_b16 v[184:185], v98 offset:48448
	s_waitcnt lgkmcnt(0)
	v_mfma_f32_16x16x32_bf16 v[174:177], v[182:185], v[178:181], v[174:177]
	ds_read_b64_tr_b16 v[182:183], v98 offset:46176
	ds_read_b64_tr_b16 v[184:185], v98 offset:48480
	v_cvt_pk_bf16_f32 v68, v67, v68
	v_cvt_pk_bf16_f32 v69, v69, v71
	v_cvt_pk_bf16_f32 v70, v73, v74
	v_cvt_pk_bf16_f32 v71, v77, v79
	ds_read_b64_tr_b16 v[74:75], v98 offset:52992
	ds_read_b64_tr_b16 v[72:73], v98 offset:50688
	ds_read_b64_tr_b16 v[76:77], v98 offset:50720
	ds_read_b64_tr_b16 v[78:79], v98 offset:53024
	v_mfma_f32_16x16x32_bf16 v[170:173], v[186:189], v[178:181], v[170:173]
	s_waitcnt lgkmcnt(2)
	v_mfma_f32_16x16x32_bf16 v[72:75], v[72:75], v[68:71], v[84:87]
	s_nop 2
	ds_read_b64_tr_b16 v[84:85], v98 offset:50752
	ds_read_b64_tr_b16 v[86:87], v98 offset:53056
	s_waitcnt lgkmcnt(2)
	v_mfma_f32_16x16x32_bf16 v[76:79], v[76:79], v[68:71], v[170:173]
	s_nop 2
	ds_read_b64_tr_b16 v[170:171], v98 offset:50784
	ds_read_b64_tr_b16 v[172:173], v98 offset:53088
	v_cvt_pk_bf16_f32 v60, v59, v60
	v_cvt_pk_bf16_f32 v61, v61, v62
	v_mfma_f32_16x16x32_bf16 v[80:83], v[182:185], v[178:181], v[80:83]
	v_cvt_pk_bf16_f32 v62, v63, v64
	v_cvt_pk_bf16_f32 v63, v65, v66
	v_div_scale_f32 v59, s[4:5], v58, v58, 1.0
	s_waitcnt lgkmcnt(2)
	v_mfma_f32_16x16x32_bf16 v[84:87], v[84:87], v[68:71], v[174:177]
	s_or_b32 s4, s17, 2
	s_waitcnt lgkmcnt(0)
	v_mfma_f32_16x16x32_bf16 v[68:71], v[170:173], v[68:71], v[80:83]
	ds_read_b64_tr_b16 v[66:67], v98 offset:57600
	ds_read_b64_tr_b16 v[64:65], v98 offset:55296
	s_nop 0
	ds_read_b64_tr_b16 v[80:81], v98 offset:55328
	ds_read_b64_tr_b16 v[82:83], v98 offset:57632
	s_waitcnt lgkmcnt(2)
	v_mfma_f32_16x16x32_bf16 v[64:67], v[64:67], v[60:63], v[72:75]
	s_waitcnt lgkmcnt(0)
	v_mfma_f32_16x16x32_bf16 v[72:75], v[80:83], v[60:63], v[76:79]
	s_nop 2
	ds_read_b64_tr_b16 v[76:77], v98 offset:55360
	ds_read_b64_tr_b16 v[78:79], v98 offset:57664
	ds_read_b64_tr_b16 v[80:81], v98 offset:55392
	ds_read_b64_tr_b16 v[82:83], v98 offset:57696
	s_waitcnt lgkmcnt(2)
	v_mfma_f32_16x16x32_bf16 v[76:79], v[76:79], v[60:63], v[84:87]
	s_waitcnt lgkmcnt(0)
	v_mfma_f32_16x16x32_bf16 v[60:63], v[80:83], v[60:63], v[68:71]
	s_nop 2
	v_rcp_f32_e32 v68, v59
	s_nop 0
	v_fma_f32 v69, -v59, v68, 1.0
	v_fmac_f32_e32 v68, v69, v68
	v_div_scale_f32 v69, vcc, 1.0, v58, 1.0
	v_mul_f32_e32 v70, v69, v68
	v_fma_f32 v71, -v59, v70, v69
	v_fmac_f32_e32 v70, v71, v68
	v_fma_f32 v59, -v59, v70, v69
	v_div_fmas_f32 v59, v59, v68, v70
	v_div_fixup_f32 v68, v59, v58, 1.0
	v_pk_mul_f32 v[66:67], v[68:69], v[66:67] op_sel_hi:[0,1]
	v_pk_mul_f32 v[64:65], v[68:69], v[64:65] op_sel_hi:[0,1]
	v_lshl_add_u64 v[58:59], v[102:103], 0, s[80:81]
	v_pk_mul_f32 v[70:71], v[68:69], v[74:75] op_sel_hi:[0,1]
	v_pk_mul_f32 v[72:73], v[68:69], v[72:73] op_sel_hi:[0,1]
	v_cvt_pk_bf16_f32 v64, v64, v65
	v_cvt_pk_bf16_f32 v65, v66, v67
	v_cvt_pk_bf16_f32 v66, v72, v73
	v_cvt_pk_bf16_f32 v67, v70, v71
	global_store_dwordx4 v[58:59], v[64:67], off
	v_pk_mul_f32 v[70:71], v[68:69], v[62:63] op_sel_hi:[0,1]
	v_pk_mul_f32 v[62:63], v[68:69], v[60:61] op_sel_hi:[0,1]
	v_pk_mul_f32 v[66:67], v[68:69], v[76:77] op_sel_hi:[0,1]
	v_cvt_pk_bf16_f32 v60, v66, v67
	v_pk_mul_f32 v[64:65], v[68:69], v[78:79] op_sel_hi:[0,1]
	v_cvt_pk_bf16_f32 v61, v64, v65
	v_cvt_pk_bf16_f32 v62, v62, v63
	v_cvt_pk_bf16_f32 v63, v70, v71
	global_store_dwordx4 v[58:59], v[60:63], off offset:64
	s_nop 1
	v_cvt_f32_ubyte0_e32 v60, s4
	v_mul_f32_e32 v60, -0.5, v60
	v_exp_f32_e32 v88, v60
	ds_read_b128 v[60:63], v100
	ds_read_b128 v[64:67], v100 offset:64
	s_waitcnt vmcnt(15) lgkmcnt(1)
	v_mfma_f32_16x16x32_bf16 v[60:63], v[60:63], v[54:57], 0
	v_readlane_b32 s4, v128, 1
	s_waitcnt vmcnt(14) lgkmcnt(0)
	v_mfma_f32_16x16x32_bf16 v[60:63], v[64:67], v[50:53], v[60:63]
	ds_read_b128 v[64:67], v100 offset:2304
	ds_read_b128 v[68:71], v100 offset:2368
	s_waitcnt lgkmcnt(1)
	v_mfma_f32_16x16x32_bf16 v[64:67], v[64:67], v[54:57], 0
	s_waitcnt lgkmcnt(0)
	v_mfma_f32_16x16x32_bf16 v[64:67], v[68:71], v[50:53], v[64:67]
	ds_read_b128 v[68:71], v100 offset:4608
	ds_read_b128 v[72:75], v100 offset:4672
	s_waitcnt lgkmcnt(1)
	v_mfma_f32_16x16x32_bf16 v[68:71], v[68:71], v[54:57], 0
	s_waitcnt lgkmcnt(0)
	v_mfma_f32_16x16x32_bf16 v[68:71], v[72:75], v[50:53], v[68:71]
	ds_read_b128 v[72:75], v100 offset:6912
	ds_read_b128 v[76:79], v100 offset:6976
	s_waitcnt lgkmcnt(1)
	v_mfma_f32_16x16x32_bf16 v[72:75], v[72:75], v[54:57], 0
	s_waitcnt lgkmcnt(0)
	v_mfma_f32_16x16x32_bf16 v[72:75], v[76:79], v[50:53], v[72:75]
	ds_read_b128 v[76:79], v100 offset:9216
	ds_read_b128 v[80:83], v100 offset:9280
	s_waitcnt lgkmcnt(1)
	v_mfma_f32_16x16x32_bf16 v[76:79], v[76:79], v[54:57], 0
	s_waitcnt lgkmcnt(0)
	v_mfma_f32_16x16x32_bf16 v[76:79], v[80:83], v[50:53], v[76:79]
	ds_read_b128 v[80:83], v100 offset:11520
	ds_read_b128 v[84:87], v100 offset:11584
	s_waitcnt lgkmcnt(1)
	v_mfma_f32_16x16x32_bf16 v[80:83], v[80:83], v[54:57], 0
	s_waitcnt lgkmcnt(0)
	v_mfma_f32_16x16x32_bf16 v[80:83], v[84:87], v[50:53], v[80:83]
	ds_read_b128 v[84:87], v100 offset:13824
	ds_read_b128 v[170:173], v100 offset:13888
	s_waitcnt lgkmcnt(1)
	v_mfma_f32_16x16x32_bf16 v[84:87], v[84:87], v[54:57], 0
	s_waitcnt lgkmcnt(0)
	v_mfma_f32_16x16x32_bf16 v[84:87], v[170:173], v[50:53], v[84:87]
	ds_read_b128 v[170:173], v100 offset:16128
	ds_read_b128 v[174:177], v100 offset:16192
	s_waitcnt lgkmcnt(1)
	v_mfma_f32_16x16x32_bf16 v[170:173], v[170:173], v[54:57], 0
	s_waitcnt lgkmcnt(0)
	v_mfma_f32_16x16x32_bf16 v[170:173], v[174:177], v[50:53], v[170:173]
	ds_read_b128 v[174:177], v100 offset:18432
	ds_read_b128 v[178:181], v100 offset:18496
	s_waitcnt lgkmcnt(1)
	v_mfma_f32_16x16x32_bf16 v[174:177], v[174:177], v[54:57], 0
	s_nop 3
	v_mul_f32_e32 v89, 0x3e38aa3b, v172
	v_mul_f32_e32 v99, 0x3e38aa3b, v173
	s_waitcnt lgkmcnt(0)
	v_mfma_f32_16x16x32_bf16 v[174:177], v[178:181], v[50:53], v[174:177]
	ds_read_b128 v[178:181], v100 offset:20736
	ds_read_b128 v[182:185], v100 offset:20800
	s_waitcnt lgkmcnt(1)
	v_mfma_f32_16x16x32_bf16 v[54:57], v[178:181], v[54:57], 0
	s_nop 3
	v_mul_f32_e32 v101, 0x3e38aa3b, v174
	v_mul_f32_e32 v102, 0x3e38aa3b, v175
	v_mul_f32_e32 v103, 0x3e38aa3b, v176
	s_waitcnt lgkmcnt(0)
	v_mfma_f32_16x16x32_bf16 v[50:53], v[182:185], v[50:53], v[54:57]
	v_mul_f32_e32 v169, 0x3e38aa3b, v177
	s_nop 1
	v_mul_f32_e32 v54, 0xbfb8aa3b, v88
	v_mul_f32_e32 v55, 0x3e38aa3b, v60
	v_mul_f32_e32 v56, 0x3e38aa3b, v61
	v_fmac_f32_e32 v55, v129, v54
	v_fmac_f32_e32 v56, v130, v54
	v_mul_f32_e32 v60, 0x3e38aa3b, v62
	v_mul_f32_e32 v61, 0x3e38aa3b, v63
	v_max3_f32 v57, v55, s75, v56
	v_fmac_f32_e32 v60, v131, v54
	v_fmac_f32_e32 v61, v132, v54
	v_mul_f32_e32 v62, 0x3e38aa3b, v64
	v_mul_f32_e32 v63, 0x3e38aa3b, v65
	v_max3_f32 v57, v57, v60, v61
	v_fmac_f32_e32 v62, v133, v54
	v_fmac_f32_e32 v63, v134, v54
	v_mul_f32_e32 v64, 0x3e38aa3b, v66
	v_mul_f32_e32 v65, 0x3e38aa3b, v67
	v_max3_f32 v57, v57, v62, v63
	v_fmac_f32_e32 v64, v135, v54
	v_fmac_f32_e32 v65, v136, v54
	v_mul_f32_e32 v66, 0x3e38aa3b, v68
	v_mul_f32_e32 v67, 0x3e38aa3b, v69
	v_max3_f32 v57, v57, v64, v65
	v_fmac_f32_e32 v66, v137, v54
	v_fmac_f32_e32 v67, v138, v54
	v_mul_f32_e32 v68, 0x3e38aa3b, v70
	v_mul_f32_e32 v70, 0x3e38aa3b, v71
	v_max3_f32 v57, v57, v66, v67
	v_fmac_f32_e32 v68, v139, v54
	v_fmac_f32_e32 v70, v140, v54
	v_mul_f32_e32 v71, 0x3e38aa3b, v72
	v_mul_f32_e32 v72, 0x3e38aa3b, v73
	v_max3_f32 v57, v57, v68, v70
	v_fmac_f32_e32 v71, v141, v54
	v_fmac_f32_e32 v72, v142, v54
	v_mul_f32_e32 v73, 0x3e38aa3b, v74
	v_mul_f32_e32 v74, 0x3e38aa3b, v75
	v_max3_f32 v57, v57, v71, v72
	v_fmac_f32_e32 v73, v143, v54
	v_fmac_f32_e32 v74, v144, v54
	v_mul_f32_e32 v75, 0x3e38aa3b, v76
	v_mul_f32_e32 v76, 0x3e38aa3b, v77
	v_max3_f32 v57, v57, v73, v74
	v_fmac_f32_e32 v75, v145, v54
	v_fmac_f32_e32 v76, v146, v54
	v_mul_f32_e32 v77, 0x3e38aa3b, v78
	v_mul_f32_e32 v78, 0x3e38aa3b, v79
	v_max3_f32 v57, v57, v75, v76
	v_fmac_f32_e32 v77, v147, v54
	v_fmac_f32_e32 v78, v148, v54
	v_mul_f32_e32 v79, 0x3e38aa3b, v80
	v_mul_f32_e32 v80, 0x3e38aa3b, v81
	v_max3_f32 v57, v57, v77, v78
	v_fmac_f32_e32 v79, v149, v54
	v_fmac_f32_e32 v80, v150, v54
	v_mul_f32_e32 v81, 0x3e38aa3b, v82
	v_mul_f32_e32 v82, 0x3e38aa3b, v83
	v_max3_f32 v57, v57, v79, v80
	v_fmac_f32_e32 v81, v151, v54
	v_fmac_f32_e32 v82, v152, v54
	v_mul_f32_e32 v83, 0x3e38aa3b, v84
	v_mul_f32_e32 v84, 0x3e38aa3b, v85
	v_max3_f32 v57, v57, v81, v82
	v_fmac_f32_e32 v83, v153, v54
	v_fmac_f32_e32 v84, v154, v54
	v_mul_f32_e32 v85, 0x3e38aa3b, v86
	v_mul_f32_e32 v86, 0x3e38aa3b, v87
	v_max3_f32 v57, v57, v83, v84
	v_fmac_f32_e32 v85, v155, v54
	v_fmac_f32_e32 v86, v156, v54
	v_mul_f32_e32 v87, 0x3e38aa3b, v170
	v_mul_f32_e32 v88, 0x3e38aa3b, v171
	v_max3_f32 v57, v57, v85, v86
	v_fmac_f32_e32 v87, v157, v54
	v_fmac_f32_e32 v88, v158, v54
	v_max3_f32 v57, v57, v87, v88
	v_fmac_f32_e32 v89, v159, v54
	v_fmac_f32_e32 v99, v160, v54
	v_max3_f32 v57, v57, v89, v99
	v_fmac_f32_e32 v101, v161, v54
	v_fmac_f32_e32 v102, v162, v54
	v_max3_f32 v57, v57, v101, v102
	v_fmac_f32_e32 v103, v163, v54
	v_fmac_f32_e32 v169, v164, v54
	v_mul_f32_e32 v50, 0x3e38aa3b, v50
	v_mul_f32_e32 v170, 0x3e38aa3b, v51
	v_max3_f32 v57, v57, v103, v169
	v_fmac_f32_e32 v50, v165, v54
	v_fmac_f32_e32 v170, v166, v54
	v_max3_f32 v51, v57, v50, v170
	v_mul_f32_e32 v57, 0x3e38aa3b, v52
	v_mul_f32_e32 v171, 0x3e38aa3b, v53
	v_fmac_f32_e32 v57, v167, v54
	v_fmac_f32_e32 v171, v168, v54
	v_max3_f32 v51, v51, v57, v171
	v_mov_b32_e32 v53, v51
	s_nop 1
	v_permlane16_swap_b32_e32 v53, v51
	v_mul_f32_e32 v52, s4, v249
	s_waitcnt lgkmcnt(0)
	v_max_f32_e32 v53, v53, v53
	v_max_f32_e32 v51, v51, v53
	v_mov_b32_e32 v53, v51
	s_nop 1
	v_permlane32_swap_b32_e32 v53, v51
	s_waitcnt lgkmcnt(0)
	v_max3_f32 v172, v51, v53, v52
	v_sub_f32_e32 v51, v55, v172
	v_exp_f32_e32 v173, v51
	v_sub_f32_e32 v52, v56, v172
	v_exp_f32_e32 v174, v52
	v_sub_f32_e32 v52, v60, v172
	v_exp_f32_e32 v175, v52
	v_sub_f32_e32 v52, v61, v172
	v_exp_f32_e32 v176, v52
	v_sub_f32_e32 v52, v62, v172
	v_add_f32_e32 v51, 0, v173
	v_exp_f32_e32 v177, v52
	v_sub_f32_e32 v52, v63, v172
	v_add_f32_e32 v51, v174, v51
	v_exp_f32_e32 v178, v52
	v_sub_f32_e32 v52, v64, v172
	v_add_f32_e32 v51, v175, v51
	v_exp_f32_e32 v179, v52
	v_sub_f32_e32 v52, v65, v172
	v_add_f32_e32 v51, v176, v51
	v_exp_f32_e32 v180, v52
	v_sub_f32_e32 v52, v66, v172
	v_add_f32_e32 v51, v177, v51
	v_exp_f32_e32 v69, v52
	v_sub_f32_e32 v52, v67, v172
	v_add_f32_e32 v51, v178, v51
	v_exp_f32_e32 v181, v52
	v_sub_f32_e32 v52, v68, v172
	v_add_f32_e32 v51, v179, v51
	v_exp_f32_e32 v182, v52
	v_sub_f32_e32 v52, v70, v172
	v_add_f32_e32 v51, v180, v51
	v_exp_f32_e32 v183, v52
	v_sub_f32_e32 v52, v71, v172
	v_add_f32_e32 v51, v69, v51
	v_exp_f32_e32 v184, v52
	v_sub_f32_e32 v52, v72, v172
	v_add_f32_e32 v51, v181, v51
	v_exp_f32_e32 v185, v52
	v_sub_f32_e32 v52, v73, v172
	v_add_f32_e32 v51, v182, v51
	v_exp_f32_e32 v73, v52
	v_sub_f32_e32 v52, v74, v172
	v_add_f32_e32 v51, v183, v51
	v_exp_f32_e32 v186, v52
	v_sub_f32_e32 v52, v75, v172
	v_add_f32_e32 v51, v184, v51
	v_exp_f32_e32 v64, v52
	v_sub_f32_e32 v52, v76, v172
	v_add_f32_e32 v51, v185, v51
	v_exp_f32_e32 v67, v52
	v_sub_f32_e32 v52, v77, v172
	v_add_f32_e32 v51, v73, v51
	v_exp_f32_e32 v68, v52
	v_sub_f32_e32 v52, v78, v172
	v_add_f32_e32 v51, v186, v51
	v_exp_f32_e32 v72, v52
	v_sub_f32_e32 v52, v79, v172
	v_add_f32_e32 v51, v64, v51
	v_exp_f32_e32 v187, v52
	v_sub_f32_e32 v52, v80, v172
	v_add_f32_e32 v51, v67, v51
	v_exp_f32_e32 v188, v52
	v_sub_f32_e32 v52, v81, v172
	v_add_f32_e32 v51, v68, v51
	v_exp_f32_e32 v189, v52
	v_sub_f32_e32 v52, v82, v172
	v_add_f32_e32 v51, v72, v51
	v_exp_f32_e32 v190, v52
	v_sub_f32_e32 v52, v83, v172
	v_add_f32_e32 v51, v187, v51
	v_exp_f32_e32 v61, v52
	v_sub_f32_e32 v52, v84, v172
	v_add_f32_e32 v51, v188, v51
	v_exp_f32_e32 v62, v52
	v_sub_f32_e32 v52, v85, v172
	v_add_f32_e32 v51, v189, v51
	v_exp_f32_e32 v63, v52
	v_sub_f32_e32 v52, v86, v172
	v_add_f32_e32 v51, v190, v51
	v_exp_f32_e32 v65, v52
	v_sub_f32_e32 v52, v87, v172
	v_add_f32_e32 v51, v61, v51
	v_exp_f32_e32 v66, v52
	v_sub_f32_e32 v52, v88, v172
	v_add_f32_e32 v51, v62, v51
	v_exp_f32_e32 v70, v52
	v_sub_f32_e32 v52, v89, v172
	v_add_f32_e32 v51, v63, v51
	v_exp_f32_e32 v71, v52
	v_sub_f32_e32 v52, v99, v172
	v_add_f32_e32 v51, v65, v51
	v_exp_f32_e32 v99, v52
	v_add_f32_e32 v51, v66, v51
	v_add_f32_e32 v51, v70, v51
	v_add_f32_e32 v51, v71, v51
	v_add_f32_e32 v52, v99, v51
	v_sub_f32_e32 v51, v101, v172
	v_exp_f32_e32 v51, v51
	v_sub_f32_e32 v50, v50, v172
	v_sub_f32_e32 v57, v57, v172
	v_exp_f32_e32 v57, v57
	v_add_f32_e32 v53, v51, v52
	v_sub_f32_e32 v52, v102, v172
	v_exp_f32_e32 v52, v52
	v_sub_f32_e32 v60, v171, v172
	v_exp_f32_e32 v60, v60
	v_add_f32_e32 v54, v52, v53
	v_sub_f32_e32 v53, v103, v172
	v_exp_f32_e32 v53, v53
	s_nop 0
	v_add_f32_e32 v55, v53, v54
	v_sub_f32_e32 v54, v169, v172
	v_exp_f32_e32 v54, v54
	s_nop 0
	v_add_f32_e32 v56, v54, v55
	v_exp_f32_e32 v55, v50
	s_nop 0
	v_add_f32_e32 v50, v55, v56
	v_sub_f32_e32 v56, v170, v172
	v_exp_f32_e32 v56, v56
	s_nop 0
	v_add_f32_e32 v50, v56, v50
	v_add_f32_e32 v50, v57, v50
	v_add_f32_e32 v50, v60, v50
	v_mov_b32_e32 v74, v50
	s_nop 1
	v_permlane16_swap_b32_e32 v74, v50
	s_waitcnt lgkmcnt(0)
	v_add_f32_e32 v50, v50, v74
	v_mov_b32_e32 v74, v50
	s_nop 1
	v_permlane32_swap_b32_e32 v74, v50
	s_waitcnt lgkmcnt(0)
	v_add_f32_e32 v50, v50, v74
	v_fma_f32 v74, s4, v249, -v172
	v_exp_f32_e32 v74, v74
	s_nop 0
	v_add_f32_e32 v50, v74, v50
	v_cvt_pk_bf16_f32 v74, v173, v174
	v_cvt_pk_bf16_f32 v75, v175, v176
	v_cvt_pk_bf16_f32 v76, v177, v178
	v_cvt_pk_bf16_f32 v77, v179, v180
	ds_read_b64_tr_b16 v[80:81], v98 offset:39168
	ds_read_b64_tr_b16 v[78:79], v98 offset:36864
	ds_read_b64_tr_b16 v[82:83], v98 offset:36896
	ds_read_b64_tr_b16 v[84:85], v98 offset:39200
	ds_read_b64_tr_b16 v[86:87], v98 offset:36928
	ds_read_b64_tr_b16 v[88:89], v98 offset:39232
	ds_read_b64_tr_b16 v[170:171], v98 offset:36960
	ds_read_b64_tr_b16 v[172:173], v98 offset:39264
	s_waitcnt lgkmcnt(6)
	v_mfma_f32_16x16x32_bf16 v[78:81], v[78:81], v[74:77], 0
	s_waitcnt lgkmcnt(4)
	v_mfma_f32_16x16x32_bf16 v[82:85], v[82:85], v[74:77], 0
	s_waitcnt lgkmcnt(2)
	v_mfma_f32_16x16x32_bf16 v[86:89], v[86:89], v[74:77], 0
	s_waitcnt lgkmcnt(0)
	v_mfma_f32_16x16x32_bf16 v[74:77], v[170:173], v[74:77], 0
	v_cvt_pk_bf16_f32 v170, v69, v181
	v_cvt_pk_bf16_f32 v171, v182, v183
	v_cvt_pk_bf16_f32 v172, v184, v185
	v_cvt_pk_bf16_f32 v173, v73, v186
	ds_read_b64_tr_b16 v[176:177], v98 offset:43776
	ds_read_b64_tr_b16 v[174:175], v98 offset:41472
	ds_read_b64_tr_b16 v[178:179], v98 offset:41504
	s_waitcnt lgkmcnt(1)
	v_mfma_f32_16x16x32_bf16 v[78:81], v[174:177], v[170:173], v[78:81]
	ds_read_b64_tr_b16 v[180:181], v98 offset:43808
	ds_read_b64_tr_b16 v[174:175], v98 offset:41536
	ds_read_b64_tr_b16 v[176:177], v98 offset:43840
	s_waitcnt lgkmcnt(0)
	v_mfma_f32_16x16x32_bf16 v[86:89], v[174:177], v[170:173], v[86:89]
	ds_read_b64_tr_b16 v[174:175], v98 offset:41568
	ds_read_b64_tr_b16 v[176:177], v98 offset:43872
	v_mfma_f32_16x16x32_bf16 v[82:85], v[178:181], v[170:173], v[82:85]
	s_waitcnt lgkmcnt(0)
	v_mfma_f32_16x16x32_bf16 v[74:77], v[174:177], v[170:173], v[74:77]
	v_cvt_pk_bf16_f32 v170, v64, v67
	v_cvt_pk_bf16_f32 v171, v68, v72
	v_cvt_pk_bf16_f32 v172, v187, v188
	v_cvt_pk_bf16_f32 v173, v189, v190
	ds_read_b64_tr_b16 v[176:177], v98 offset:48384
	ds_read_b64_tr_b16 v[174:175], v98 offset:46080
	ds_read_b64_tr_b16 v[178:179], v98 offset:46112
	s_waitcnt lgkmcnt(1)
	v_mfma_f32_16x16x32_bf16 v[78:81], v[174:177], v[170:173], v[78:81]
	ds_read_b64_tr_b16 v[180:181], v98 offset:48416
	ds_read_b64_tr_b16 v[174:175], v98 offset:46144
	ds_read_b64_tr_b16 v[176:177], v98 offset:48448
	s_waitcnt lgkmcnt(0)
	v_mfma_f32_16x16x32_bf16 v[86:89], v[174:177], v[170:173], v[86:89]
	ds_read_b64_tr_b16 v[174:175], v98 offset:46176
	ds_read_b64_tr_b16 v[176:177], v98 offset:48480
	v_cvt_pk_bf16_f32 v62, v61, v62
	v_cvt_pk_bf16_f32 v63, v63, v65
	s_waitcnt lgkmcnt(0)
	v_mfma_f32_16x16x32_bf16 v[72:75], v[174:177], v[170:173], v[74:77]
	v_cvt_pk_bf16_f32 v64, v66, v70
	v_cvt_pk_bf16_f32 v65, v71, v99
	ds_read_b64_tr_b16 v[68:69], v98 offset:52992
	ds_read_b64_tr_b16 v[66:67], v98 offset:50688
	s_nop 0
	ds_read_b64_tr_b16 v[76:77], v98 offset:50720
	s_waitcnt lgkmcnt(1)
	v_mfma_f32_16x16x32_bf16 v[66:69], v[66:69], v[62:65], v[78:81]
	s_nop 2
	ds_read_b64_tr_b16 v[78:79], v98 offset:53024
	v_mfma_f32_16x16x32_bf16 v[82:85], v[178:181], v[170:173], v[82:85]
	s_waitcnt lgkmcnt(0)
	v_mfma_f32_16x16x32_bf16 v[76:79], v[76:79], v[62:65], v[82:85]
	ds_read_b64_tr_b16 v[80:81], v98 offset:50752
	s_nop 4
	ds_read_b64_tr_b16 v[82:83], v98 offset:53056
	s_waitcnt lgkmcnt(0)
	v_mfma_f32_16x16x32_bf16 v[80:83], v[80:83], v[62:65], v[86:89]
	ds_read_b64_tr_b16 v[84:85], v98 offset:50784
	s_nop 1
	ds_read_b64_tr_b16 v[86:87], v98 offset:53088
	v_cvt_pk_bf16_f32 v52, v51, v52
	v_cvt_pk_bf16_f32 v53, v53, v54
	s_waitcnt lgkmcnt(0)
	v_mfma_f32_16x16x32_bf16 v[62:65], v[84:87], v[62:65], v[72:75]
	v_cvt_pk_bf16_f32 v54, v55, v56
	v_cvt_pk_bf16_f32 v55, v57, v60
	s_nop 2
	ds_read_b64_tr_b16 v[72:73], v98 offset:57600
	ds_read_b64_tr_b16 v[70:71], v98 offset:55296
	ds_read_b64_tr_b16 v[84:85], v98 offset:55328
	ds_read_b64_tr_b16 v[86:87], v98 offset:57632
	v_div_scale_f32 v51, s[4:5], v50, v50, 1.0
	s_waitcnt lgkmcnt(2)
	v_mfma_f32_16x16x32_bf16 v[66:69], v[70:73], v[52:55], v[66:69]
	v_rcp_f32_e32 v56, v51
	s_or_b32 s4, s17, 3
	v_fma_f32 v57, -v51, v56, 1.0
	s_waitcnt lgkmcnt(0)
	v_mfma_f32_16x16x32_bf16 v[70:73], v[84:87], v[52:55], v[76:79]
	ds_read_b64_tr_b16 v[74:75], v98 offset:55360
	s_nop 1
	ds_read_b64_tr_b16 v[76:77], v98 offset:57664
	v_fmac_f32_e32 v56, v57, v56
	v_div_scale_f32 v57, vcc, 1.0, v50, 1.0
	s_waitcnt lgkmcnt(0)
	v_mfma_f32_16x16x32_bf16 v[74:77], v[74:77], v[52:55], v[80:83]
	ds_read_b64_tr_b16 v[78:79], v98 offset:55392
	s_nop 1
	ds_read_b64_tr_b16 v[80:81], v98 offset:57696
	v_mul_f32_e32 v60, v57, v56
	v_fma_f32 v61, -v51, v60, v57
	v_fmac_f32_e32 v60, v61, v56
	v_fma_f32 v51, -v51, v60, v57
	s_waitcnt lgkmcnt(0)
	v_mfma_f32_16x16x32_bf16 v[52:55], v[78:81], v[52:55], v[62:65]
	v_div_fmas_f32 v51, v51, v56, v60
	v_div_fixup_f32 v50, v51, v50, 1.0
	v_pk_mul_f32 v[60:61], v[50:51], v[66:67] op_sel_hi:[0,1]
	v_pk_mul_f32 v[56:57], v[50:51], v[68:69] op_sel_hi:[0,1]
	v_pk_mul_f32 v[62:63], v[50:51], v[70:71] op_sel_hi:[0,1]
	v_cvt_pk_bf16_f32 v60, v60, v61
	v_cvt_pk_bf16_f32 v61, v56, v57
	v_pk_mul_f32 v[64:65], v[50:51], v[72:73] op_sel_hi:[0,1]
	v_cvt_pk_bf16_f32 v62, v62, v63
	v_cvt_pk_bf16_f32 v63, v64, v65
	global_store_dwordx4 v[58:59], v[60:63], off offset:128
	v_pk_mul_f32 v[56:57], v[50:51], v[76:77] op_sel_hi:[0,1]
	v_pk_mul_f32 v[54:55], v[50:51], v[54:55] op_sel_hi:[0,1]
	v_pk_mul_f32 v[60:61], v[50:51], v[74:75] op_sel_hi:[0,1]
	v_pk_mul_f32 v[52:53], v[50:51], v[52:53] op_sel_hi:[0,1]
	v_cvt_pk_bf16_f32 v50, v60, v61
	v_cvt_pk_bf16_f32 v51, v56, v57
	v_cvt_pk_bf16_f32 v52, v52, v53
	v_cvt_pk_bf16_f32 v53, v54, v55
	global_store_dwordx4 v[58:59], v[50:53], off offset:192
	s_nop 1
	v_cvt_f32_ubyte0_e32 v50, s4
	v_mul_f32_e32 v50, -0.5, v50
	v_exp_f32_e32 v88, v50
	ds_read_b128 v[50:53], v100
	ds_read_b128 v[54:57], v100 offset:64
	s_waitcnt vmcnt(15) lgkmcnt(1)
	v_mfma_f32_16x16x32_bf16 v[50:53], v[50:53], v[46:49], 0
	v_readlane_b32 s4, v128, 2
	s_waitcnt vmcnt(14) lgkmcnt(0)
	v_mfma_f32_16x16x32_bf16 v[50:53], v[54:57], v[42:45], v[50:53]
	ds_read_b128 v[54:57], v100 offset:2304
	ds_read_b128 v[60:63], v100 offset:2368
	s_waitcnt lgkmcnt(1)
	v_mfma_f32_16x16x32_bf16 v[54:57], v[54:57], v[46:49], 0
	s_waitcnt lgkmcnt(0)
	v_mfma_f32_16x16x32_bf16 v[54:57], v[60:63], v[42:45], v[54:57]
	ds_read_b128 v[60:63], v100 offset:4608
	ds_read_b128 v[64:67], v100 offset:4672
	s_waitcnt lgkmcnt(1)
	v_mfma_f32_16x16x32_bf16 v[60:63], v[60:63], v[46:49], 0
	s_waitcnt lgkmcnt(0)
	v_mfma_f32_16x16x32_bf16 v[60:63], v[64:67], v[42:45], v[60:63]
	ds_read_b128 v[64:67], v100 offset:6912
	ds_read_b128 v[68:71], v100 offset:6976
	s_waitcnt lgkmcnt(1)
	v_mfma_f32_16x16x32_bf16 v[64:67], v[64:67], v[46:49], 0
	s_waitcnt lgkmcnt(0)
	v_mfma_f32_16x16x32_bf16 v[64:67], v[68:71], v[42:45], v[64:67]
	ds_read_b128 v[68:71], v100 offset:9216
	ds_read_b128 v[72:75], v100 offset:9280
	s_waitcnt lgkmcnt(1)
	v_mfma_f32_16x16x32_bf16 v[68:71], v[68:71], v[46:49], 0
	s_waitcnt lgkmcnt(0)
	v_mfma_f32_16x16x32_bf16 v[68:71], v[72:75], v[42:45], v[68:71]
	ds_read_b128 v[72:75], v100 offset:11520
	ds_read_b128 v[76:79], v100 offset:11584
	s_waitcnt lgkmcnt(1)
	v_mfma_f32_16x16x32_bf16 v[72:75], v[72:75], v[46:49], 0
	s_waitcnt lgkmcnt(0)
	v_mfma_f32_16x16x32_bf16 v[72:75], v[76:79], v[42:45], v[72:75]
	ds_read_b128 v[76:79], v100 offset:13824
	ds_read_b128 v[80:83], v100 offset:13888
	s_waitcnt lgkmcnt(1)
	v_mfma_f32_16x16x32_bf16 v[76:79], v[76:79], v[46:49], 0
	s_waitcnt lgkmcnt(0)
	v_mfma_f32_16x16x32_bf16 v[76:79], v[80:83], v[42:45], v[76:79]
	ds_read_b128 v[80:83], v100 offset:16128
	ds_read_b128 v[84:87], v100 offset:16192
	s_waitcnt lgkmcnt(1)
	v_mfma_f32_16x16x32_bf16 v[80:83], v[80:83], v[46:49], 0
	s_waitcnt lgkmcnt(0)
	v_mfma_f32_16x16x32_bf16 v[80:83], v[84:87], v[42:45], v[80:83]
	ds_read_b128 v[84:87], v100 offset:18432
	ds_read_b128 v[170:173], v100 offset:18496
	s_waitcnt lgkmcnt(1)
	v_mfma_f32_16x16x32_bf16 v[84:87], v[84:87], v[46:49], 0
	s_waitcnt lgkmcnt(0)
	v_mfma_f32_16x16x32_bf16 v[84:87], v[170:173], v[42:45], v[84:87]
	ds_read_b128 v[170:173], v100 offset:20736
	ds_read_b128 v[174:177], v100 offset:20800
	s_waitcnt lgkmcnt(1)
	v_mfma_f32_16x16x32_bf16 v[46:49], v[170:173], v[46:49], 0
	s_waitcnt lgkmcnt(0)
	v_mfma_f32_16x16x32_bf16 v[42:45], v[174:177], v[42:45], v[46:49]
	s_nop 5
	v_mul_f32_e32 v46, 0xbfb8aa3b, v88
	v_mul_f32_e32 v47, 0x3e38aa3b, v50
	v_mul_f32_e32 v48, 0x3e38aa3b, v51
	v_fmac_f32_e32 v47, v129, v46
	v_fmac_f32_e32 v48, v130, v46
	v_mul_f32_e32 v50, 0x3e38aa3b, v52
	v_mul_f32_e32 v51, 0x3e38aa3b, v53
	v_max3_f32 v49, v47, s75, v48
	v_fmac_f32_e32 v50, v131, v46
	v_fmac_f32_e32 v51, v132, v46
	v_mul_f32_e32 v52, 0x3e38aa3b, v54
	v_mul_f32_e32 v53, 0x3e38aa3b, v55
	v_max3_f32 v49, v49, v50, v51
	v_fmac_f32_e32 v52, v133, v46
	v_fmac_f32_e32 v53, v134, v46
	v_mul_f32_e32 v54, 0x3e38aa3b, v56
	v_mul_f32_e32 v55, 0x3e38aa3b, v57
	v_max3_f32 v49, v49, v52, v53
	v_fmac_f32_e32 v54, v135, v46
	v_fmac_f32_e32 v55, v136, v46
	v_mul_f32_e32 v56, 0x3e38aa3b, v60
	v_mul_f32_e32 v57, 0x3e38aa3b, v61
	v_max3_f32 v49, v49, v54, v55
	v_fmac_f32_e32 v56, v137, v46
	v_fmac_f32_e32 v57, v138, v46
	v_mul_f32_e32 v60, 0x3e38aa3b, v62
	v_mul_f32_e32 v62, 0x3e38aa3b, v63
	v_max3_f32 v49, v49, v56, v57
	v_fmac_f32_e32 v60, v139, v46
	v_fmac_f32_e32 v62, v140, v46
	v_mul_f32_e32 v63, 0x3e38aa3b, v64
	v_mul_f32_e32 v64, 0x3e38aa3b, v65
	v_max3_f32 v49, v49, v60, v62
	v_fmac_f32_e32 v63, v141, v46
	v_fmac_f32_e32 v64, v142, v46
	v_mul_f32_e32 v65, 0x3e38aa3b, v66
	v_mul_f32_e32 v66, 0x3e38aa3b, v67
	v_max3_f32 v49, v49, v63, v64
	v_fmac_f32_e32 v65, v143, v46
	v_fmac_f32_e32 v66, v144, v46
	v_mul_f32_e32 v67, 0x3e38aa3b, v68
	v_mul_f32_e32 v68, 0x3e38aa3b, v69
	v_max3_f32 v49, v49, v65, v66
	v_fmac_f32_e32 v67, v145, v46
	v_fmac_f32_e32 v68, v146, v46
	v_mul_f32_e32 v69, 0x3e38aa3b, v70
	v_mul_f32_e32 v70, 0x3e38aa3b, v71
	v_max3_f32 v49, v49, v67, v68
	v_fmac_f32_e32 v69, v147, v46
	v_fmac_f32_e32 v70, v148, v46
	v_mul_f32_e32 v71, 0x3e38aa3b, v72
	v_mul_f32_e32 v72, 0x3e38aa3b, v73
	v_max3_f32 v49, v49, v69, v70
	v_fmac_f32_e32 v71, v149, v46
	v_fmac_f32_e32 v72, v150, v46
	v_mul_f32_e32 v73, 0x3e38aa3b, v74
	v_mul_f32_e32 v74, 0x3e38aa3b, v75
	v_max3_f32 v49, v49, v71, v72
	v_fmac_f32_e32 v73, v151, v46
	v_fmac_f32_e32 v74, v152, v46
	v_mul_f32_e32 v75, 0x3e38aa3b, v76
	v_mul_f32_e32 v76, 0x3e38aa3b, v77
	v_max3_f32 v49, v49, v73, v74
	v_fmac_f32_e32 v75, v153, v46
	v_fmac_f32_e32 v76, v154, v46
	v_mul_f32_e32 v77, 0x3e38aa3b, v78
	v_mul_f32_e32 v78, 0x3e38aa3b, v79
	v_max3_f32 v49, v49, v75, v76
	v_fmac_f32_e32 v77, v155, v46
	v_fmac_f32_e32 v78, v156, v46
	v_mul_f32_e32 v79, 0x3e38aa3b, v80
	v_mul_f32_e32 v80, 0x3e38aa3b, v81
	v_max3_f32 v49, v49, v77, v78
	v_fmac_f32_e32 v79, v157, v46
	v_fmac_f32_e32 v80, v158, v46
	v_mul_f32_e32 v81, 0x3e38aa3b, v82
	v_mul_f32_e32 v82, 0x3e38aa3b, v83
	v_max3_f32 v49, v49, v79, v80
	v_fmac_f32_e32 v81, v159, v46
	v_fmac_f32_e32 v82, v160, v46
	v_mul_f32_e32 v83, 0x3e38aa3b, v84
	v_mul_f32_e32 v84, 0x3e38aa3b, v85
	v_max3_f32 v49, v49, v81, v82
	v_fmac_f32_e32 v83, v161, v46
	v_fmac_f32_e32 v84, v162, v46
	v_mul_f32_e32 v85, 0x3e38aa3b, v86
	v_mul_f32_e32 v86, 0x3e38aa3b, v87
	v_max3_f32 v49, v49, v83, v84
	v_fmac_f32_e32 v85, v163, v46
	v_fmac_f32_e32 v86, v164, v46
	v_mul_f32_e32 v42, 0x3e38aa3b, v42
	v_mul_f32_e32 v87, 0x3e38aa3b, v43
	v_max3_f32 v49, v49, v85, v86
	v_fmac_f32_e32 v42, v165, v46
	v_fmac_f32_e32 v87, v166, v46
	v_max3_f32 v43, v49, v42, v87
	v_mul_f32_e32 v49, 0x3e38aa3b, v44
	v_mul_f32_e32 v88, 0x3e38aa3b, v45
	v_fmac_f32_e32 v49, v167, v46
	v_fmac_f32_e32 v88, v168, v46
	v_max3_f32 v43, v43, v49, v88
	v_mov_b32_e32 v45, v43
	s_nop 1
	v_permlane16_swap_b32_e32 v45, v43
	v_mul_f32_e32 v44, s4, v249
	s_waitcnt lgkmcnt(0)
	v_max_f32_e32 v45, v45, v45
	v_max_f32_e32 v43, v43, v45
	v_mov_b32_e32 v45, v43
	s_nop 1
	v_permlane32_swap_b32_e32 v45, v43
	s_waitcnt lgkmcnt(0)
	v_max3_f32 v89, v43, v45, v44
	v_sub_f32_e32 v43, v47, v89
	v_exp_f32_e32 v99, v43
	v_sub_f32_e32 v44, v48, v89
	v_exp_f32_e32 v101, v44
	v_sub_f32_e32 v44, v50, v89
	v_exp_f32_e32 v102, v44
	v_sub_f32_e32 v44, v51, v89
	v_exp_f32_e32 v103, v44
	v_sub_f32_e32 v44, v52, v89
	v_add_f32_e32 v43, 0, v99
	v_exp_f32_e32 v169, v44
	v_sub_f32_e32 v44, v53, v89
	v_add_f32_e32 v43, v101, v43
	v_exp_f32_e32 v170, v44
	v_sub_f32_e32 v44, v54, v89
	v_add_f32_e32 v43, v102, v43
	v_exp_f32_e32 v171, v44
	v_sub_f32_e32 v44, v55, v89
	v_add_f32_e32 v43, v103, v43
	v_exp_f32_e32 v172, v44
	v_sub_f32_e32 v44, v56, v89
	v_add_f32_e32 v43, v169, v43
	v_exp_f32_e32 v61, v44
	v_sub_f32_e32 v44, v57, v89
	v_add_f32_e32 v43, v170, v43
	v_exp_f32_e32 v173, v44
	v_sub_f32_e32 v44, v60, v89
	v_add_f32_e32 v43, v171, v43
	v_exp_f32_e32 v174, v44
	v_sub_f32_e32 v44, v62, v89
	v_add_f32_e32 v43, v172, v43
	v_exp_f32_e32 v175, v44
	v_sub_f32_e32 v44, v63, v89
	v_add_f32_e32 v43, v61, v43
	v_exp_f32_e32 v176, v44
	v_sub_f32_e32 v44, v64, v89
	v_add_f32_e32 v43, v173, v43
	v_exp_f32_e32 v177, v44
	v_sub_f32_e32 v44, v65, v89
	v_add_f32_e32 v43, v174, v43
	v_exp_f32_e32 v65, v44
	v_sub_f32_e32 v44, v66, v89
	v_add_f32_e32 v43, v175, v43
	v_exp_f32_e32 v178, v44
	v_sub_f32_e32 v44, v67, v89
	v_add_f32_e32 v43, v176, v43
	v_exp_f32_e32 v54, v44
	v_sub_f32_e32 v44, v68, v89
	v_add_f32_e32 v43, v177, v43
	v_exp_f32_e32 v57, v44
	v_sub_f32_e32 v44, v69, v89
	v_add_f32_e32 v43, v65, v43
	v_exp_f32_e32 v60, v44
	v_sub_f32_e32 v44, v70, v89
	v_add_f32_e32 v43, v178, v43
	v_exp_f32_e32 v64, v44
	v_sub_f32_e32 v44, v71, v89
	v_add_f32_e32 v43, v54, v43
	v_exp_f32_e32 v179, v44
	v_sub_f32_e32 v44, v72, v89
	v_add_f32_e32 v43, v57, v43
	v_exp_f32_e32 v180, v44
	v_sub_f32_e32 v44, v73, v89
	v_add_f32_e32 v43, v60, v43
	v_exp_f32_e32 v181, v44
	v_sub_f32_e32 v44, v74, v89
	v_add_f32_e32 v43, v64, v43
	v_exp_f32_e32 v182, v44
	v_sub_f32_e32 v44, v75, v89
	v_add_f32_e32 v43, v179, v43
	v_exp_f32_e32 v51, v44
	v_sub_f32_e32 v44, v76, v89
	v_add_f32_e32 v43, v180, v43
	v_exp_f32_e32 v52, v44
	v_sub_f32_e32 v44, v77, v89
	v_add_f32_e32 v43, v181, v43
	v_exp_f32_e32 v53, v44
	v_sub_f32_e32 v44, v78, v89
	v_add_f32_e32 v43, v182, v43
	v_exp_f32_e32 v55, v44
	v_sub_f32_e32 v44, v79, v89
	v_add_f32_e32 v43, v51, v43
	v_exp_f32_e32 v56, v44
	v_sub_f32_e32 v44, v80, v89
	v_add_f32_e32 v43, v52, v43
	v_exp_f32_e32 v62, v44
	v_sub_f32_e32 v44, v81, v89
	v_add_f32_e32 v43, v53, v43
	v_exp_f32_e32 v63, v44
	v_sub_f32_e32 v44, v82, v89
	v_add_f32_e32 v43, v55, v43
	v_exp_f32_e32 v183, v44
	v_add_f32_e32 v43, v56, v43
	v_add_f32_e32 v43, v62, v43
	v_add_f32_e32 v43, v63, v43
	v_add_f32_e32 v44, v183, v43
	v_sub_f32_e32 v43, v83, v89
	v_exp_f32_e32 v43, v43
	v_sub_f32_e32 v42, v42, v89
	v_sub_f32_e32 v49, v49, v89
	v_exp_f32_e32 v49, v49
	v_add_f32_e32 v45, v43, v44
	v_sub_f32_e32 v44, v84, v89
	v_exp_f32_e32 v44, v44
	v_sub_f32_e32 v50, v88, v89
	v_exp_f32_e32 v50, v50
	v_add_f32_e32 v46, v44, v45
	v_sub_f32_e32 v45, v85, v89
	v_exp_f32_e32 v45, v45
	s_nop 0
	v_add_f32_e32 v47, v45, v46
	v_sub_f32_e32 v46, v86, v89
	v_exp_f32_e32 v46, v46
	s_nop 0
	v_add_f32_e32 v48, v46, v47
	v_exp_f32_e32 v47, v42
	s_nop 0
	v_add_f32_e32 v42, v47, v48
	v_sub_f32_e32 v48, v87, v89
	v_exp_f32_e32 v48, v48
	s_nop 0
	v_add_f32_e32 v42, v48, v42
	v_add_f32_e32 v42, v49, v42
	v_add_f32_e32 v42, v50, v42
	v_mov_b32_e32 v66, v42
	s_nop 1
	v_permlane16_swap_b32_e32 v66, v42
	s_waitcnt lgkmcnt(0)
	v_add_f32_e32 v42, v42, v66
	v_mov_b32_e32 v66, v42
	s_nop 1
	v_permlane32_swap_b32_e32 v66, v42
	s_waitcnt lgkmcnt(0)
	v_add_f32_e32 v42, v42, v66
	v_fma_f32 v66, s4, v249, -v89
	v_exp_f32_e32 v66, v66
	s_nop 0
	v_add_f32_e32 v42, v66, v42
	v_cvt_pk_bf16_f32 v66, v99, v101
	v_cvt_pk_bf16_f32 v67, v102, v103
	v_cvt_pk_bf16_f32 v68, v169, v170
	v_cvt_pk_bf16_f32 v69, v171, v172
	ds_read_b64_tr_b16 v[72:73], v98 offset:39168
	ds_read_b64_tr_b16 v[70:71], v98 offset:36864
	ds_read_b64_tr_b16 v[74:75], v98 offset:36896
	ds_read_b64_tr_b16 v[76:77], v98 offset:39200
	ds_read_b64_tr_b16 v[78:79], v98 offset:36928
	ds_read_b64_tr_b16 v[80:81], v98 offset:39232
	ds_read_b64_tr_b16 v[82:83], v98 offset:36960
	ds_read_b64_tr_b16 v[84:85], v98 offset:39264
	s_waitcnt lgkmcnt(6)
	v_mfma_f32_16x16x32_bf16 v[70:73], v[70:73], v[66:69], 0
	s_waitcnt lgkmcnt(4)
	v_mfma_f32_16x16x32_bf16 v[74:77], v[74:77], v[66:69], 0
	s_waitcnt lgkmcnt(2)
	v_mfma_f32_16x16x32_bf16 v[78:81], v[78:81], v[66:69], 0
	s_waitcnt lgkmcnt(0)
	v_mfma_f32_16x16x32_bf16 v[66:69], v[82:85], v[66:69], 0
	v_cvt_pk_bf16_f32 v82, v61, v173
	v_cvt_pk_bf16_f32 v83, v174, v175
	v_cvt_pk_bf16_f32 v84, v176, v177
	v_cvt_pk_bf16_f32 v85, v65, v178
	ds_read_b64_tr_b16 v[88:89], v98 offset:43776
	ds_read_b64_tr_b16 v[86:87], v98 offset:41472
	ds_read_b64_tr_b16 v[170:171], v98 offset:41504
	s_waitcnt lgkmcnt(1)
	v_mfma_f32_16x16x32_bf16 v[70:73], v[86:89], v[82:85], v[70:73]
	ds_read_b64_tr_b16 v[172:173], v98 offset:43808
	ds_read_b64_tr_b16 v[86:87], v98 offset:41536
	ds_read_b64_tr_b16 v[88:89], v98 offset:43840
	s_waitcnt lgkmcnt(0)
	v_mfma_f32_16x16x32_bf16 v[78:81], v[86:89], v[82:85], v[78:81]
	ds_read_b64_tr_b16 v[86:87], v98 offset:41568
	ds_read_b64_tr_b16 v[88:89], v98 offset:43872
	v_mfma_f32_16x16x32_bf16 v[74:77], v[170:173], v[82:85], v[74:77]
	s_waitcnt lgkmcnt(0)
	v_mfma_f32_16x16x32_bf16 v[66:69], v[86:89], v[82:85], v[66:69]
	v_cvt_pk_bf16_f32 v82, v54, v57
	v_cvt_pk_bf16_f32 v83, v60, v64
	v_cvt_pk_bf16_f32 v84, v179, v180
	v_cvt_pk_bf16_f32 v85, v181, v182
	ds_read_b64_tr_b16 v[88:89], v98 offset:48384
	ds_read_b64_tr_b16 v[86:87], v98 offset:46080
	ds_read_b64_tr_b16 v[170:171], v98 offset:46112
	s_waitcnt lgkmcnt(1)
	v_mfma_f32_16x16x32_bf16 v[70:73], v[86:89], v[82:85], v[70:73]
	ds_read_b64_tr_b16 v[172:173], v98 offset:48416
	ds_read_b64_tr_b16 v[86:87], v98 offset:46144
	ds_read_b64_tr_b16 v[88:89], v98 offset:48448
	s_waitcnt lgkmcnt(0)
	v_mfma_f32_16x16x32_bf16 v[78:81], v[86:89], v[82:85], v[78:81]
	ds_read_b64_tr_b16 v[86:87], v98 offset:46176
	ds_read_b64_tr_b16 v[88:89], v98 offset:48480
	v_cvt_pk_bf16_f32 v52, v51, v52
	v_cvt_pk_bf16_f32 v53, v53, v55
	s_waitcnt lgkmcnt(0)
	v_mfma_f32_16x16x32_bf16 v[64:67], v[86:89], v[82:85], v[66:69]
	v_cvt_pk_bf16_f32 v54, v56, v62
	v_cvt_pk_bf16_f32 v55, v63, v183
	ds_read_b64_tr_b16 v[62:63], v98 offset:52992
	ds_read_b64_tr_b16 v[60:61], v98 offset:50688
	s_nop 0
	ds_read_b64_tr_b16 v[68:69], v98 offset:50720
	s_waitcnt lgkmcnt(1)
	v_mfma_f32_16x16x32_bf16 v[60:63], v[60:63], v[52:55], v[70:73]
	s_nop 2
	ds_read_b64_tr_b16 v[70:71], v98 offset:53024
	v_mfma_f32_16x16x32_bf16 v[74:77], v[170:173], v[82:85], v[74:77]
	s_waitcnt lgkmcnt(0)
	v_mfma_f32_16x16x32_bf16 v[68:71], v[68:71], v[52:55], v[74:77]
	ds_read_b64_tr_b16 v[72:73], v98 offset:50752
	s_nop 4
	ds_read_b64_tr_b16 v[74:75], v98 offset:53056
	s_waitcnt lgkmcnt(0)
	v_mfma_f32_16x16x32_bf16 v[72:75], v[72:75], v[52:55], v[78:81]
	ds_read_b64_tr_b16 v[76:77], v98 offset:50784
	s_nop 1
	ds_read_b64_tr_b16 v[78:79], v98 offset:53088
	v_cvt_pk_bf16_f32 v44, v43, v44
	v_cvt_pk_bf16_f32 v45, v45, v46
	s_waitcnt lgkmcnt(0)
	v_mfma_f32_16x16x32_bf16 v[52:55], v[76:79], v[52:55], v[64:67]
	v_cvt_pk_bf16_f32 v46, v47, v48
	v_cvt_pk_bf16_f32 v47, v49, v50
	ds_read_b64_tr_b16 v[50:51], v98 offset:57600
	ds_read_b64_tr_b16 v[48:49], v98 offset:55296
	s_nop 0
	ds_read_b64_tr_b16 v[64:65], v98 offset:55328
	ds_read_b64_tr_b16 v[66:67], v98 offset:57632
	s_waitcnt lgkmcnt(2)
	v_mfma_f32_16x16x32_bf16 v[48:51], v[48:51], v[44:47], v[60:63]
	v_div_scale_f32 v43, s[4:5], v42, v42, 1.0
	s_or_b32 s4, s17, 4
	s_waitcnt lgkmcnt(0)
	v_mfma_f32_16x16x32_bf16 v[60:63], v[64:67], v[44:47], v[68:71]
	ds_read_b64_tr_b16 v[64:65], v98 offset:55360
	ds_read_b64_tr_b16 v[66:67], v98 offset:57664
	s_nop 0
	ds_read_b64_tr_b16 v[68:69], v98 offset:55392
	ds_read_b64_tr_b16 v[70:71], v98 offset:57696
	s_waitcnt lgkmcnt(2)
	v_mfma_f32_16x16x32_bf16 v[64:67], v[64:67], v[44:47], v[72:75]
	s_waitcnt lgkmcnt(0)
	v_mfma_f32_16x16x32_bf16 v[44:47], v[68:71], v[44:47], v[52:55]
	s_nop 2
	v_rcp_f32_e32 v52, v43
	s_nop 0
	v_fma_f32 v53, -v43, v52, 1.0
	v_fmac_f32_e32 v52, v53, v52
	v_div_scale_f32 v53, vcc, 1.0, v42, 1.0
	v_mul_f32_e32 v54, v53, v52
	v_fma_f32 v55, -v43, v54, v53
	v_fmac_f32_e32 v54, v55, v52
	v_fma_f32 v43, -v43, v54, v53
	v_div_fmas_f32 v43, v43, v52, v54
	v_div_fixup_f32 v42, v43, v42, 1.0
	v_pk_mul_f32 v[50:51], v[42:43], v[50:51] op_sel_hi:[0,1]
	v_pk_mul_f32 v[48:49], v[42:43], v[48:49] op_sel_hi:[0,1]
	v_pk_mul_f32 v[52:53], v[42:43], v[62:63] op_sel_hi:[0,1]
	v_pk_mul_f32 v[54:55], v[42:43], v[60:61] op_sel_hi:[0,1]
	v_cvt_pk_bf16_f32 v48, v48, v49
	v_cvt_pk_bf16_f32 v49, v50, v51
	v_cvt_pk_bf16_f32 v50, v54, v55
	v_cvt_pk_bf16_f32 v51, v52, v53
	global_store_dwordx4 v[58:59], v[48:51], off offset:256
	v_pk_mul_f32 v[46:47], v[42:43], v[46:47] op_sel_hi:[0,1]
	v_pk_mul_f32 v[44:45], v[42:43], v[44:45] op_sel_hi:[0,1]
	v_pk_mul_f32 v[48:49], v[42:43], v[66:67] op_sel_hi:[0,1]
	v_pk_mul_f32 v[50:51], v[42:43], v[64:65] op_sel_hi:[0,1]
	v_cvt_pk_bf16_f32 v42, v50, v51
	v_cvt_pk_bf16_f32 v43, v48, v49
	v_cvt_pk_bf16_f32 v44, v44, v45
	v_cvt_pk_bf16_f32 v45, v46, v47
	global_store_dwordx4 v[58:59], v[42:45], off offset:320
	s_nop 1
	v_cvt_f32_ubyte0_e32 v42, s4
	v_mul_f32_e32 v42, -0.5, v42
	v_exp_f32_e32 v88, v42
	ds_read_b128 v[42:45], v100
	ds_read_b128 v[46:49], v100 offset:64
	s_waitcnt vmcnt(15) lgkmcnt(1)
	v_mfma_f32_16x16x32_bf16 v[42:45], v[42:45], v[38:41], 0
	v_readlane_b32 s4, v128, 3
	s_waitcnt vmcnt(14) lgkmcnt(0)
	v_mfma_f32_16x16x32_bf16 v[42:45], v[46:49], v[34:37], v[42:45]
	ds_read_b128 v[46:49], v100 offset:2304
	ds_read_b128 v[50:53], v100 offset:2368
	s_waitcnt lgkmcnt(1)
	v_mfma_f32_16x16x32_bf16 v[46:49], v[46:49], v[38:41], 0
	s_waitcnt lgkmcnt(0)
	v_mfma_f32_16x16x32_bf16 v[46:49], v[50:53], v[34:37], v[46:49]
	ds_read_b128 v[50:53], v100 offset:4608
	ds_read_b128 v[54:57], v100 offset:4672
	s_waitcnt lgkmcnt(1)
	v_mfma_f32_16x16x32_bf16 v[50:53], v[50:53], v[38:41], 0
	s_waitcnt lgkmcnt(0)
	v_mfma_f32_16x16x32_bf16 v[50:53], v[54:57], v[34:37], v[50:53]
	ds_read_b128 v[54:57], v100 offset:6912
	ds_read_b128 v[60:63], v100 offset:6976
	s_waitcnt lgkmcnt(1)
	v_mfma_f32_16x16x32_bf16 v[54:57], v[54:57], v[38:41], 0
	s_waitcnt lgkmcnt(0)
	v_mfma_f32_16x16x32_bf16 v[54:57], v[60:63], v[34:37], v[54:57]
	ds_read_b128 v[60:63], v100 offset:9216
	ds_read_b128 v[64:67], v100 offset:9280
	s_waitcnt lgkmcnt(1)
	v_mfma_f32_16x16x32_bf16 v[60:63], v[60:63], v[38:41], 0
	s_waitcnt lgkmcnt(0)
	v_mfma_f32_16x16x32_bf16 v[60:63], v[64:67], v[34:37], v[60:63]
	ds_read_b128 v[64:67], v100 offset:11520
	ds_read_b128 v[68:71], v100 offset:11584
	s_waitcnt lgkmcnt(1)
	v_mfma_f32_16x16x32_bf16 v[64:67], v[64:67], v[38:41], 0
	s_waitcnt lgkmcnt(0)
	v_mfma_f32_16x16x32_bf16 v[64:67], v[68:71], v[34:37], v[64:67]
	ds_read_b128 v[68:71], v100 offset:13824
	ds_read_b128 v[72:75], v100 offset:13888
	s_waitcnt lgkmcnt(1)
	v_mfma_f32_16x16x32_bf16 v[68:71], v[68:71], v[38:41], 0
	s_waitcnt lgkmcnt(0)
	v_mfma_f32_16x16x32_bf16 v[68:71], v[72:75], v[34:37], v[68:71]
	ds_read_b128 v[72:75], v100 offset:16128
	ds_read_b128 v[76:79], v100 offset:16192
	s_waitcnt lgkmcnt(1)
	v_mfma_f32_16x16x32_bf16 v[72:75], v[72:75], v[38:41], 0
	s_waitcnt lgkmcnt(0)
	v_mfma_f32_16x16x32_bf16 v[72:75], v[76:79], v[34:37], v[72:75]
	ds_read_b128 v[76:79], v100 offset:18432
	ds_read_b128 v[80:83], v100 offset:18496
	s_waitcnt lgkmcnt(1)
	v_mfma_f32_16x16x32_bf16 v[76:79], v[76:79], v[38:41], 0
	s_waitcnt lgkmcnt(0)
	v_mfma_f32_16x16x32_bf16 v[76:79], v[80:83], v[34:37], v[76:79]
	ds_read_b128 v[80:83], v100 offset:20736
	ds_read_b128 v[84:87], v100 offset:20800
	s_waitcnt lgkmcnt(1)
	v_mfma_f32_16x16x32_bf16 v[38:41], v[80:83], v[38:41], 0
	s_waitcnt lgkmcnt(0)
	v_mfma_f32_16x16x32_bf16 v[34:37], v[84:87], v[34:37], v[38:41]
	s_nop 5
	v_mul_f32_e32 v38, 0xbfb8aa3b, v88
	v_mul_f32_e32 v39, 0x3e38aa3b, v42
	v_mul_f32_e32 v40, 0x3e38aa3b, v43
	v_fmac_f32_e32 v39, v129, v38
	v_fmac_f32_e32 v40, v130, v38
	v_mul_f32_e32 v42, 0x3e38aa3b, v44
	v_mul_f32_e32 v43, 0x3e38aa3b, v45
	v_max3_f32 v41, v39, s75, v40
	v_fmac_f32_e32 v42, v131, v38
	v_fmac_f32_e32 v43, v132, v38
	v_mul_f32_e32 v44, 0x3e38aa3b, v46
	v_mul_f32_e32 v45, 0x3e38aa3b, v47
	v_max3_f32 v41, v41, v42, v43
	v_fmac_f32_e32 v44, v133, v38
	v_fmac_f32_e32 v45, v134, v38
	v_mul_f32_e32 v46, 0x3e38aa3b, v48
	v_mul_f32_e32 v47, 0x3e38aa3b, v49
	v_max3_f32 v41, v41, v44, v45
	v_fmac_f32_e32 v46, v135, v38
	v_fmac_f32_e32 v47, v136, v38
	v_mul_f32_e32 v48, 0x3e38aa3b, v50
	v_mul_f32_e32 v49, 0x3e38aa3b, v51
	v_max3_f32 v41, v41, v46, v47
	v_fmac_f32_e32 v48, v137, v38
	v_fmac_f32_e32 v49, v138, v38
	v_mul_f32_e32 v50, 0x3e38aa3b, v52
	v_mul_f32_e32 v52, 0x3e38aa3b, v53
	v_max3_f32 v41, v41, v48, v49
	v_fmac_f32_e32 v50, v139, v38
	v_fmac_f32_e32 v52, v140, v38
	v_mul_f32_e32 v53, 0x3e38aa3b, v54
	v_mul_f32_e32 v54, 0x3e38aa3b, v55
	v_max3_f32 v41, v41, v50, v52
	v_fmac_f32_e32 v53, v141, v38
	v_fmac_f32_e32 v54, v142, v38
	v_mul_f32_e32 v55, 0x3e38aa3b, v56
	v_mul_f32_e32 v56, 0x3e38aa3b, v57
	v_max3_f32 v41, v41, v53, v54
	v_fmac_f32_e32 v55, v143, v38
	v_fmac_f32_e32 v56, v144, v38
	v_mul_f32_e32 v57, 0x3e38aa3b, v60
	v_mul_f32_e32 v60, 0x3e38aa3b, v61
	v_max3_f32 v41, v41, v55, v56
	v_fmac_f32_e32 v57, v145, v38
	v_fmac_f32_e32 v60, v146, v38
	v_mul_f32_e32 v61, 0x3e38aa3b, v62
	v_mul_f32_e32 v62, 0x3e38aa3b, v63
	v_max3_f32 v41, v41, v57, v60
	v_fmac_f32_e32 v61, v147, v38
	v_fmac_f32_e32 v62, v148, v38
	v_mul_f32_e32 v63, 0x3e38aa3b, v64
	v_mul_f32_e32 v64, 0x3e38aa3b, v65
	v_max3_f32 v41, v41, v61, v62
	v_fmac_f32_e32 v63, v149, v38
	v_fmac_f32_e32 v64, v150, v38
	v_mul_f32_e32 v65, 0x3e38aa3b, v66
	v_mul_f32_e32 v66, 0x3e38aa3b, v67
	v_max3_f32 v41, v41, v63, v64
	v_fmac_f32_e32 v65, v151, v38
	v_fmac_f32_e32 v66, v152, v38
	v_mul_f32_e32 v67, 0x3e38aa3b, v68
	v_mul_f32_e32 v68, 0x3e38aa3b, v69
	v_max3_f32 v41, v41, v65, v66
	v_fmac_f32_e32 v67, v153, v38
	v_fmac_f32_e32 v68, v154, v38
	v_mul_f32_e32 v69, 0x3e38aa3b, v70
	v_mul_f32_e32 v70, 0x3e38aa3b, v71
	v_max3_f32 v41, v41, v67, v68
	v_fmac_f32_e32 v69, v155, v38
	v_fmac_f32_e32 v70, v156, v38
	v_mul_f32_e32 v71, 0x3e38aa3b, v72
	v_mul_f32_e32 v72, 0x3e38aa3b, v73
	v_max3_f32 v41, v41, v69, v70
	v_fmac_f32_e32 v71, v157, v38
	v_fmac_f32_e32 v72, v158, v38
	v_mul_f32_e32 v73, 0x3e38aa3b, v74
	v_mul_f32_e32 v74, 0x3e38aa3b, v75
	v_max3_f32 v41, v41, v71, v72
	v_fmac_f32_e32 v73, v159, v38
	v_fmac_f32_e32 v74, v160, v38
	v_mul_f32_e32 v75, 0x3e38aa3b, v76
	v_mul_f32_e32 v76, 0x3e38aa3b, v77
	v_max3_f32 v41, v41, v73, v74
	v_fmac_f32_e32 v75, v161, v38
	v_fmac_f32_e32 v76, v162, v38
	v_mul_f32_e32 v77, 0x3e38aa3b, v78
	v_mul_f32_e32 v78, 0x3e38aa3b, v79
	v_max3_f32 v41, v41, v75, v76
	v_fmac_f32_e32 v77, v163, v38
	v_fmac_f32_e32 v78, v164, v38
	v_mul_f32_e32 v34, 0x3e38aa3b, v34
	v_mul_f32_e32 v79, 0x3e38aa3b, v35
	v_max3_f32 v41, v41, v77, v78
	v_fmac_f32_e32 v34, v165, v38
	v_fmac_f32_e32 v79, v166, v38
	v_max3_f32 v35, v41, v34, v79
	v_mul_f32_e32 v41, 0x3e38aa3b, v36
	v_mul_f32_e32 v80, 0x3e38aa3b, v37
	v_fmac_f32_e32 v41, v167, v38
	v_fmac_f32_e32 v80, v168, v38
	v_max3_f32 v35, v35, v41, v80
	v_mov_b32_e32 v37, v35
	s_nop 1
	v_permlane16_swap_b32_e32 v37, v35
	v_mul_f32_e32 v36, s4, v249
	s_waitcnt lgkmcnt(0)
	v_max_f32_e32 v37, v37, v37
	v_max_f32_e32 v35, v35, v37
	v_mov_b32_e32 v37, v35
	s_nop 1
	v_permlane32_swap_b32_e32 v37, v35
	s_waitcnt lgkmcnt(0)
	v_max3_f32 v81, v35, v37, v36
	v_sub_f32_e32 v35, v39, v81
	v_exp_f32_e32 v82, v35
	v_sub_f32_e32 v36, v40, v81
	v_exp_f32_e32 v83, v36
	v_sub_f32_e32 v36, v42, v81
	v_exp_f32_e32 v84, v36
	v_sub_f32_e32 v36, v43, v81
	v_exp_f32_e32 v85, v36
	v_sub_f32_e32 v36, v44, v81
	v_add_f32_e32 v35, 0, v82
	v_exp_f32_e32 v86, v36
	v_sub_f32_e32 v36, v45, v81
	v_add_f32_e32 v35, v83, v35
	v_exp_f32_e32 v87, v36
	v_sub_f32_e32 v36, v46, v81
	v_add_f32_e32 v35, v84, v35
	v_exp_f32_e32 v88, v36
	v_sub_f32_e32 v36, v47, v81
	v_add_f32_e32 v35, v85, v35
	v_exp_f32_e32 v89, v36
	v_sub_f32_e32 v36, v48, v81
	v_add_f32_e32 v35, v86, v35
	v_exp_f32_e32 v51, v36
	v_sub_f32_e32 v36, v49, v81
	v_add_f32_e32 v35, v87, v35
	v_exp_f32_e32 v99, v36
	v_sub_f32_e32 v36, v50, v81
	v_add_f32_e32 v35, v88, v35
	v_exp_f32_e32 v101, v36
	v_sub_f32_e32 v36, v52, v81
	v_add_f32_e32 v35, v89, v35
	v_exp_f32_e32 v102, v36
	v_sub_f32_e32 v36, v53, v81
	v_add_f32_e32 v35, v51, v35
	v_exp_f32_e32 v103, v36
	v_sub_f32_e32 v36, v54, v81
	v_add_f32_e32 v35, v99, v35
	v_exp_f32_e32 v169, v36
	v_sub_f32_e32 v36, v55, v81
	v_add_f32_e32 v35, v101, v35
	v_exp_f32_e32 v55, v36
	v_sub_f32_e32 v36, v56, v81
	v_add_f32_e32 v35, v102, v35
	v_exp_f32_e32 v56, v36
	v_sub_f32_e32 v36, v57, v81
	v_add_f32_e32 v35, v103, v35
	v_exp_f32_e32 v46, v36
	v_sub_f32_e32 v36, v60, v81
	v_add_f32_e32 v35, v169, v35
	v_exp_f32_e32 v49, v36
	v_sub_f32_e32 v36, v61, v81
	v_add_f32_e32 v35, v55, v35
	v_exp_f32_e32 v50, v36
	v_sub_f32_e32 v36, v62, v81
	v_add_f32_e32 v35, v56, v35
	v_exp_f32_e32 v54, v36
	v_sub_f32_e32 v36, v63, v81
	v_add_f32_e32 v35, v46, v35
	v_exp_f32_e32 v57, v36
	v_sub_f32_e32 v36, v64, v81
	v_add_f32_e32 v35, v49, v35
	v_exp_f32_e32 v170, v36
	v_sub_f32_e32 v36, v65, v81
	v_add_f32_e32 v35, v50, v35
	v_exp_f32_e32 v171, v36
	v_sub_f32_e32 v36, v66, v81
	v_add_f32_e32 v35, v54, v35
	v_exp_f32_e32 v172, v36
	v_sub_f32_e32 v36, v67, v81
	v_add_f32_e32 v35, v57, v35
	v_exp_f32_e32 v43, v36
	v_sub_f32_e32 v36, v68, v81
	v_add_f32_e32 v35, v170, v35
	v_exp_f32_e32 v44, v36
	v_sub_f32_e32 v36, v69, v81
	v_add_f32_e32 v35, v171, v35
	v_exp_f32_e32 v45, v36
	v_sub_f32_e32 v36, v70, v81
	v_add_f32_e32 v35, v172, v35
	v_exp_f32_e32 v47, v36
	v_sub_f32_e32 v36, v71, v81
	v_add_f32_e32 v35, v43, v35
	v_exp_f32_e32 v48, v36
	v_sub_f32_e32 v36, v72, v81
	v_add_f32_e32 v35, v44, v35
	v_exp_f32_e32 v52, v36
	v_sub_f32_e32 v36, v73, v81
	v_add_f32_e32 v35, v45, v35
	v_exp_f32_e32 v53, v36
	v_sub_f32_e32 v36, v74, v81
	v_add_f32_e32 v35, v47, v35
	v_exp_f32_e32 v173, v36
	v_add_f32_e32 v35, v48, v35
	v_add_f32_e32 v35, v52, v35
	v_add_f32_e32 v35, v53, v35
	v_add_f32_e32 v36, v173, v35
	v_sub_f32_e32 v35, v75, v81
	v_exp_f32_e32 v35, v35
	v_sub_f32_e32 v34, v34, v81
	v_sub_f32_e32 v41, v41, v81
	v_exp_f32_e32 v41, v41
	v_add_f32_e32 v37, v35, v36
	v_sub_f32_e32 v36, v76, v81
	v_exp_f32_e32 v36, v36
	v_sub_f32_e32 v42, v80, v81
	v_exp_f32_e32 v42, v42
	v_add_f32_e32 v38, v36, v37
	v_sub_f32_e32 v37, v77, v81
	v_exp_f32_e32 v37, v37
	s_nop 0
	v_add_f32_e32 v39, v37, v38
	v_sub_f32_e32 v38, v78, v81
	v_exp_f32_e32 v38, v38
	s_nop 0
	v_add_f32_e32 v40, v38, v39
	v_exp_f32_e32 v39, v34
	s_nop 0
	v_add_f32_e32 v34, v39, v40
	v_sub_f32_e32 v40, v79, v81
	v_exp_f32_e32 v40, v40
	s_nop 0
	v_add_f32_e32 v34, v40, v34
	v_add_f32_e32 v34, v41, v34
	v_add_f32_e32 v34, v42, v34
	v_mov_b32_e32 v60, v34
	s_nop 1
	v_permlane16_swap_b32_e32 v60, v34
	s_waitcnt lgkmcnt(0)
	v_add_f32_e32 v34, v34, v60
	v_mov_b32_e32 v60, v34
	s_nop 1
	v_permlane32_swap_b32_e32 v60, v34
	s_waitcnt lgkmcnt(0)
	v_add_f32_e32 v34, v34, v60
	v_fma_f32 v60, s4, v249, -v81
	v_exp_f32_e32 v60, v60
	s_nop 0
	v_add_f32_e32 v34, v60, v34
	v_cvt_pk_bf16_f32 v60, v82, v83
	v_cvt_pk_bf16_f32 v61, v84, v85
	v_cvt_pk_bf16_f32 v62, v86, v87
	v_cvt_pk_bf16_f32 v63, v88, v89
	ds_read_b64_tr_b16 v[66:67], v98 offset:39168
	ds_read_b64_tr_b16 v[64:65], v98 offset:36864
	ds_read_b64_tr_b16 v[68:69], v98 offset:36896
	ds_read_b64_tr_b16 v[70:71], v98 offset:39200
	ds_read_b64_tr_b16 v[72:73], v98 offset:36928
	ds_read_b64_tr_b16 v[74:75], v98 offset:39232
	ds_read_b64_tr_b16 v[76:77], v98 offset:36960
	ds_read_b64_tr_b16 v[78:79], v98 offset:39264
	s_waitcnt lgkmcnt(6)
	v_mfma_f32_16x16x32_bf16 v[64:67], v[64:67], v[60:63], 0
	s_waitcnt lgkmcnt(4)
	v_mfma_f32_16x16x32_bf16 v[68:71], v[68:71], v[60:63], 0
	s_waitcnt lgkmcnt(2)
	v_mfma_f32_16x16x32_bf16 v[72:75], v[72:75], v[60:63], 0
	s_waitcnt lgkmcnt(0)
	v_mfma_f32_16x16x32_bf16 v[60:63], v[76:79], v[60:63], 0
	v_cvt_pk_bf16_f32 v76, v51, v99
	v_cvt_pk_bf16_f32 v77, v101, v102
	v_cvt_pk_bf16_f32 v78, v103, v169
	v_cvt_pk_bf16_f32 v79, v55, v56
	ds_read_b64_tr_b16 v[82:83], v98 offset:43776
	ds_read_b64_tr_b16 v[80:81], v98 offset:41472
	ds_read_b64_tr_b16 v[84:85], v98 offset:41504
	s_waitcnt lgkmcnt(1)
	v_mfma_f32_16x16x32_bf16 v[64:67], v[80:83], v[76:79], v[64:67]
	ds_read_b64_tr_b16 v[86:87], v98 offset:43808
	ds_read_b64_tr_b16 v[80:81], v98 offset:41536
	ds_read_b64_tr_b16 v[82:83], v98 offset:43840
	s_waitcnt lgkmcnt(0)
	v_mfma_f32_16x16x32_bf16 v[72:75], v[80:83], v[76:79], v[72:75]
	ds_read_b64_tr_b16 v[80:81], v98 offset:41568
	ds_read_b64_tr_b16 v[82:83], v98 offset:43872
	v_mfma_f32_16x16x32_bf16 v[68:71], v[84:87], v[76:79], v[68:71]
	s_waitcnt lgkmcnt(0)
	v_mfma_f32_16x16x32_bf16 v[60:63], v[80:83], v[76:79], v[60:63]
	v_cvt_pk_bf16_f32 v76, v46, v49
	v_cvt_pk_bf16_f32 v77, v50, v54
	v_cvt_pk_bf16_f32 v78, v57, v170
	v_cvt_pk_bf16_f32 v79, v171, v172
	ds_read_b64_tr_b16 v[56:57], v98 offset:48384
	ds_read_b64_tr_b16 v[54:55], v98 offset:46080
	ds_read_b64_tr_b16 v[80:81], v98 offset:46112
	ds_read_b64_tr_b16 v[82:83], v98 offset:48416
	s_waitcnt lgkmcnt(2)
	v_mfma_f32_16x16x32_bf16 v[54:57], v[54:57], v[76:79], v[64:67]
	s_waitcnt lgkmcnt(0)
	v_mfma_f32_16x16x32_bf16 v[64:67], v[80:83], v[76:79], v[68:71]
	s_nop 2
	ds_read_b64_tr_b16 v[68:69], v98 offset:46144
	ds_read_b64_tr_b16 v[70:71], v98 offset:48448
	s_waitcnt lgkmcnt(0)
	v_mfma_f32_16x16x32_bf16 v[68:71], v[68:71], v[76:79], v[72:75]
	s_nop 2
	ds_read_b64_tr_b16 v[72:73], v98 offset:46176
	ds_read_b64_tr_b16 v[74:75], v98 offset:48480
	v_cvt_pk_bf16_f32 v44, v43, v44
	v_cvt_pk_bf16_f32 v45, v45, v47
	v_cvt_pk_bf16_f32 v46, v48, v52
	v_cvt_pk_bf16_f32 v47, v53, v173
	ds_read_b64_tr_b16 v[50:51], v98 offset:52992
	ds_read_b64_tr_b16 v[48:49], v98 offset:50688
	ds_read_b64_tr_b16 v[52:53], v98 offset:50720
	s_waitcnt lgkmcnt(1)
	v_mfma_f32_16x16x32_bf16 v[48:51], v[48:51], v[44:47], v[54:57]
	s_nop 2
	ds_read_b64_tr_b16 v[54:55], v98 offset:53024
	s_waitcnt lgkmcnt(0)
	v_mfma_f32_16x16x32_bf16 v[52:55], v[52:55], v[44:47], v[64:67]
	s_nop 2
	ds_read_b64_tr_b16 v[64:65], v98 offset:50752
	ds_read_b64_tr_b16 v[66:67], v98 offset:53056
	s_waitcnt lgkmcnt(0)
	v_mfma_f32_16x16x32_bf16 v[64:67], v[64:67], v[44:47], v[68:71]
	s_nop 2
	ds_read_b64_tr_b16 v[68:69], v98 offset:50784
	ds_read_b64_tr_b16 v[70:71], v98 offset:53088
	v_cvt_pk_bf16_f32 v36, v35, v36
	v_cvt_pk_bf16_f32 v37, v37, v38
	v_mfma_f32_16x16x32_bf16 v[60:63], v[72:75], v[76:79], v[60:63]
	v_cvt_pk_bf16_f32 v38, v39, v40
	v_cvt_pk_bf16_f32 v39, v41, v42
	v_div_scale_f32 v35, s[4:5], v34, v34, 1.0
	s_waitcnt lgkmcnt(0)
	v_mfma_f32_16x16x32_bf16 v[44:47], v[68:71], v[44:47], v[60:63]
	ds_read_b64_tr_b16 v[42:43], v98 offset:57600
	ds_read_b64_tr_b16 v[40:41], v98 offset:55296
	s_nop 2
	ds_read_b64_tr_b16 v[60:61], v98 offset:55328
	ds_read_b64_tr_b16 v[62:63], v98 offset:57632
	s_or_b32 s4, s17, 5
	s_waitcnt lgkmcnt(2)
	v_mfma_f32_16x16x32_bf16 v[40:43], v[40:43], v[36:39], v[48:51]
	s_waitcnt lgkmcnt(0)
	v_mfma_f32_16x16x32_bf16 v[48:51], v[60:63], v[36:39], v[52:55]
	s_nop 2
	ds_read_b64_tr_b16 v[52:53], v98 offset:55360
	ds_read_b64_tr_b16 v[54:55], v98 offset:57664
	ds_read_b64_tr_b16 v[60:61], v98 offset:55392
	ds_read_b64_tr_b16 v[62:63], v98 offset:57696
	s_waitcnt lgkmcnt(2)
	v_mfma_f32_16x16x32_bf16 v[52:55], v[52:55], v[36:39], v[64:67]
	s_waitcnt lgkmcnt(0)
	v_mfma_f32_16x16x32_bf16 v[36:39], v[60:63], v[36:39], v[44:47]
	s_nop 2
	v_rcp_f32_e32 v44, v35
	s_nop 0
	v_fma_f32 v45, -v35, v44, 1.0
	v_fmac_f32_e32 v44, v45, v44
	v_div_scale_f32 v45, vcc, 1.0, v34, 1.0
	v_mul_f32_e32 v46, v45, v44
	v_fma_f32 v47, -v35, v46, v45
	v_fmac_f32_e32 v46, v47, v44
	v_fma_f32 v35, -v35, v46, v45
	v_div_fmas_f32 v35, v35, v44, v46
	v_div_fixup_f32 v34, v35, v34, 1.0
	v_pk_mul_f32 v[42:43], v[34:35], v[42:43] op_sel_hi:[0,1]
	v_pk_mul_f32 v[40:41], v[34:35], v[40:41] op_sel_hi:[0,1]
	v_pk_mul_f32 v[44:45], v[34:35], v[50:51] op_sel_hi:[0,1]
	v_pk_mul_f32 v[46:47], v[34:35], v[48:49] op_sel_hi:[0,1]
	v_cvt_pk_bf16_f32 v40, v40, v41
	v_cvt_pk_bf16_f32 v41, v42, v43
	v_cvt_pk_bf16_f32 v42, v46, v47
	v_cvt_pk_bf16_f32 v43, v44, v45
	global_store_dwordx4 v[58:59], v[40:43], off offset:384
	v_pk_mul_f32 v[38:39], v[34:35], v[38:39] op_sel_hi:[0,1]
	v_pk_mul_f32 v[36:37], v[34:35], v[36:37] op_sel_hi:[0,1]
	v_pk_mul_f32 v[40:41], v[34:35], v[54:55] op_sel_hi:[0,1]
	v_pk_mul_f32 v[42:43], v[34:35], v[52:53] op_sel_hi:[0,1]
	v_cvt_pk_bf16_f32 v34, v42, v43
	v_cvt_pk_bf16_f32 v35, v40, v41
	v_cvt_pk_bf16_f32 v36, v36, v37
	v_cvt_pk_bf16_f32 v37, v38, v39
	global_store_dwordx4 v[58:59], v[34:37], off offset:448
	s_nop 1
	v_cvt_f32_ubyte0_e32 v34, s4
	v_mul_f32_e32 v34, -0.5, v34
	v_exp_f32_e32 v80, v34
	ds_read_b128 v[34:37], v100
	ds_read_b128 v[38:41], v100 offset:64
	s_waitcnt vmcnt(15) lgkmcnt(1)
	v_mfma_f32_16x16x32_bf16 v[34:37], v[34:37], v[30:33], 0
	v_readlane_b32 s4, v128, 4
	s_waitcnt vmcnt(14) lgkmcnt(0)
	v_mfma_f32_16x16x32_bf16 v[34:37], v[38:41], v[26:29], v[34:37]
	ds_read_b128 v[38:41], v100 offset:2304
	ds_read_b128 v[42:45], v100 offset:2368
	s_waitcnt lgkmcnt(1)
	v_mfma_f32_16x16x32_bf16 v[38:41], v[38:41], v[30:33], 0
	s_waitcnt lgkmcnt(0)
	v_mfma_f32_16x16x32_bf16 v[38:41], v[42:45], v[26:29], v[38:41]
	ds_read_b128 v[42:45], v100 offset:4608
	ds_read_b128 v[46:49], v100 offset:4672
	s_waitcnt lgkmcnt(1)
	v_mfma_f32_16x16x32_bf16 v[42:45], v[42:45], v[30:33], 0
	s_waitcnt lgkmcnt(0)
	v_mfma_f32_16x16x32_bf16 v[42:45], v[46:49], v[26:29], v[42:45]
	ds_read_b128 v[46:49], v100 offset:6912
	ds_read_b128 v[50:53], v100 offset:6976
	s_waitcnt lgkmcnt(1)
	v_mfma_f32_16x16x32_bf16 v[46:49], v[46:49], v[30:33], 0
	s_waitcnt lgkmcnt(0)
	v_mfma_f32_16x16x32_bf16 v[46:49], v[50:53], v[26:29], v[46:49]
	ds_read_b128 v[50:53], v100 offset:9216
	ds_read_b128 v[54:57], v100 offset:9280
	s_waitcnt lgkmcnt(1)
	v_mfma_f32_16x16x32_bf16 v[50:53], v[50:53], v[30:33], 0
	s_waitcnt lgkmcnt(0)
	v_mfma_f32_16x16x32_bf16 v[50:53], v[54:57], v[26:29], v[50:53]
	ds_read_b128 v[54:57], v100 offset:11520
	ds_read_b128 v[60:63], v100 offset:11584
	s_waitcnt lgkmcnt(1)
	v_mfma_f32_16x16x32_bf16 v[54:57], v[54:57], v[30:33], 0
	s_waitcnt lgkmcnt(0)
	v_mfma_f32_16x16x32_bf16 v[54:57], v[60:63], v[26:29], v[54:57]
	ds_read_b128 v[60:63], v100 offset:13824
	ds_read_b128 v[64:67], v100 offset:13888
	s_waitcnt lgkmcnt(1)
	v_mfma_f32_16x16x32_bf16 v[60:63], v[60:63], v[30:33], 0
	s_waitcnt lgkmcnt(0)
	v_mfma_f32_16x16x32_bf16 v[60:63], v[64:67], v[26:29], v[60:63]
	ds_read_b128 v[64:67], v100 offset:16128
	ds_read_b128 v[68:71], v100 offset:16192
	s_waitcnt lgkmcnt(1)
	v_mfma_f32_16x16x32_bf16 v[64:67], v[64:67], v[30:33], 0
	s_waitcnt lgkmcnt(0)
	v_mfma_f32_16x16x32_bf16 v[64:67], v[68:71], v[26:29], v[64:67]
	ds_read_b128 v[68:71], v100 offset:18432
	ds_read_b128 v[72:75], v100 offset:18496
	s_waitcnt lgkmcnt(1)
	v_mfma_f32_16x16x32_bf16 v[68:71], v[68:71], v[30:33], 0
	s_waitcnt lgkmcnt(0)
	v_mfma_f32_16x16x32_bf16 v[68:71], v[72:75], v[26:29], v[68:71]
	ds_read_b128 v[72:75], v100 offset:20736
	ds_read_b128 v[76:79], v100 offset:20800
	s_waitcnt lgkmcnt(1)
	v_mfma_f32_16x16x32_bf16 v[30:33], v[72:75], v[30:33], 0
	s_waitcnt lgkmcnt(0)
	v_mfma_f32_16x16x32_bf16 v[26:29], v[76:79], v[26:29], v[30:33]
	s_nop 5
	v_mul_f32_e32 v30, 0xbfb8aa3b, v80
	v_mul_f32_e32 v31, 0x3e38aa3b, v34
	v_mul_f32_e32 v32, 0x3e38aa3b, v35
	v_fmac_f32_e32 v31, v129, v30
	v_fmac_f32_e32 v32, v130, v30
	v_mul_f32_e32 v34, 0x3e38aa3b, v36
	v_mul_f32_e32 v35, 0x3e38aa3b, v37
	v_max3_f32 v33, v31, s75, v32
	v_fmac_f32_e32 v34, v131, v30
	v_fmac_f32_e32 v35, v132, v30
	v_mul_f32_e32 v36, 0x3e38aa3b, v38
	v_mul_f32_e32 v37, 0x3e38aa3b, v39
	v_max3_f32 v33, v33, v34, v35
	v_fmac_f32_e32 v36, v133, v30
	v_fmac_f32_e32 v37, v134, v30
	v_mul_f32_e32 v38, 0x3e38aa3b, v40
	v_mul_f32_e32 v39, 0x3e38aa3b, v41
	v_max3_f32 v33, v33, v36, v37
	v_fmac_f32_e32 v38, v135, v30
	v_fmac_f32_e32 v39, v136, v30
	v_mul_f32_e32 v40, 0x3e38aa3b, v42
	v_mul_f32_e32 v41, 0x3e38aa3b, v43
	v_max3_f32 v33, v33, v38, v39
	v_fmac_f32_e32 v40, v137, v30
	v_fmac_f32_e32 v41, v138, v30
	v_mul_f32_e32 v42, 0x3e38aa3b, v44
	v_mul_f32_e32 v44, 0x3e38aa3b, v45
	v_max3_f32 v33, v33, v40, v41
	v_fmac_f32_e32 v42, v139, v30
	v_fmac_f32_e32 v44, v140, v30
	v_mul_f32_e32 v45, 0x3e38aa3b, v46
	v_mul_f32_e32 v46, 0x3e38aa3b, v47
	v_max3_f32 v33, v33, v42, v44
	v_fmac_f32_e32 v45, v141, v30
	v_fmac_f32_e32 v46, v142, v30
	v_mul_f32_e32 v47, 0x3e38aa3b, v48
	v_mul_f32_e32 v48, 0x3e38aa3b, v49
	v_max3_f32 v33, v33, v45, v46
	v_fmac_f32_e32 v47, v143, v30
	v_fmac_f32_e32 v48, v144, v30
	v_mul_f32_e32 v49, 0x3e38aa3b, v50
	v_mul_f32_e32 v50, 0x3e38aa3b, v51
	v_max3_f32 v33, v33, v47, v48
	v_fmac_f32_e32 v49, v145, v30
	v_fmac_f32_e32 v50, v146, v30
	v_mul_f32_e32 v51, 0x3e38aa3b, v52
	v_mul_f32_e32 v52, 0x3e38aa3b, v53
	v_max3_f32 v33, v33, v49, v50
	v_fmac_f32_e32 v51, v147, v30
	v_fmac_f32_e32 v52, v148, v30
	v_mul_f32_e32 v53, 0x3e38aa3b, v54
	v_mul_f32_e32 v54, 0x3e38aa3b, v55
	v_max3_f32 v33, v33, v51, v52
	v_fmac_f32_e32 v53, v149, v30
	v_fmac_f32_e32 v54, v150, v30
	v_mul_f32_e32 v55, 0x3e38aa3b, v56
	v_mul_f32_e32 v56, 0x3e38aa3b, v57
	v_max3_f32 v33, v33, v53, v54
	v_fmac_f32_e32 v55, v151, v30
	v_fmac_f32_e32 v56, v152, v30
	v_mul_f32_e32 v57, 0x3e38aa3b, v60
	v_mul_f32_e32 v60, 0x3e38aa3b, v61
	v_max3_f32 v33, v33, v55, v56
	v_fmac_f32_e32 v57, v153, v30
	v_fmac_f32_e32 v60, v154, v30
	v_mul_f32_e32 v61, 0x3e38aa3b, v62
	v_mul_f32_e32 v62, 0x3e38aa3b, v63
	v_max3_f32 v33, v33, v57, v60
	v_fmac_f32_e32 v61, v155, v30
	v_fmac_f32_e32 v62, v156, v30
	v_mul_f32_e32 v63, 0x3e38aa3b, v64
	v_mul_f32_e32 v64, 0x3e38aa3b, v65
	v_max3_f32 v33, v33, v61, v62
	v_fmac_f32_e32 v63, v157, v30
	v_fmac_f32_e32 v64, v158, v30
	v_mul_f32_e32 v65, 0x3e38aa3b, v66
	v_mul_f32_e32 v66, 0x3e38aa3b, v67
	v_max3_f32 v33, v33, v63, v64
	v_fmac_f32_e32 v65, v159, v30
	v_fmac_f32_e32 v66, v160, v30
	v_mul_f32_e32 v67, 0x3e38aa3b, v68
	v_mul_f32_e32 v68, 0x3e38aa3b, v69
	v_max3_f32 v33, v33, v65, v66
	v_fmac_f32_e32 v67, v161, v30
	v_fmac_f32_e32 v68, v162, v30
	v_mul_f32_e32 v69, 0x3e38aa3b, v70
	v_mul_f32_e32 v70, 0x3e38aa3b, v71
	v_max3_f32 v33, v33, v67, v68
	v_fmac_f32_e32 v69, v163, v30
	v_fmac_f32_e32 v70, v164, v30
	v_mul_f32_e32 v26, 0x3e38aa3b, v26
	v_mul_f32_e32 v71, 0x3e38aa3b, v27
	v_max3_f32 v33, v33, v69, v70
	v_fmac_f32_e32 v26, v165, v30
	v_fmac_f32_e32 v71, v166, v30
	v_max3_f32 v27, v33, v26, v71
	v_mul_f32_e32 v33, 0x3e38aa3b, v28
	v_mul_f32_e32 v72, 0x3e38aa3b, v29
	v_fmac_f32_e32 v33, v167, v30
	v_fmac_f32_e32 v72, v168, v30
	v_max3_f32 v27, v27, v33, v72
	v_mov_b32_e32 v29, v27
	s_nop 1
	v_permlane16_swap_b32_e32 v29, v27
	v_mul_f32_e32 v28, s4, v249
	s_waitcnt lgkmcnt(0)
	v_max_f32_e32 v29, v29, v29
	v_max_f32_e32 v27, v27, v29
	v_mov_b32_e32 v29, v27
	s_nop 1
	v_permlane32_swap_b32_e32 v29, v27
	s_waitcnt lgkmcnt(0)
	v_max3_f32 v73, v27, v29, v28
	v_sub_f32_e32 v27, v31, v73
	v_exp_f32_e32 v74, v27
	v_sub_f32_e32 v28, v32, v73
	v_exp_f32_e32 v75, v28
	v_sub_f32_e32 v28, v34, v73
	v_exp_f32_e32 v76, v28
	v_sub_f32_e32 v28, v35, v73
	v_exp_f32_e32 v77, v28
	v_sub_f32_e32 v28, v36, v73
	v_add_f32_e32 v27, 0, v74
	v_exp_f32_e32 v78, v28
	v_sub_f32_e32 v28, v37, v73
	v_add_f32_e32 v27, v75, v27
	v_exp_f32_e32 v79, v28
	v_sub_f32_e32 v28, v38, v73
	v_add_f32_e32 v27, v76, v27
	v_exp_f32_e32 v80, v28
	v_sub_f32_e32 v28, v39, v73
	v_add_f32_e32 v27, v77, v27
	v_exp_f32_e32 v81, v28
	v_sub_f32_e32 v28, v40, v73
	v_add_f32_e32 v27, v78, v27
	v_exp_f32_e32 v43, v28
	v_sub_f32_e32 v28, v41, v73
	v_add_f32_e32 v27, v79, v27
	v_exp_f32_e32 v82, v28
	v_sub_f32_e32 v28, v42, v73
	v_add_f32_e32 v27, v80, v27
	v_exp_f32_e32 v83, v28
	v_sub_f32_e32 v28, v44, v73
	v_add_f32_e32 v27, v81, v27
	v_exp_f32_e32 v84, v28
	v_sub_f32_e32 v28, v45, v73
	v_add_f32_e32 v27, v43, v27
	v_exp_f32_e32 v85, v28
	v_sub_f32_e32 v28, v46, v73
	v_add_f32_e32 v27, v82, v27
	v_exp_f32_e32 v86, v28
	v_sub_f32_e32 v28, v47, v73
	v_add_f32_e32 v27, v83, v27
	v_exp_f32_e32 v47, v28
	v_sub_f32_e32 v28, v48, v73
	v_add_f32_e32 v27, v84, v27
	v_exp_f32_e32 v87, v28
	v_sub_f32_e32 v28, v49, v73
	v_add_f32_e32 v27, v85, v27
	v_exp_f32_e32 v38, v28
	v_sub_f32_e32 v28, v50, v73
	v_add_f32_e32 v27, v86, v27
	v_exp_f32_e32 v41, v28
	v_sub_f32_e32 v28, v51, v73
	v_add_f32_e32 v27, v47, v27
	v_exp_f32_e32 v42, v28
	v_sub_f32_e32 v28, v52, v73
	v_add_f32_e32 v27, v87, v27
	v_exp_f32_e32 v46, v28
	v_sub_f32_e32 v28, v53, v73
	v_add_f32_e32 v27, v38, v27
	v_exp_f32_e32 v88, v28
	v_sub_f32_e32 v28, v54, v73
	v_add_f32_e32 v27, v41, v27
	v_exp_f32_e32 v89, v28
	v_sub_f32_e32 v28, v55, v73
	v_add_f32_e32 v27, v42, v27
	v_exp_f32_e32 v99, v28
	v_sub_f32_e32 v28, v56, v73
	v_add_f32_e32 v27, v46, v27
	v_exp_f32_e32 v56, v28
	v_sub_f32_e32 v28, v57, v73
	v_add_f32_e32 v27, v88, v27
	v_exp_f32_e32 v35, v28
	v_sub_f32_e32 v28, v60, v73
	v_add_f32_e32 v27, v89, v27
	v_exp_f32_e32 v36, v28
	v_sub_f32_e32 v28, v61, v73
	v_add_f32_e32 v27, v99, v27
	v_exp_f32_e32 v37, v28
	v_sub_f32_e32 v28, v62, v73
	v_add_f32_e32 v27, v56, v27
	v_exp_f32_e32 v39, v28
	v_sub_f32_e32 v28, v63, v73
	v_add_f32_e32 v27, v35, v27
	v_exp_f32_e32 v40, v28
	v_sub_f32_e32 v28, v64, v73
	v_add_f32_e32 v27, v36, v27
	v_exp_f32_e32 v44, v28
	v_sub_f32_e32 v28, v65, v73
	v_add_f32_e32 v27, v37, v27
	v_exp_f32_e32 v45, v28
	v_sub_f32_e32 v28, v66, v73
	v_add_f32_e32 v27, v39, v27
	v_exp_f32_e32 v57, v28
	v_add_f32_e32 v27, v40, v27
	v_add_f32_e32 v27, v44, v27
	v_add_f32_e32 v27, v45, v27
	v_add_f32_e32 v28, v57, v27
	v_sub_f32_e32 v27, v67, v73
	v_exp_f32_e32 v27, v27
	v_sub_f32_e32 v26, v26, v73
	v_sub_f32_e32 v33, v33, v73
	v_exp_f32_e32 v33, v33
	v_add_f32_e32 v29, v27, v28
	v_sub_f32_e32 v28, v68, v73
	v_exp_f32_e32 v28, v28
	v_sub_f32_e32 v34, v72, v73
	v_exp_f32_e32 v34, v34
	v_add_f32_e32 v30, v28, v29
	v_sub_f32_e32 v29, v69, v73
	v_exp_f32_e32 v29, v29
	s_nop 0
	v_add_f32_e32 v31, v29, v30
	v_sub_f32_e32 v30, v70, v73
	v_exp_f32_e32 v30, v30
	s_nop 0
	v_add_f32_e32 v32, v30, v31
	v_exp_f32_e32 v31, v26
	s_nop 0
	v_add_f32_e32 v26, v31, v32
	v_sub_f32_e32 v32, v71, v73
	v_exp_f32_e32 v32, v32
	s_nop 0
	v_add_f32_e32 v26, v32, v26
	v_add_f32_e32 v26, v33, v26
	v_add_f32_e32 v26, v34, v26
	v_mov_b32_e32 v48, v26
	s_nop 1
	v_permlane16_swap_b32_e32 v48, v26
	s_waitcnt lgkmcnt(0)
	v_add_f32_e32 v26, v26, v48
	v_mov_b32_e32 v48, v26
	s_nop 1
	v_permlane32_swap_b32_e32 v48, v26
	s_waitcnt lgkmcnt(0)
	v_add_f32_e32 v26, v26, v48
	v_fma_f32 v48, s4, v249, -v73
	v_exp_f32_e32 v48, v48
	s_nop 0
	v_add_f32_e32 v26, v48, v26
	v_cvt_pk_bf16_f32 v48, v74, v75
	v_cvt_pk_bf16_f32 v49, v76, v77
	v_cvt_pk_bf16_f32 v50, v78, v79
	v_cvt_pk_bf16_f32 v51, v80, v81
	ds_read_b64_tr_b16 v[54:55], v98 offset:39168
	ds_read_b64_tr_b16 v[52:53], v98 offset:36864
	ds_read_b64_tr_b16 v[60:61], v98 offset:36896
	ds_read_b64_tr_b16 v[62:63], v98 offset:39200
	ds_read_b64_tr_b16 v[64:65], v98 offset:36928
	ds_read_b64_tr_b16 v[66:67], v98 offset:39232
	ds_read_b64_tr_b16 v[68:69], v98 offset:36960
	ds_read_b64_tr_b16 v[70:71], v98 offset:39264
	s_waitcnt lgkmcnt(6)
	v_mfma_f32_16x16x32_bf16 v[52:55], v[52:55], v[48:51], 0
	s_waitcnt lgkmcnt(4)
	v_mfma_f32_16x16x32_bf16 v[60:63], v[60:63], v[48:51], 0
	s_waitcnt lgkmcnt(2)
	v_mfma_f32_16x16x32_bf16 v[64:67], v[64:67], v[48:51], 0
	s_waitcnt lgkmcnt(0)
	v_mfma_f32_16x16x32_bf16 v[48:51], v[68:71], v[48:51], 0
	v_cvt_pk_bf16_f32 v68, v43, v82
	v_cvt_pk_bf16_f32 v69, v83, v84
	v_cvt_pk_bf16_f32 v70, v85, v86
	v_cvt_pk_bf16_f32 v71, v47, v87
	ds_read_b64_tr_b16 v[74:75], v98 offset:43776
	ds_read_b64_tr_b16 v[72:73], v98 offset:41472
	ds_read_b64_tr_b16 v[76:77], v98 offset:41504
	s_waitcnt lgkmcnt(1)
	v_mfma_f32_16x16x32_bf16 v[52:55], v[72:75], v[68:71], v[52:55]
	ds_read_b64_tr_b16 v[78:79], v98 offset:43808
	ds_read_b64_tr_b16 v[72:73], v98 offset:41536
	ds_read_b64_tr_b16 v[74:75], v98 offset:43840
	s_waitcnt lgkmcnt(0)
	v_mfma_f32_16x16x32_bf16 v[64:67], v[72:75], v[68:71], v[64:67]
	ds_read_b64_tr_b16 v[72:73], v98 offset:41568
	ds_read_b64_tr_b16 v[74:75], v98 offset:43872
	v_mfma_f32_16x16x32_bf16 v[60:63], v[76:79], v[68:71], v[60:63]
	s_waitcnt lgkmcnt(0)
	v_mfma_f32_16x16x32_bf16 v[48:51], v[72:75], v[68:71], v[48:51]
	v_cvt_pk_bf16_f32 v68, v38, v41
	v_cvt_pk_bf16_f32 v69, v42, v46
	v_cvt_pk_bf16_f32 v70, v88, v89
	v_cvt_pk_bf16_f32 v71, v99, v56
	ds_read_b64_tr_b16 v[74:75], v98 offset:48384
	ds_read_b64_tr_b16 v[72:73], v98 offset:46080
	ds_read_b64_tr_b16 v[76:77], v98 offset:46112
	s_waitcnt lgkmcnt(1)
	v_mfma_f32_16x16x32_bf16 v[52:55], v[72:75], v[68:71], v[52:55]
	ds_read_b64_tr_b16 v[78:79], v98 offset:48416
	ds_read_b64_tr_b16 v[72:73], v98 offset:46144
	ds_read_b64_tr_b16 v[74:75], v98 offset:48448
	s_waitcnt lgkmcnt(0)
	v_mfma_f32_16x16x32_bf16 v[64:67], v[72:75], v[68:71], v[64:67]
	ds_read_b64_tr_b16 v[72:73], v98 offset:46176
	ds_read_b64_tr_b16 v[74:75], v98 offset:48480
	v_cvt_pk_bf16_f32 v36, v35, v36
	v_cvt_pk_bf16_f32 v37, v37, v39
	s_waitcnt lgkmcnt(0)
	v_mfma_f32_16x16x32_bf16 v[46:49], v[72:75], v[68:71], v[48:51]
	v_cvt_pk_bf16_f32 v38, v40, v44
	v_cvt_pk_bf16_f32 v39, v45, v57
	ds_read_b64_tr_b16 v[42:43], v98 offset:52992
	ds_read_b64_tr_b16 v[40:41], v98 offset:50688
	s_nop 0
	ds_read_b64_tr_b16 v[50:51], v98 offset:50720
	s_waitcnt lgkmcnt(1)
	v_mfma_f32_16x16x32_bf16 v[40:43], v[40:43], v[36:39], v[52:55]
	s_nop 2
	ds_read_b64_tr_b16 v[52:53], v98 offset:53024
	ds_read_b64_tr_b16 v[54:55], v98 offset:50752
	ds_read_b64_tr_b16 v[56:57], v98 offset:53056
	v_mfma_f32_16x16x32_bf16 v[60:63], v[76:79], v[68:71], v[60:63]
	s_waitcnt lgkmcnt(2)
	v_mfma_f32_16x16x32_bf16 v[50:53], v[50:53], v[36:39], v[60:63]
	s_nop 5
	ds_read_b64_tr_b16 v[60:61], v98 offset:50784
	ds_read_b64_tr_b16 v[62:63], v98 offset:53088
	v_cvt_pk_bf16_f32 v28, v27, v28
	v_cvt_pk_bf16_f32 v29, v29, v30
	s_waitcnt lgkmcnt(2)
	v_mfma_f32_16x16x32_bf16 v[54:57], v[54:57], v[36:39], v[64:67]
	v_cvt_pk_bf16_f32 v30, v31, v32
	v_cvt_pk_bf16_f32 v31, v33, v34
	ds_read_b64_tr_b16 v[34:35], v98 offset:57600
	ds_read_b64_tr_b16 v[32:33], v98 offset:55296
	ds_read_b64_tr_b16 v[44:45], v98 offset:55328
	s_waitcnt lgkmcnt(3)
	v_mfma_f32_16x16x32_bf16 v[36:39], v[60:63], v[36:39], v[46:49]
	v_div_scale_f32 v27, s[4:5], v26, v26, 1.0
	s_or_b32 s4, s17, 6
	s_nop 0
	ds_read_b64_tr_b16 v[46:47], v98 offset:57632
	s_waitcnt lgkmcnt(2)
	v_mfma_f32_16x16x32_bf16 v[32:35], v[32:35], v[28:31], v[40:43]
	s_waitcnt lgkmcnt(0)
	v_mfma_f32_16x16x32_bf16 v[40:43], v[44:47], v[28:31], v[50:53]
	ds_read_b64_tr_b16 v[44:45], v98 offset:55360
	ds_read_b64_tr_b16 v[46:47], v98 offset:57664
	ds_read_b64_tr_b16 v[48:49], v98 offset:55392
	ds_read_b64_tr_b16 v[50:51], v98 offset:57696
	s_waitcnt lgkmcnt(2)
	v_mfma_f32_16x16x32_bf16 v[44:47], v[44:47], v[28:31], v[54:57]
	s_waitcnt lgkmcnt(0)
	v_mfma_f32_16x16x32_bf16 v[28:31], v[48:51], v[28:31], v[36:39]
	s_nop 2
	v_rcp_f32_e32 v36, v27
	s_nop 0
	v_fma_f32 v37, -v27, v36, 1.0
	v_fmac_f32_e32 v36, v37, v36
	v_div_scale_f32 v37, vcc, 1.0, v26, 1.0
	v_mul_f32_e32 v38, v37, v36
	v_fma_f32 v39, -v27, v38, v37
	v_fmac_f32_e32 v38, v39, v36
	v_fma_f32 v27, -v27, v38, v37
	v_div_fmas_f32 v27, v27, v36, v38
	v_div_fixup_f32 v26, v27, v26, 1.0
	v_pk_mul_f32 v[34:35], v[26:27], v[34:35] op_sel_hi:[0,1]
	v_pk_mul_f32 v[32:33], v[26:27], v[32:33] op_sel_hi:[0,1]
	v_pk_mul_f32 v[36:37], v[26:27], v[42:43] op_sel_hi:[0,1]
	v_pk_mul_f32 v[38:39], v[26:27], v[40:41] op_sel_hi:[0,1]
	v_cvt_pk_bf16_f32 v32, v32, v33
	v_cvt_pk_bf16_f32 v33, v34, v35
	v_cvt_pk_bf16_f32 v34, v38, v39
	v_cvt_pk_bf16_f32 v35, v36, v37
	global_store_dwordx4 v[58:59], v[32:35], off offset:512
	v_pk_mul_f32 v[30:31], v[26:27], v[30:31] op_sel_hi:[0,1]
	v_pk_mul_f32 v[28:29], v[26:27], v[28:29] op_sel_hi:[0,1]
	v_pk_mul_f32 v[32:33], v[26:27], v[46:47] op_sel_hi:[0,1]
	v_pk_mul_f32 v[34:35], v[26:27], v[44:45] op_sel_hi:[0,1]
	v_cvt_pk_bf16_f32 v26, v34, v35
	v_cvt_pk_bf16_f32 v27, v32, v33
	v_cvt_pk_bf16_f32 v28, v28, v29
	v_cvt_pk_bf16_f32 v29, v30, v31
	global_store_dwordx4 v[58:59], v[26:29], off offset:576
	s_nop 1
	v_cvt_f32_ubyte0_e32 v26, s4
	v_mul_f32_e32 v26, -0.5, v26
	v_exp_f32_e32 v72, v26
	ds_read_b128 v[26:29], v100
	ds_read_b128 v[30:33], v100 offset:64
	s_waitcnt vmcnt(15) lgkmcnt(1)
	v_mfma_f32_16x16x32_bf16 v[26:29], v[26:29], v[22:25], 0
	v_readlane_b32 s4, v128, 5
	s_waitcnt vmcnt(14) lgkmcnt(0)
	v_mfma_f32_16x16x32_bf16 v[26:29], v[30:33], v[18:21], v[26:29]
	ds_read_b128 v[30:33], v100 offset:2304
	ds_read_b128 v[34:37], v100 offset:2368
	s_waitcnt lgkmcnt(1)
	v_mfma_f32_16x16x32_bf16 v[30:33], v[30:33], v[22:25], 0
	s_waitcnt lgkmcnt(0)
	v_mfma_f32_16x16x32_bf16 v[30:33], v[34:37], v[18:21], v[30:33]
	ds_read_b128 v[34:37], v100 offset:4608
	ds_read_b128 v[38:41], v100 offset:4672
	s_waitcnt lgkmcnt(1)
	v_mfma_f32_16x16x32_bf16 v[34:37], v[34:37], v[22:25], 0
	s_waitcnt lgkmcnt(0)
	v_mfma_f32_16x16x32_bf16 v[34:37], v[38:41], v[18:21], v[34:37]
	ds_read_b128 v[38:41], v100 offset:6912
	ds_read_b128 v[42:45], v100 offset:6976
	s_waitcnt lgkmcnt(1)
	v_mfma_f32_16x16x32_bf16 v[38:41], v[38:41], v[22:25], 0
	s_waitcnt lgkmcnt(0)
	v_mfma_f32_16x16x32_bf16 v[38:41], v[42:45], v[18:21], v[38:41]
	ds_read_b128 v[42:45], v100 offset:9216
	ds_read_b128 v[46:49], v100 offset:9280
	s_waitcnt lgkmcnt(1)
	v_mfma_f32_16x16x32_bf16 v[42:45], v[42:45], v[22:25], 0
	s_waitcnt lgkmcnt(0)
	v_mfma_f32_16x16x32_bf16 v[42:45], v[46:49], v[18:21], v[42:45]
	ds_read_b128 v[46:49], v100 offset:11520
	ds_read_b128 v[50:53], v100 offset:11584
	s_waitcnt lgkmcnt(1)
	v_mfma_f32_16x16x32_bf16 v[46:49], v[46:49], v[22:25], 0
	s_waitcnt lgkmcnt(0)
	v_mfma_f32_16x16x32_bf16 v[46:49], v[50:53], v[18:21], v[46:49]
	ds_read_b128 v[50:53], v100 offset:13824
	ds_read_b128 v[54:57], v100 offset:13888
	s_waitcnt lgkmcnt(1)
	v_mfma_f32_16x16x32_bf16 v[50:53], v[50:53], v[22:25], 0
	s_waitcnt lgkmcnt(0)
	v_mfma_f32_16x16x32_bf16 v[50:53], v[54:57], v[18:21], v[50:53]
	ds_read_b128 v[54:57], v100 offset:16128
	ds_read_b128 v[60:63], v100 offset:16192
	s_waitcnt lgkmcnt(1)
	v_mfma_f32_16x16x32_bf16 v[54:57], v[54:57], v[22:25], 0
	s_waitcnt lgkmcnt(0)
	v_mfma_f32_16x16x32_bf16 v[54:57], v[60:63], v[18:21], v[54:57]
	ds_read_b128 v[60:63], v100 offset:18432
	ds_read_b128 v[64:67], v100 offset:18496
	s_waitcnt lgkmcnt(1)
	v_mfma_f32_16x16x32_bf16 v[60:63], v[60:63], v[22:25], 0
	s_waitcnt lgkmcnt(0)
	v_mfma_f32_16x16x32_bf16 v[60:63], v[64:67], v[18:21], v[60:63]
	ds_read_b128 v[64:67], v100 offset:20736
	ds_read_b128 v[68:71], v100 offset:20800
	s_waitcnt lgkmcnt(1)
	v_mfma_f32_16x16x32_bf16 v[22:25], v[64:67], v[22:25], 0
	s_waitcnt lgkmcnt(0)
	v_mfma_f32_16x16x32_bf16 v[18:21], v[68:71], v[18:21], v[22:25]
	s_nop 5
	v_mul_f32_e32 v22, 0xbfb8aa3b, v72
	v_mul_f32_e32 v23, 0x3e38aa3b, v26
	v_mul_f32_e32 v24, 0x3e38aa3b, v27
	v_fmac_f32_e32 v23, v129, v22
	v_fmac_f32_e32 v24, v130, v22
	v_mul_f32_e32 v26, 0x3e38aa3b, v28
	v_mul_f32_e32 v27, 0x3e38aa3b, v29
	v_max3_f32 v25, v23, s75, v24
	v_fmac_f32_e32 v26, v131, v22
	v_fmac_f32_e32 v27, v132, v22
	v_mul_f32_e32 v28, 0x3e38aa3b, v30
	v_mul_f32_e32 v29, 0x3e38aa3b, v31
	v_max3_f32 v25, v25, v26, v27
	v_fmac_f32_e32 v28, v133, v22
	v_fmac_f32_e32 v29, v134, v22
	v_mul_f32_e32 v30, 0x3e38aa3b, v32
	v_mul_f32_e32 v31, 0x3e38aa3b, v33
	v_max3_f32 v25, v25, v28, v29
	v_fmac_f32_e32 v30, v135, v22
	v_fmac_f32_e32 v31, v136, v22
	v_mul_f32_e32 v32, 0x3e38aa3b, v34
	v_mul_f32_e32 v33, 0x3e38aa3b, v35
	v_max3_f32 v25, v25, v30, v31
	v_fmac_f32_e32 v32, v137, v22
	v_fmac_f32_e32 v33, v138, v22
	v_mul_f32_e32 v34, 0x3e38aa3b, v36
	v_mul_f32_e32 v36, 0x3e38aa3b, v37
	v_max3_f32 v25, v25, v32, v33
	v_fmac_f32_e32 v34, v139, v22
	v_fmac_f32_e32 v36, v140, v22
	v_mul_f32_e32 v37, 0x3e38aa3b, v38
	v_mul_f32_e32 v38, 0x3e38aa3b, v39
	v_max3_f32 v25, v25, v34, v36
	v_fmac_f32_e32 v37, v141, v22
	v_fmac_f32_e32 v38, v142, v22
	v_mul_f32_e32 v39, 0x3e38aa3b, v40
	v_mul_f32_e32 v40, 0x3e38aa3b, v41
	v_max3_f32 v25, v25, v37, v38
	v_fmac_f32_e32 v39, v143, v22
	v_fmac_f32_e32 v40, v144, v22
	v_mul_f32_e32 v41, 0x3e38aa3b, v42
	v_mul_f32_e32 v42, 0x3e38aa3b, v43
	v_max3_f32 v25, v25, v39, v40
	v_fmac_f32_e32 v41, v145, v22
	v_fmac_f32_e32 v42, v146, v22
	v_mul_f32_e32 v43, 0x3e38aa3b, v44
	v_mul_f32_e32 v44, 0x3e38aa3b, v45
	v_max3_f32 v25, v25, v41, v42
	v_fmac_f32_e32 v43, v147, v22
	v_fmac_f32_e32 v44, v148, v22
	v_mul_f32_e32 v45, 0x3e38aa3b, v46
	v_mul_f32_e32 v46, 0x3e38aa3b, v47
	v_max3_f32 v25, v25, v43, v44
	v_fmac_f32_e32 v45, v149, v22
	v_fmac_f32_e32 v46, v150, v22
	v_mul_f32_e32 v47, 0x3e38aa3b, v48
	v_mul_f32_e32 v48, 0x3e38aa3b, v49
	v_max3_f32 v25, v25, v45, v46
	v_fmac_f32_e32 v47, v151, v22
	v_fmac_f32_e32 v48, v152, v22
	v_mul_f32_e32 v49, 0x3e38aa3b, v50
	v_mul_f32_e32 v50, 0x3e38aa3b, v51
	v_max3_f32 v25, v25, v47, v48
	v_fmac_f32_e32 v49, v153, v22
	v_fmac_f32_e32 v50, v154, v22
	v_mul_f32_e32 v51, 0x3e38aa3b, v52
	v_mul_f32_e32 v52, 0x3e38aa3b, v53
	v_max3_f32 v25, v25, v49, v50
	v_fmac_f32_e32 v51, v155, v22
	v_fmac_f32_e32 v52, v156, v22
	v_mul_f32_e32 v53, 0x3e38aa3b, v54
	v_mul_f32_e32 v54, 0x3e38aa3b, v55
	v_max3_f32 v25, v25, v51, v52
	v_fmac_f32_e32 v53, v157, v22
	v_fmac_f32_e32 v54, v158, v22
	v_mul_f32_e32 v55, 0x3e38aa3b, v56
	v_mul_f32_e32 v56, 0x3e38aa3b, v57
	v_max3_f32 v25, v25, v53, v54
	v_fmac_f32_e32 v55, v159, v22
	v_fmac_f32_e32 v56, v160, v22
	v_mul_f32_e32 v57, 0x3e38aa3b, v60
	v_mul_f32_e32 v60, 0x3e38aa3b, v61
	v_max3_f32 v25, v25, v55, v56
	v_fmac_f32_e32 v57, v161, v22
	v_fmac_f32_e32 v60, v162, v22
	v_mul_f32_e32 v61, 0x3e38aa3b, v62
	v_mul_f32_e32 v62, 0x3e38aa3b, v63
	v_max3_f32 v25, v25, v57, v60
	v_fmac_f32_e32 v61, v163, v22
	v_fmac_f32_e32 v62, v164, v22
	v_mul_f32_e32 v18, 0x3e38aa3b, v18
	v_mul_f32_e32 v63, 0x3e38aa3b, v19
	v_max3_f32 v25, v25, v61, v62
	v_fmac_f32_e32 v18, v165, v22
	v_fmac_f32_e32 v63, v166, v22
	v_max3_f32 v19, v25, v18, v63
	v_mul_f32_e32 v25, 0x3e38aa3b, v20
	v_mul_f32_e32 v64, 0x3e38aa3b, v21
	v_fmac_f32_e32 v25, v167, v22
	v_fmac_f32_e32 v64, v168, v22
	v_max3_f32 v19, v19, v25, v64
	v_mov_b32_e32 v21, v19
	s_nop 1
	v_permlane16_swap_b32_e32 v21, v19
	v_mul_f32_e32 v20, s4, v249
	s_waitcnt lgkmcnt(0)
	v_max_f32_e32 v21, v21, v21
	v_max_f32_e32 v19, v19, v21
	v_mov_b32_e32 v21, v19
	s_nop 1
	v_permlane32_swap_b32_e32 v21, v19
	s_waitcnt lgkmcnt(0)
	v_max3_f32 v65, v19, v21, v20
	v_sub_f32_e32 v19, v23, v65
	v_exp_f32_e32 v66, v19
	v_sub_f32_e32 v20, v24, v65
	v_exp_f32_e32 v67, v20
	v_sub_f32_e32 v20, v26, v65
	v_exp_f32_e32 v68, v20
	v_sub_f32_e32 v20, v27, v65
	v_exp_f32_e32 v69, v20
	v_sub_f32_e32 v20, v28, v65
	v_add_f32_e32 v19, 0, v66
	v_exp_f32_e32 v70, v20
	v_sub_f32_e32 v20, v29, v65
	v_add_f32_e32 v19, v67, v19
	v_exp_f32_e32 v71, v20
	v_sub_f32_e32 v20, v30, v65
	v_add_f32_e32 v19, v68, v19
	v_exp_f32_e32 v72, v20
	v_sub_f32_e32 v20, v31, v65
	v_add_f32_e32 v19, v69, v19
	v_exp_f32_e32 v73, v20
	v_sub_f32_e32 v20, v32, v65
	v_add_f32_e32 v19, v70, v19
	v_exp_f32_e32 v35, v20
	v_sub_f32_e32 v20, v33, v65
	v_add_f32_e32 v19, v71, v19
	v_exp_f32_e32 v74, v20
	v_sub_f32_e32 v20, v34, v65
	v_add_f32_e32 v19, v72, v19
	v_exp_f32_e32 v75, v20
	v_sub_f32_e32 v20, v36, v65
	v_add_f32_e32 v19, v73, v19
	v_exp_f32_e32 v76, v20
	v_sub_f32_e32 v20, v37, v65
	v_add_f32_e32 v19, v35, v19
	v_exp_f32_e32 v77, v20
	v_sub_f32_e32 v20, v38, v65
	v_add_f32_e32 v19, v74, v19
	v_exp_f32_e32 v78, v20
	v_sub_f32_e32 v20, v39, v65
	v_add_f32_e32 v19, v75, v19
	v_exp_f32_e32 v39, v20
	v_sub_f32_e32 v20, v40, v65
	v_add_f32_e32 v19, v76, v19
	v_exp_f32_e32 v79, v20
	v_sub_f32_e32 v20, v41, v65
	v_add_f32_e32 v19, v77, v19
	v_exp_f32_e32 v30, v20
	v_sub_f32_e32 v20, v42, v65
	v_add_f32_e32 v19, v78, v19
	v_exp_f32_e32 v33, v20
	v_sub_f32_e32 v20, v43, v65
	v_add_f32_e32 v19, v39, v19
	v_exp_f32_e32 v34, v20
	v_sub_f32_e32 v20, v44, v65
	v_add_f32_e32 v19, v79, v19
	v_exp_f32_e32 v38, v20
	v_sub_f32_e32 v20, v45, v65
	v_add_f32_e32 v19, v30, v19
	v_exp_f32_e32 v80, v20
	v_sub_f32_e32 v20, v46, v65
	v_add_f32_e32 v19, v33, v19
	v_exp_f32_e32 v81, v20
	v_sub_f32_e32 v20, v47, v65
	v_add_f32_e32 v19, v34, v19
	v_exp_f32_e32 v82, v20
	v_sub_f32_e32 v20, v48, v65
	v_add_f32_e32 v19, v38, v19
	v_exp_f32_e32 v83, v20
	v_sub_f32_e32 v20, v49, v65
	v_add_f32_e32 v19, v80, v19
	v_exp_f32_e32 v27, v20
	v_sub_f32_e32 v20, v50, v65
	v_add_f32_e32 v19, v81, v19
	v_exp_f32_e32 v28, v20
	v_sub_f32_e32 v20, v51, v65
	v_add_f32_e32 v19, v82, v19
	v_exp_f32_e32 v29, v20
	v_sub_f32_e32 v20, v52, v65
	v_add_f32_e32 v19, v83, v19
	v_exp_f32_e32 v31, v20
	v_sub_f32_e32 v20, v53, v65
	v_add_f32_e32 v19, v27, v19
	v_exp_f32_e32 v32, v20
	v_sub_f32_e32 v20, v54, v65
	v_add_f32_e32 v19, v28, v19
	v_exp_f32_e32 v36, v20
	v_sub_f32_e32 v20, v55, v65
	v_add_f32_e32 v19, v29, v19
	v_exp_f32_e32 v37, v20
	v_sub_f32_e32 v20, v56, v65
	v_add_f32_e32 v19, v31, v19
	v_exp_f32_e32 v56, v20
	v_add_f32_e32 v19, v32, v19
	v_add_f32_e32 v19, v36, v19
	v_add_f32_e32 v19, v37, v19
	v_add_f32_e32 v20, v56, v19
	v_sub_f32_e32 v19, v57, v65
	v_exp_f32_e32 v19, v19
	v_sub_f32_e32 v18, v18, v65
	v_sub_f32_e32 v25, v25, v65
	v_exp_f32_e32 v25, v25
	v_add_f32_e32 v21, v19, v20
	v_sub_f32_e32 v20, v60, v65
	v_exp_f32_e32 v20, v20
	v_sub_f32_e32 v26, v64, v65
	v_exp_f32_e32 v26, v26
	v_add_f32_e32 v22, v20, v21
	v_sub_f32_e32 v21, v61, v65
	v_exp_f32_e32 v21, v21
	s_nop 0
	v_add_f32_e32 v23, v21, v22
	v_sub_f32_e32 v22, v62, v65
	v_exp_f32_e32 v22, v22
	s_nop 0
	v_add_f32_e32 v24, v22, v23
	v_exp_f32_e32 v23, v18
	s_nop 0
	v_add_f32_e32 v18, v23, v24
	v_sub_f32_e32 v24, v63, v65
	v_exp_f32_e32 v24, v24
	s_nop 0
	v_add_f32_e32 v18, v24, v18
	v_add_f32_e32 v18, v25, v18
	v_add_f32_e32 v18, v26, v18
	v_mov_b32_e32 v40, v18
	s_nop 1
	v_permlane16_swap_b32_e32 v40, v18
	s_waitcnt lgkmcnt(0)
	v_add_f32_e32 v18, v18, v40
	v_mov_b32_e32 v40, v18
	s_nop 1
	v_permlane32_swap_b32_e32 v40, v18
	s_waitcnt lgkmcnt(0)
	v_add_f32_e32 v18, v18, v40
	v_fma_f32 v40, s4, v249, -v65
	v_exp_f32_e32 v40, v40
	s_nop 0
	v_add_f32_e32 v18, v40, v18
	v_cvt_pk_bf16_f32 v40, v66, v67
	v_cvt_pk_bf16_f32 v41, v68, v69
	v_cvt_pk_bf16_f32 v42, v70, v71
	v_cvt_pk_bf16_f32 v43, v72, v73
	ds_read_b64_tr_b16 v[46:47], v98 offset:39168
	ds_read_b64_tr_b16 v[44:45], v98 offset:36864
	ds_read_b64_tr_b16 v[48:49], v98 offset:36896
	ds_read_b64_tr_b16 v[50:51], v98 offset:39200
	ds_read_b64_tr_b16 v[52:53], v98 offset:36928
	ds_read_b64_tr_b16 v[54:55], v98 offset:39232
	ds_read_b64_tr_b16 v[60:61], v98 offset:36960
	ds_read_b64_tr_b16 v[62:63], v98 offset:39264
	s_waitcnt lgkmcnt(6)
	v_mfma_f32_16x16x32_bf16 v[44:47], v[44:47], v[40:43], 0
	s_waitcnt lgkmcnt(4)
	v_mfma_f32_16x16x32_bf16 v[48:51], v[48:51], v[40:43], 0
	s_waitcnt lgkmcnt(2)
	v_mfma_f32_16x16x32_bf16 v[52:55], v[52:55], v[40:43], 0
	s_waitcnt lgkmcnt(0)
	v_mfma_f32_16x16x32_bf16 v[40:43], v[60:63], v[40:43], 0
	v_cvt_pk_bf16_f32 v60, v35, v74
	v_cvt_pk_bf16_f32 v61, v75, v76
	v_cvt_pk_bf16_f32 v62, v77, v78
	v_cvt_pk_bf16_f32 v63, v39, v79
	ds_read_b64_tr_b16 v[66:67], v98 offset:43776
	ds_read_b64_tr_b16 v[64:65], v98 offset:41472
	ds_read_b64_tr_b16 v[68:69], v98 offset:41504
	s_waitcnt lgkmcnt(1)
	v_mfma_f32_16x16x32_bf16 v[44:47], v[64:67], v[60:63], v[44:47]
	ds_read_b64_tr_b16 v[70:71], v98 offset:43808
	ds_read_b64_tr_b16 v[64:65], v98 offset:41536
	ds_read_b64_tr_b16 v[66:67], v98 offset:43840
	s_waitcnt lgkmcnt(0)
	v_mfma_f32_16x16x32_bf16 v[52:55], v[64:67], v[60:63], v[52:55]
	ds_read_b64_tr_b16 v[64:65], v98 offset:41568
	ds_read_b64_tr_b16 v[66:67], v98 offset:43872
	v_mfma_f32_16x16x32_bf16 v[48:51], v[68:71], v[60:63], v[48:51]
	s_waitcnt lgkmcnt(0)
	v_mfma_f32_16x16x32_bf16 v[40:43], v[64:67], v[60:63], v[40:43]
	v_cvt_pk_bf16_f32 v60, v30, v33
	v_cvt_pk_bf16_f32 v61, v34, v38
	v_cvt_pk_bf16_f32 v62, v80, v81
	v_cvt_pk_bf16_f32 v63, v82, v83
	ds_read_b64_tr_b16 v[66:67], v98 offset:48384
	ds_read_b64_tr_b16 v[64:65], v98 offset:46080
	ds_read_b64_tr_b16 v[68:69], v98 offset:46112
	s_waitcnt lgkmcnt(1)
	v_mfma_f32_16x16x32_bf16 v[44:47], v[64:67], v[60:63], v[44:47]
	ds_read_b64_tr_b16 v[70:71], v98 offset:48416
	ds_read_b64_tr_b16 v[64:65], v98 offset:46144
	ds_read_b64_tr_b16 v[66:67], v98 offset:48448
	s_waitcnt lgkmcnt(0)
	v_mfma_f32_16x16x32_bf16 v[52:55], v[64:67], v[60:63], v[52:55]
	ds_read_b64_tr_b16 v[64:65], v98 offset:46176
	ds_read_b64_tr_b16 v[66:67], v98 offset:48480
	v_cvt_pk_bf16_f32 v28, v27, v28
	v_cvt_pk_bf16_f32 v29, v29, v31
	s_waitcnt lgkmcnt(0)
	v_mfma_f32_16x16x32_bf16 v[38:41], v[64:67], v[60:63], v[40:43]
	v_cvt_pk_bf16_f32 v30, v32, v36
	v_cvt_pk_bf16_f32 v31, v37, v56
	ds_read_b64_tr_b16 v[34:35], v98 offset:52992
	ds_read_b64_tr_b16 v[32:33], v98 offset:50688
	s_nop 0
	ds_read_b64_tr_b16 v[42:43], v98 offset:50720
	s_waitcnt lgkmcnt(1)
	v_mfma_f32_16x16x32_bf16 v[32:35], v[32:35], v[28:31], v[44:47]
	s_nop 2
	ds_read_b64_tr_b16 v[44:45], v98 offset:53024
	v_mfma_f32_16x16x32_bf16 v[48:51], v[68:71], v[60:63], v[48:51]
	s_waitcnt lgkmcnt(0)
	v_mfma_f32_16x16x32_bf16 v[42:45], v[42:45], v[28:31], v[48:51]
	ds_read_b64_tr_b16 v[46:47], v98 offset:50752
	s_nop 4
	ds_read_b64_tr_b16 v[48:49], v98 offset:53056
	s_waitcnt lgkmcnt(0)
	v_mfma_f32_16x16x32_bf16 v[46:49], v[46:49], v[28:31], v[52:55]
	ds_read_b64_tr_b16 v[50:51], v98 offset:50784
	s_nop 1
	ds_read_b64_tr_b16 v[52:53], v98 offset:53088
	v_cvt_pk_bf16_f32 v20, v19, v20
	v_cvt_pk_bf16_f32 v21, v21, v22
	s_waitcnt lgkmcnt(0)
	v_mfma_f32_16x16x32_bf16 v[28:31], v[50:53], v[28:31], v[38:41]
	v_cvt_pk_bf16_f32 v22, v23, v24
	v_cvt_pk_bf16_f32 v23, v25, v26
	ds_read_b64_tr_b16 v[26:27], v98 offset:57600
	ds_read_b64_tr_b16 v[24:25], v98 offset:55296
	ds_read_b64_tr_b16 v[36:37], v98 offset:55328
	ds_read_b64_tr_b16 v[38:39], v98 offset:57632
	s_waitcnt lgkmcnt(2)
	v_mfma_f32_16x16x32_bf16 v[24:27], v[24:27], v[20:23], v[32:35]
	v_div_scale_f32 v19, s[4:5], v18, v18, 1.0
	s_or_b32 s4, s17, 7
	s_waitcnt lgkmcnt(0)
	v_mfma_f32_16x16x32_bf16 v[32:35], v[36:39], v[20:23], v[42:45]
	ds_read_b64_tr_b16 v[36:37], v98 offset:55360
	ds_read_b64_tr_b16 v[38:39], v98 offset:57664
	ds_read_b64_tr_b16 v[40:41], v98 offset:55392
	ds_read_b64_tr_b16 v[42:43], v98 offset:57696
	s_add_i32 s17, s17, 8
	s_waitcnt lgkmcnt(2)
	v_mfma_f32_16x16x32_bf16 v[36:39], v[36:39], v[20:23], v[46:49]
	s_cmpk_gt_i32 s9, 0xff
	s_waitcnt lgkmcnt(0)
	v_mfma_f32_16x16x32_bf16 v[20:23], v[40:43], v[20:23], v[28:31]
	s_nop 2
	v_rcp_f32_e32 v28, v19
	s_nop 0
	v_fma_f32 v29, -v19, v28, 1.0
	v_fmac_f32_e32 v28, v29, v28
	v_div_scale_f32 v29, vcc, 1.0, v18, 1.0
	v_mul_f32_e32 v30, v29, v28
	v_fma_f32 v31, -v19, v30, v29
	v_fmac_f32_e32 v30, v31, v28
	v_fma_f32 v19, -v19, v30, v29
	v_div_fmas_f32 v19, v19, v28, v30
	v_div_fixup_f32 v18, v19, v18, 1.0
	v_pk_mul_f32 v[26:27], v[18:19], v[26:27] op_sel_hi:[0,1]
	v_pk_mul_f32 v[24:25], v[18:19], v[24:25] op_sel_hi:[0,1]
	v_pk_mul_f32 v[28:29], v[18:19], v[34:35] op_sel_hi:[0,1]
	v_pk_mul_f32 v[30:31], v[18:19], v[32:33] op_sel_hi:[0,1]
	v_cvt_pk_bf16_f32 v24, v24, v25
	v_cvt_pk_bf16_f32 v25, v26, v27
	v_cvt_pk_bf16_f32 v26, v30, v31
	v_cvt_pk_bf16_f32 v27, v28, v29
	global_store_dwordx4 v[58:59], v[24:27], off offset:640
	v_pk_mul_f32 v[22:23], v[18:19], v[22:23] op_sel_hi:[0,1]
	v_pk_mul_f32 v[20:21], v[18:19], v[20:21] op_sel_hi:[0,1]
	v_pk_mul_f32 v[24:25], v[18:19], v[38:39] op_sel_hi:[0,1]
	v_pk_mul_f32 v[26:27], v[18:19], v[36:37] op_sel_hi:[0,1]
	v_cvt_pk_bf16_f32 v18, v26, v27
	v_cvt_pk_bf16_f32 v19, v24, v25
	v_cvt_pk_bf16_f32 v20, v20, v21
	v_cvt_pk_bf16_f32 v21, v22, v23
	global_store_dwordx4 v[58:59], v[18:21], off offset:704
	s_nop 1
	v_cvt_f32_ubyte0_e32 v18, s4
	v_mul_f32_e32 v18, -0.5, v18
	v_exp_f32_e32 v64, v18
	ds_read_b128 v[18:21], v100
	ds_read_b128 v[22:25], v100 offset:64
	s_waitcnt vmcnt(15) lgkmcnt(1)
	v_mfma_f32_16x16x32_bf16 v[18:21], v[18:21], v[14:17], 0
	v_readlane_b32 s4, v128, 6
	s_waitcnt vmcnt(14) lgkmcnt(0)
	v_mfma_f32_16x16x32_bf16 v[18:21], v[22:25], v[10:13], v[18:21]
	ds_read_b128 v[22:25], v100 offset:2304
	ds_read_b128 v[26:29], v100 offset:2368
	s_waitcnt lgkmcnt(1)
	v_mfma_f32_16x16x32_bf16 v[22:25], v[22:25], v[14:17], 0
	s_waitcnt lgkmcnt(0)
	v_mfma_f32_16x16x32_bf16 v[22:25], v[26:29], v[10:13], v[22:25]
	ds_read_b128 v[26:29], v100 offset:4608
	ds_read_b128 v[30:33], v100 offset:4672
	s_waitcnt lgkmcnt(1)
	v_mfma_f32_16x16x32_bf16 v[26:29], v[26:29], v[14:17], 0
	s_waitcnt lgkmcnt(0)
	v_mfma_f32_16x16x32_bf16 v[26:29], v[30:33], v[10:13], v[26:29]
	ds_read_b128 v[30:33], v100 offset:6912
	ds_read_b128 v[34:37], v100 offset:6976
	s_waitcnt lgkmcnt(1)
	v_mfma_f32_16x16x32_bf16 v[30:33], v[30:33], v[14:17], 0
	s_waitcnt lgkmcnt(0)
	v_mfma_f32_16x16x32_bf16 v[30:33], v[34:37], v[10:13], v[30:33]
	ds_read_b128 v[34:37], v100 offset:9216
	ds_read_b128 v[38:41], v100 offset:9280
	s_waitcnt lgkmcnt(1)
	v_mfma_f32_16x16x32_bf16 v[34:37], v[34:37], v[14:17], 0
	s_waitcnt lgkmcnt(0)
	v_mfma_f32_16x16x32_bf16 v[34:37], v[38:41], v[10:13], v[34:37]
	ds_read_b128 v[38:41], v100 offset:11520
	ds_read_b128 v[42:45], v100 offset:11584
	s_waitcnt lgkmcnt(1)
	v_mfma_f32_16x16x32_bf16 v[38:41], v[38:41], v[14:17], 0
	s_waitcnt lgkmcnt(0)
	v_mfma_f32_16x16x32_bf16 v[38:41], v[42:45], v[10:13], v[38:41]
	ds_read_b128 v[42:45], v100 offset:13824
	ds_read_b128 v[46:49], v100 offset:13888
	s_waitcnt lgkmcnt(1)
	v_mfma_f32_16x16x32_bf16 v[42:45], v[42:45], v[14:17], 0
	s_waitcnt lgkmcnt(0)
	v_mfma_f32_16x16x32_bf16 v[42:45], v[46:49], v[10:13], v[42:45]
	ds_read_b128 v[46:49], v100 offset:16128
	ds_read_b128 v[50:53], v100 offset:16192
	s_waitcnt lgkmcnt(1)
	v_mfma_f32_16x16x32_bf16 v[46:49], v[46:49], v[14:17], 0
	s_waitcnt lgkmcnt(0)
	v_mfma_f32_16x16x32_bf16 v[46:49], v[50:53], v[10:13], v[46:49]
	ds_read_b128 v[50:53], v100 offset:18432
	ds_read_b128 v[54:57], v100 offset:18496
	s_waitcnt lgkmcnt(1)
	v_mfma_f32_16x16x32_bf16 v[50:53], v[50:53], v[14:17], 0
	s_waitcnt lgkmcnt(0)
	v_mfma_f32_16x16x32_bf16 v[50:53], v[54:57], v[10:13], v[50:53]
	ds_read_b128 v[54:57], v100 offset:20736
	ds_read_b128 v[60:63], v100 offset:20800
	s_waitcnt lgkmcnt(1)
	v_mfma_f32_16x16x32_bf16 v[14:17], v[54:57], v[14:17], 0
	s_waitcnt lgkmcnt(0)
	v_mfma_f32_16x16x32_bf16 v[10:13], v[60:63], v[10:13], v[14:17]
	s_nop 5
	v_mul_f32_e32 v14, 0xbfb8aa3b, v64
	v_mul_f32_e32 v15, 0x3e38aa3b, v18
	v_mul_f32_e32 v16, 0x3e38aa3b, v19
	v_fmac_f32_e32 v15, v129, v14
	v_fmac_f32_e32 v16, v130, v14
	v_mul_f32_e32 v18, 0x3e38aa3b, v20
	v_mul_f32_e32 v19, 0x3e38aa3b, v21
	v_max3_f32 v17, v15, s75, v16
	v_fmac_f32_e32 v18, v131, v14
	v_fmac_f32_e32 v19, v132, v14
	v_mul_f32_e32 v20, 0x3e38aa3b, v22
	v_mul_f32_e32 v21, 0x3e38aa3b, v23
	v_max3_f32 v17, v17, v18, v19
	v_fmac_f32_e32 v20, v133, v14
	v_fmac_f32_e32 v21, v134, v14
	v_mul_f32_e32 v22, 0x3e38aa3b, v24
	v_mul_f32_e32 v23, 0x3e38aa3b, v25
	v_max3_f32 v17, v17, v20, v21
	v_fmac_f32_e32 v22, v135, v14
	v_fmac_f32_e32 v23, v136, v14
	v_mul_f32_e32 v24, 0x3e38aa3b, v26
	v_mul_f32_e32 v25, 0x3e38aa3b, v27
	v_max3_f32 v17, v17, v22, v23
	v_fmac_f32_e32 v24, v137, v14
	v_fmac_f32_e32 v25, v138, v14
	v_mul_f32_e32 v26, 0x3e38aa3b, v28
	v_mul_f32_e32 v28, 0x3e38aa3b, v29
	v_max3_f32 v17, v17, v24, v25
	v_fmac_f32_e32 v26, v139, v14
	v_fmac_f32_e32 v28, v140, v14
	v_mul_f32_e32 v29, 0x3e38aa3b, v30
	v_mul_f32_e32 v30, 0x3e38aa3b, v31
	v_max3_f32 v17, v17, v26, v28
	v_fmac_f32_e32 v29, v141, v14
	v_fmac_f32_e32 v30, v142, v14
	v_mul_f32_e32 v31, 0x3e38aa3b, v32
	v_mul_f32_e32 v32, 0x3e38aa3b, v33
	v_max3_f32 v17, v17, v29, v30
	v_fmac_f32_e32 v31, v143, v14
	v_fmac_f32_e32 v32, v144, v14
	v_mul_f32_e32 v33, 0x3e38aa3b, v34
	v_mul_f32_e32 v34, 0x3e38aa3b, v35
	v_max3_f32 v17, v17, v31, v32
	v_fmac_f32_e32 v33, v145, v14
	v_fmac_f32_e32 v34, v146, v14
	v_mul_f32_e32 v35, 0x3e38aa3b, v36
	v_mul_f32_e32 v36, 0x3e38aa3b, v37
	v_max3_f32 v17, v17, v33, v34
	v_fmac_f32_e32 v35, v147, v14
	v_fmac_f32_e32 v36, v148, v14
	v_mul_f32_e32 v37, 0x3e38aa3b, v38
	v_mul_f32_e32 v38, 0x3e38aa3b, v39
	v_max3_f32 v17, v17, v35, v36
	v_fmac_f32_e32 v37, v149, v14
	v_fmac_f32_e32 v38, v150, v14
	v_mul_f32_e32 v39, 0x3e38aa3b, v40
	v_mul_f32_e32 v40, 0x3e38aa3b, v41
	v_max3_f32 v17, v17, v37, v38
	v_fmac_f32_e32 v39, v151, v14
	v_fmac_f32_e32 v40, v152, v14
	v_mul_f32_e32 v41, 0x3e38aa3b, v42
	v_mul_f32_e32 v42, 0x3e38aa3b, v43
	v_max3_f32 v17, v17, v39, v40
	v_fmac_f32_e32 v41, v153, v14
	v_fmac_f32_e32 v42, v154, v14
	v_mul_f32_e32 v43, 0x3e38aa3b, v44
	v_mul_f32_e32 v44, 0x3e38aa3b, v45
	v_max3_f32 v17, v17, v41, v42
	v_fmac_f32_e32 v43, v155, v14
	v_fmac_f32_e32 v44, v156, v14
	v_mul_f32_e32 v45, 0x3e38aa3b, v46
	v_mul_f32_e32 v46, 0x3e38aa3b, v47
	v_max3_f32 v17, v17, v43, v44
	v_fmac_f32_e32 v45, v157, v14
	v_fmac_f32_e32 v46, v158, v14
	v_mul_f32_e32 v47, 0x3e38aa3b, v48
	v_mul_f32_e32 v48, 0x3e38aa3b, v49
	v_max3_f32 v17, v17, v45, v46
	v_fmac_f32_e32 v47, v159, v14
	v_fmac_f32_e32 v48, v160, v14
	v_mul_f32_e32 v49, 0x3e38aa3b, v50
	v_mul_f32_e32 v50, 0x3e38aa3b, v51
	v_max3_f32 v17, v17, v47, v48
	v_fmac_f32_e32 v49, v161, v14
	v_fmac_f32_e32 v50, v162, v14
	v_mul_f32_e32 v51, 0x3e38aa3b, v52
	v_mul_f32_e32 v52, 0x3e38aa3b, v53
	v_max3_f32 v17, v17, v49, v50
	v_fmac_f32_e32 v51, v163, v14
	v_fmac_f32_e32 v52, v164, v14
	v_mul_f32_e32 v10, 0x3e38aa3b, v10
	v_mul_f32_e32 v53, 0x3e38aa3b, v11
	v_max3_f32 v17, v17, v51, v52
	v_fmac_f32_e32 v10, v165, v14
	v_fmac_f32_e32 v53, v166, v14
	v_max3_f32 v11, v17, v10, v53
	v_mul_f32_e32 v17, 0x3e38aa3b, v12
	v_mul_f32_e32 v54, 0x3e38aa3b, v13
	v_fmac_f32_e32 v17, v167, v14
	v_fmac_f32_e32 v54, v168, v14
	v_max3_f32 v11, v11, v17, v54
	v_mov_b32_e32 v13, v11
	s_nop 1
	v_permlane16_swap_b32_e32 v13, v11
	v_mul_f32_e32 v12, s4, v249
	s_waitcnt lgkmcnt(0)
	v_max_f32_e32 v13, v13, v13
	v_max_f32_e32 v11, v11, v13
	v_mov_b32_e32 v13, v11
	s_nop 1
	v_permlane32_swap_b32_e32 v13, v11
	s_waitcnt lgkmcnt(0)
	v_max3_f32 v55, v11, v13, v12
	v_sub_f32_e32 v11, v15, v55
	v_exp_f32_e32 v56, v11
	v_sub_f32_e32 v12, v16, v55
	v_exp_f32_e32 v57, v12
	v_sub_f32_e32 v12, v18, v55
	v_exp_f32_e32 v60, v12
	v_sub_f32_e32 v12, v19, v55
	v_exp_f32_e32 v61, v12
	v_sub_f32_e32 v12, v20, v55
	v_add_f32_e32 v11, 0, v56
	v_exp_f32_e32 v62, v12
	v_sub_f32_e32 v12, v21, v55
	v_add_f32_e32 v11, v57, v11
	v_exp_f32_e32 v63, v12
	v_sub_f32_e32 v12, v22, v55
	v_add_f32_e32 v11, v60, v11
	v_exp_f32_e32 v64, v12
	v_sub_f32_e32 v12, v23, v55
	v_add_f32_e32 v11, v61, v11
	v_exp_f32_e32 v65, v12
	v_sub_f32_e32 v12, v24, v55
	v_add_f32_e32 v11, v62, v11
	v_exp_f32_e32 v27, v12
	v_sub_f32_e32 v12, v25, v55
	v_add_f32_e32 v11, v63, v11
	v_exp_f32_e32 v66, v12
	v_sub_f32_e32 v12, v26, v55
	v_add_f32_e32 v11, v64, v11
	v_exp_f32_e32 v67, v12
	v_sub_f32_e32 v12, v28, v55
	v_add_f32_e32 v11, v65, v11
	v_exp_f32_e32 v68, v12
	v_sub_f32_e32 v12, v29, v55
	v_add_f32_e32 v11, v27, v11
	v_exp_f32_e32 v69, v12
	v_sub_f32_e32 v12, v30, v55
	v_add_f32_e32 v11, v66, v11
	v_exp_f32_e32 v70, v12
	v_sub_f32_e32 v12, v31, v55
	v_add_f32_e32 v11, v67, v11
	v_exp_f32_e32 v31, v12
	v_sub_f32_e32 v12, v32, v55
	v_add_f32_e32 v11, v68, v11
	v_exp_f32_e32 v71, v12
	v_sub_f32_e32 v12, v33, v55
	v_add_f32_e32 v11, v69, v11
	v_exp_f32_e32 v22, v12
	v_sub_f32_e32 v12, v34, v55
	v_add_f32_e32 v11, v70, v11
	v_exp_f32_e32 v25, v12
	v_sub_f32_e32 v12, v35, v55
	v_add_f32_e32 v11, v31, v11
	v_exp_f32_e32 v26, v12
	v_sub_f32_e32 v12, v36, v55
	v_add_f32_e32 v11, v71, v11
	v_exp_f32_e32 v30, v12
	v_sub_f32_e32 v12, v37, v55
	v_add_f32_e32 v11, v22, v11
	v_exp_f32_e32 v72, v12
	v_sub_f32_e32 v12, v38, v55
	v_add_f32_e32 v11, v25, v11
	v_exp_f32_e32 v73, v12
	v_sub_f32_e32 v12, v39, v55
	v_add_f32_e32 v11, v26, v11
	v_exp_f32_e32 v74, v12
	v_sub_f32_e32 v12, v40, v55
	v_add_f32_e32 v11, v30, v11
	v_exp_f32_e32 v75, v12
	v_sub_f32_e32 v12, v41, v55
	v_add_f32_e32 v11, v72, v11
	v_exp_f32_e32 v19, v12
	v_sub_f32_e32 v12, v42, v55
	v_add_f32_e32 v11, v73, v11
	v_exp_f32_e32 v20, v12
	v_sub_f32_e32 v12, v43, v55
	v_add_f32_e32 v11, v74, v11
	v_exp_f32_e32 v21, v12
	v_sub_f32_e32 v12, v44, v55
	v_add_f32_e32 v11, v75, v11
	v_exp_f32_e32 v23, v12
	v_sub_f32_e32 v12, v45, v55
	v_add_f32_e32 v11, v19, v11
	v_exp_f32_e32 v24, v12
	v_sub_f32_e32 v12, v46, v55
	v_add_f32_e32 v11, v20, v11
	v_exp_f32_e32 v28, v12
	v_sub_f32_e32 v12, v47, v55
	v_add_f32_e32 v11, v21, v11
	v_exp_f32_e32 v29, v12
	v_sub_f32_e32 v12, v48, v55
	v_add_f32_e32 v11, v23, v11
	v_exp_f32_e32 v76, v12
	v_add_f32_e32 v11, v24, v11
	v_add_f32_e32 v11, v28, v11
	v_add_f32_e32 v11, v29, v11
	v_add_f32_e32 v12, v76, v11
	v_sub_f32_e32 v11, v49, v55
	v_exp_f32_e32 v11, v11
	v_sub_f32_e32 v10, v10, v55
	v_sub_f32_e32 v17, v17, v55
	v_exp_f32_e32 v17, v17
	v_add_f32_e32 v13, v11, v12
	v_sub_f32_e32 v12, v50, v55
	v_exp_f32_e32 v12, v12
	v_sub_f32_e32 v18, v54, v55
	v_exp_f32_e32 v18, v18
	v_add_f32_e32 v14, v12, v13
	v_sub_f32_e32 v13, v51, v55
	v_exp_f32_e32 v13, v13
	s_nop 0
	v_add_f32_e32 v15, v13, v14
	v_sub_f32_e32 v14, v52, v55
	v_exp_f32_e32 v14, v14
	s_nop 0
	v_add_f32_e32 v16, v14, v15
	v_exp_f32_e32 v15, v10
	s_nop 0
	v_add_f32_e32 v10, v15, v16
	v_sub_f32_e32 v16, v53, v55
	v_exp_f32_e32 v16, v16
	s_nop 0
	v_add_f32_e32 v10, v16, v10
	v_add_f32_e32 v10, v17, v10
	v_add_f32_e32 v10, v18, v10
	v_mov_b32_e32 v32, v10
	s_nop 1
	v_permlane16_swap_b32_e32 v32, v10
	s_waitcnt lgkmcnt(0)
	v_add_f32_e32 v10, v10, v32
	v_mov_b32_e32 v32, v10
	s_nop 1
	v_permlane32_swap_b32_e32 v32, v10
	s_waitcnt lgkmcnt(0)
	v_add_f32_e32 v10, v10, v32
	v_fma_f32 v32, s4, v249, -v55
	v_exp_f32_e32 v32, v32
	s_nop 0
	v_add_f32_e32 v10, v32, v10
	v_cvt_pk_bf16_f32 v32, v56, v57
	v_cvt_pk_bf16_f32 v33, v60, v61
	v_cvt_pk_bf16_f32 v34, v62, v63
	v_cvt_pk_bf16_f32 v35, v64, v65
	ds_read_b64_tr_b16 v[38:39], v98 offset:39168
	ds_read_b64_tr_b16 v[36:37], v98 offset:36864
	ds_read_b64_tr_b16 v[40:41], v98 offset:36896
	ds_read_b64_tr_b16 v[42:43], v98 offset:39200
	ds_read_b64_tr_b16 v[44:45], v98 offset:36928
	ds_read_b64_tr_b16 v[46:47], v98 offset:39232
	ds_read_b64_tr_b16 v[48:49], v98 offset:36960
	ds_read_b64_tr_b16 v[50:51], v98 offset:39264
	s_waitcnt lgkmcnt(6)
	v_mfma_f32_16x16x32_bf16 v[36:39], v[36:39], v[32:35], 0
	s_waitcnt lgkmcnt(4)
	v_mfma_f32_16x16x32_bf16 v[40:43], v[40:43], v[32:35], 0
	s_waitcnt lgkmcnt(2)
	v_mfma_f32_16x16x32_bf16 v[44:47], v[44:47], v[32:35], 0
	s_waitcnt lgkmcnt(0)
	v_mfma_f32_16x16x32_bf16 v[32:35], v[48:51], v[32:35], 0
	v_cvt_pk_bf16_f32 v48, v27, v66
	v_cvt_pk_bf16_f32 v49, v67, v68
	v_cvt_pk_bf16_f32 v50, v69, v70
	v_cvt_pk_bf16_f32 v51, v31, v71
	ds_read_b64_tr_b16 v[54:55], v98 offset:43776
	ds_read_b64_tr_b16 v[52:53], v98 offset:41472
	ds_read_b64_tr_b16 v[60:61], v98 offset:41504
	s_waitcnt lgkmcnt(1)
	v_mfma_f32_16x16x32_bf16 v[36:39], v[52:55], v[48:51], v[36:39]
	ds_read_b64_tr_b16 v[62:63], v98 offset:43808
	ds_read_b64_tr_b16 v[52:53], v98 offset:41536
	ds_read_b64_tr_b16 v[54:55], v98 offset:43840
	s_waitcnt lgkmcnt(0)
	v_mfma_f32_16x16x32_bf16 v[44:47], v[52:55], v[48:51], v[44:47]
	ds_read_b64_tr_b16 v[52:53], v98 offset:41568
	ds_read_b64_tr_b16 v[54:55], v98 offset:43872
	v_mfma_f32_16x16x32_bf16 v[40:43], v[60:63], v[48:51], v[40:43]
	s_waitcnt lgkmcnt(0)
	v_mfma_f32_16x16x32_bf16 v[32:35], v[52:55], v[48:51], v[32:35]
	v_cvt_pk_bf16_f32 v48, v22, v25
	v_cvt_pk_bf16_f32 v49, v26, v30
	v_cvt_pk_bf16_f32 v50, v72, v73
	v_cvt_pk_bf16_f32 v51, v74, v75
	ds_read_b64_tr_b16 v[54:55], v98 offset:48384
	ds_read_b64_tr_b16 v[52:53], v98 offset:46080
	ds_read_b64_tr_b16 v[60:61], v98 offset:46112
	s_waitcnt lgkmcnt(1)
	v_mfma_f32_16x16x32_bf16 v[36:39], v[52:55], v[48:51], v[36:39]
	ds_read_b64_tr_b16 v[62:63], v98 offset:48416
	ds_read_b64_tr_b16 v[52:53], v98 offset:46144
	ds_read_b64_tr_b16 v[54:55], v98 offset:48448
	s_waitcnt lgkmcnt(0)
	v_mfma_f32_16x16x32_bf16 v[44:47], v[52:55], v[48:51], v[44:47]
	ds_read_b64_tr_b16 v[52:53], v98 offset:46176
	ds_read_b64_tr_b16 v[54:55], v98 offset:48480
	v_cvt_pk_bf16_f32 v20, v19, v20
	v_cvt_pk_bf16_f32 v21, v21, v23
	s_waitcnt lgkmcnt(0)
	v_mfma_f32_16x16x32_bf16 v[30:33], v[52:55], v[48:51], v[32:35]
	v_cvt_pk_bf16_f32 v22, v24, v28
	v_cvt_pk_bf16_f32 v23, v29, v76
	ds_read_b64_tr_b16 v[26:27], v98 offset:52992
	ds_read_b64_tr_b16 v[24:25], v98 offset:50688
	s_nop 0
	ds_read_b64_tr_b16 v[34:35], v98 offset:50720
	s_waitcnt lgkmcnt(1)
	v_mfma_f32_16x16x32_bf16 v[24:27], v[24:27], v[20:23], v[36:39]
	s_nop 2
	ds_read_b64_tr_b16 v[36:37], v98 offset:53024
	v_mfma_f32_16x16x32_bf16 v[40:43], v[60:63], v[48:51], v[40:43]
	s_waitcnt lgkmcnt(0)
	v_mfma_f32_16x16x32_bf16 v[34:37], v[34:37], v[20:23], v[40:43]
	ds_read_b64_tr_b16 v[38:39], v98 offset:50752
	s_nop 4
	ds_read_b64_tr_b16 v[40:41], v98 offset:53056
	s_waitcnt lgkmcnt(0)
	v_mfma_f32_16x16x32_bf16 v[38:41], v[38:41], v[20:23], v[44:47]
	ds_read_b64_tr_b16 v[42:43], v98 offset:50784
	s_nop 1
	ds_read_b64_tr_b16 v[44:45], v98 offset:53088
	v_cvt_pk_bf16_f32 v12, v11, v12
	v_cvt_pk_bf16_f32 v13, v13, v14
	s_waitcnt lgkmcnt(0)
	v_mfma_f32_16x16x32_bf16 v[20:23], v[42:45], v[20:23], v[30:33]
	v_cvt_pk_bf16_f32 v14, v15, v16
	v_cvt_pk_bf16_f32 v15, v17, v18
	ds_read_b64_tr_b16 v[18:19], v98 offset:57600
	ds_read_b64_tr_b16 v[16:17], v98 offset:55296
	ds_read_b64_tr_b16 v[28:29], v98 offset:55328
	ds_read_b64_tr_b16 v[30:31], v98 offset:57632
	s_waitcnt lgkmcnt(2)
	v_mfma_f32_16x16x32_bf16 v[16:19], v[16:19], v[12:15], v[24:27]
	v_div_scale_f32 v11, s[4:5], v10, v10, 1.0
	v_readlane_b32 s4, v128, 7
	s_waitcnt lgkmcnt(0)
	v_mfma_f32_16x16x32_bf16 v[24:27], v[28:31], v[12:15], v[34:37]
	ds_read_b64_tr_b16 v[28:29], v98 offset:55360
	ds_read_b64_tr_b16 v[30:31], v98 offset:57664
	ds_read_b64_tr_b16 v[32:33], v98 offset:55392
	ds_read_b64_tr_b16 v[34:35], v98 offset:57696
	s_waitcnt lgkmcnt(2)
	v_mfma_f32_16x16x32_bf16 v[28:31], v[28:31], v[12:15], v[38:41]
	s_waitcnt lgkmcnt(0)
	v_mfma_f32_16x16x32_bf16 v[12:15], v[32:35], v[12:15], v[20:23]
	s_nop 2
	v_rcp_f32_e32 v20, v11
	s_nop 0
	v_fma_f32 v21, -v11, v20, 1.0
	v_fmac_f32_e32 v20, v21, v20
	v_div_scale_f32 v21, vcc, 1.0, v10, 1.0
	v_mul_f32_e32 v22, v21, v20
	v_fma_f32 v23, -v11, v22, v21
	v_fmac_f32_e32 v22, v23, v20
	v_fma_f32 v11, -v11, v22, v21
	v_div_fmas_f32 v11, v11, v20, v22
	v_div_fixup_f32 v10, v11, v10, 1.0
	v_pk_mul_f32 v[18:19], v[10:11], v[18:19] op_sel_hi:[0,1]
	v_pk_mul_f32 v[16:17], v[10:11], v[16:17] op_sel_hi:[0,1]
	v_pk_mul_f32 v[20:21], v[10:11], v[26:27] op_sel_hi:[0,1]
	v_pk_mul_f32 v[22:23], v[10:11], v[24:25] op_sel_hi:[0,1]
	v_cvt_pk_bf16_f32 v16, v16, v17
	v_cvt_pk_bf16_f32 v17, v18, v19
	v_cvt_pk_bf16_f32 v18, v22, v23
	v_cvt_pk_bf16_f32 v19, v20, v21
	global_store_dwordx4 v[58:59], v[16:19], off offset:768
	v_pk_mul_f32 v[14:15], v[10:11], v[14:15] op_sel_hi:[0,1]
	v_pk_mul_f32 v[12:13], v[10:11], v[12:13] op_sel_hi:[0,1]
	v_pk_mul_f32 v[16:17], v[10:11], v[30:31] op_sel_hi:[0,1]
	v_pk_mul_f32 v[18:19], v[10:11], v[28:29] op_sel_hi:[0,1]
	v_cvt_pk_bf16_f32 v10, v18, v19
	v_cvt_pk_bf16_f32 v11, v16, v17
	v_cvt_pk_bf16_f32 v12, v12, v13
	v_cvt_pk_bf16_f32 v13, v14, v15
	global_store_dwordx4 v[58:59], v[10:13], off offset:832
	s_nop 1
	v_cvt_f32_ubyte0_e32 v10, s17
	v_mul_f32_e32 v10, -0.5, v10
	v_exp_f32_e32 v54, v10
	ds_read_b128 v[10:13], v100
	ds_read_b128 v[14:17], v100 offset:64
	s_waitcnt vmcnt(15) lgkmcnt(1)
	v_mfma_f32_16x16x32_bf16 v[10:13], v[10:13], v[6:9], 0
	s_waitcnt vmcnt(14) lgkmcnt(0)
	v_mfma_f32_16x16x32_bf16 v[10:13], v[14:17], v[2:5], v[10:13]
	ds_read_b128 v[14:17], v100 offset:2304
	ds_read_b128 v[18:21], v100 offset:2368
	s_waitcnt lgkmcnt(1)
	v_mfma_f32_16x16x32_bf16 v[14:17], v[14:17], v[6:9], 0
	s_waitcnt lgkmcnt(0)
	v_mfma_f32_16x16x32_bf16 v[14:17], v[18:21], v[2:5], v[14:17]
	ds_read_b128 v[18:21], v100 offset:4608
	ds_read_b128 v[22:25], v100 offset:4672
	s_waitcnt lgkmcnt(1)
	v_mfma_f32_16x16x32_bf16 v[18:21], v[18:21], v[6:9], 0
	s_waitcnt lgkmcnt(0)
	v_mfma_f32_16x16x32_bf16 v[18:21], v[22:25], v[2:5], v[18:21]
	ds_read_b128 v[22:25], v100 offset:6912
	ds_read_b128 v[26:29], v100 offset:6976
	s_waitcnt lgkmcnt(1)
	v_mfma_f32_16x16x32_bf16 v[22:25], v[22:25], v[6:9], 0
	s_waitcnt lgkmcnt(0)
	v_mfma_f32_16x16x32_bf16 v[22:25], v[26:29], v[2:5], v[22:25]
	ds_read_b128 v[26:29], v100 offset:9216
	ds_read_b128 v[30:33], v100 offset:9280
	s_waitcnt lgkmcnt(1)
	v_mfma_f32_16x16x32_bf16 v[26:29], v[26:29], v[6:9], 0
	s_waitcnt lgkmcnt(0)
	v_mfma_f32_16x16x32_bf16 v[26:29], v[30:33], v[2:5], v[26:29]
	ds_read_b128 v[30:33], v100 offset:11520
	ds_read_b128 v[34:37], v100 offset:11584
	s_waitcnt lgkmcnt(1)
	v_mfma_f32_16x16x32_bf16 v[30:33], v[30:33], v[6:9], 0
	s_waitcnt lgkmcnt(0)
	v_mfma_f32_16x16x32_bf16 v[30:33], v[34:37], v[2:5], v[30:33]
	ds_read_b128 v[34:37], v100 offset:13824
	ds_read_b128 v[38:41], v100 offset:13888
	s_waitcnt lgkmcnt(1)
	v_mfma_f32_16x16x32_bf16 v[34:37], v[34:37], v[6:9], 0
	s_waitcnt lgkmcnt(0)
	v_mfma_f32_16x16x32_bf16 v[34:37], v[38:41], v[2:5], v[34:37]
	ds_read_b128 v[38:41], v100 offset:16128
	ds_read_b128 v[42:45], v100 offset:16192
	s_waitcnt lgkmcnt(1)
	v_mfma_f32_16x16x32_bf16 v[38:41], v[38:41], v[6:9], 0
	s_waitcnt lgkmcnt(0)
	v_mfma_f32_16x16x32_bf16 v[38:41], v[42:45], v[2:5], v[38:41]
	ds_read_b128 v[42:45], v100 offset:18432
	ds_read_b128 v[46:49], v100 offset:18496
	s_waitcnt lgkmcnt(1)
	v_mfma_f32_16x16x32_bf16 v[42:45], v[42:45], v[6:9], 0
	s_waitcnt lgkmcnt(0)
	v_mfma_f32_16x16x32_bf16 v[42:45], v[46:49], v[2:5], v[42:45]
	ds_read_b128 v[46:49], v100 offset:20736
	ds_read_b128 v[50:53], v100 offset:20800
	s_waitcnt lgkmcnt(1)
	v_mfma_f32_16x16x32_bf16 v[6:9], v[46:49], v[6:9], 0
	s_waitcnt lgkmcnt(0)
	v_mfma_f32_16x16x32_bf16 v[2:5], v[50:53], v[2:5], v[6:9]
	s_nop 5
	v_mul_f32_e32 v6, 0xbfb8aa3b, v54
	v_mul_f32_e32 v7, 0x3e38aa3b, v10
	v_mul_f32_e32 v8, 0x3e38aa3b, v11
	v_fmac_f32_e32 v7, v129, v6
	v_fmac_f32_e32 v8, v130, v6
	v_mul_f32_e32 v10, 0x3e38aa3b, v12
	v_mul_f32_e32 v11, 0x3e38aa3b, v13
	v_max3_f32 v9, v7, s75, v8
	v_fmac_f32_e32 v10, v131, v6
	v_fmac_f32_e32 v11, v132, v6
	v_mul_f32_e32 v12, 0x3e38aa3b, v14
	v_mul_f32_e32 v13, 0x3e38aa3b, v15
	v_max3_f32 v9, v9, v10, v11
	v_fmac_f32_e32 v12, v133, v6
	v_fmac_f32_e32 v13, v134, v6
	v_mul_f32_e32 v14, 0x3e38aa3b, v16
	v_mul_f32_e32 v15, 0x3e38aa3b, v17
	v_max3_f32 v9, v9, v12, v13
	v_fmac_f32_e32 v14, v135, v6
	v_fmac_f32_e32 v15, v136, v6
	v_mul_f32_e32 v16, 0x3e38aa3b, v18
	v_mul_f32_e32 v17, 0x3e38aa3b, v19
	v_max3_f32 v9, v9, v14, v15
	v_fmac_f32_e32 v16, v137, v6
	v_fmac_f32_e32 v17, v138, v6
	v_mul_f32_e32 v18, 0x3e38aa3b, v20
	v_mul_f32_e32 v20, 0x3e38aa3b, v21
	v_max3_f32 v9, v9, v16, v17
	v_fmac_f32_e32 v18, v139, v6
	v_fmac_f32_e32 v20, v140, v6
	v_mul_f32_e32 v21, 0x3e38aa3b, v22
	v_mul_f32_e32 v22, 0x3e38aa3b, v23
	v_max3_f32 v9, v9, v18, v20
	v_fmac_f32_e32 v21, v141, v6
	v_fmac_f32_e32 v22, v142, v6
	v_mul_f32_e32 v23, 0x3e38aa3b, v24
	v_mul_f32_e32 v24, 0x3e38aa3b, v25
	v_max3_f32 v9, v9, v21, v22
	v_fmac_f32_e32 v23, v143, v6
	v_fmac_f32_e32 v24, v144, v6
	v_mul_f32_e32 v25, 0x3e38aa3b, v26
	v_mul_f32_e32 v26, 0x3e38aa3b, v27
	v_max3_f32 v9, v9, v23, v24
	v_fmac_f32_e32 v25, v145, v6
	v_fmac_f32_e32 v26, v146, v6
	v_mul_f32_e32 v27, 0x3e38aa3b, v28
	v_mul_f32_e32 v28, 0x3e38aa3b, v29
	v_max3_f32 v9, v9, v25, v26
	v_fmac_f32_e32 v27, v147, v6
	v_fmac_f32_e32 v28, v148, v6
	v_mul_f32_e32 v29, 0x3e38aa3b, v30
	v_mul_f32_e32 v30, 0x3e38aa3b, v31
	v_max3_f32 v9, v9, v27, v28
	v_fmac_f32_e32 v29, v149, v6
	v_fmac_f32_e32 v30, v150, v6
	v_mul_f32_e32 v31, 0x3e38aa3b, v32
	v_mul_f32_e32 v32, 0x3e38aa3b, v33
	v_max3_f32 v9, v9, v29, v30
	v_fmac_f32_e32 v31, v151, v6
	v_fmac_f32_e32 v32, v152, v6
	v_mul_f32_e32 v33, 0x3e38aa3b, v34
	v_mul_f32_e32 v34, 0x3e38aa3b, v35
	v_max3_f32 v9, v9, v31, v32
	v_fmac_f32_e32 v33, v153, v6
	v_fmac_f32_e32 v34, v154, v6
	v_mul_f32_e32 v35, 0x3e38aa3b, v36
	v_mul_f32_e32 v36, 0x3e38aa3b, v37
	v_max3_f32 v9, v9, v33, v34
	v_fmac_f32_e32 v35, v155, v6
	v_fmac_f32_e32 v36, v156, v6
	v_mul_f32_e32 v37, 0x3e38aa3b, v38
	v_mul_f32_e32 v38, 0x3e38aa3b, v39
	v_max3_f32 v9, v9, v35, v36
	v_fmac_f32_e32 v37, v157, v6
	v_fmac_f32_e32 v38, v158, v6
	v_mul_f32_e32 v39, 0x3e38aa3b, v40
	v_mul_f32_e32 v40, 0x3e38aa3b, v41
	v_max3_f32 v9, v9, v37, v38
	v_fmac_f32_e32 v39, v159, v6
	v_fmac_f32_e32 v40, v160, v6
	v_mul_f32_e32 v41, 0x3e38aa3b, v42
	v_mul_f32_e32 v42, 0x3e38aa3b, v43
	v_max3_f32 v9, v9, v39, v40
	v_fmac_f32_e32 v41, v161, v6
	v_fmac_f32_e32 v42, v162, v6
	v_mul_f32_e32 v43, 0x3e38aa3b, v44
	v_mul_f32_e32 v44, 0x3e38aa3b, v45
	v_max3_f32 v9, v9, v41, v42
	v_fmac_f32_e32 v43, v163, v6
	v_fmac_f32_e32 v44, v164, v6
	v_mul_f32_e32 v2, 0x3e38aa3b, v2
	v_mul_f32_e32 v45, 0x3e38aa3b, v3
	v_max3_f32 v9, v9, v43, v44
	v_fmac_f32_e32 v2, v165, v6
	v_fmac_f32_e32 v45, v166, v6
	v_max3_f32 v3, v9, v2, v45
	v_mul_f32_e32 v9, 0x3e38aa3b, v4
	v_mul_f32_e32 v46, 0x3e38aa3b, v5
	v_fmac_f32_e32 v9, v167, v6
	v_fmac_f32_e32 v46, v168, v6
	v_max3_f32 v3, v3, v9, v46
	v_mov_b32_e32 v5, v3
	s_nop 1
	v_permlane16_swap_b32_e32 v5, v3
	v_mul_f32_e32 v4, s4, v249
	s_waitcnt lgkmcnt(0)
	v_max_f32_e32 v5, v5, v5
	v_max_f32_e32 v3, v3, v5
	v_mov_b32_e32 v5, v3
	s_nop 1
	v_permlane32_swap_b32_e32 v5, v3
	s_waitcnt lgkmcnt(0)
	v_max3_f32 v47, v3, v5, v4
	v_sub_f32_e32 v3, v7, v47
	v_exp_f32_e32 v48, v3
	v_sub_f32_e32 v4, v8, v47
	v_exp_f32_e32 v49, v4
	v_sub_f32_e32 v4, v10, v47
	v_exp_f32_e32 v50, v4
	v_sub_f32_e32 v4, v11, v47
	v_exp_f32_e32 v51, v4
	v_sub_f32_e32 v4, v12, v47
	v_add_f32_e32 v3, 0, v48
	v_exp_f32_e32 v52, v4
	v_sub_f32_e32 v4, v13, v47
	v_add_f32_e32 v3, v49, v3
	v_exp_f32_e32 v53, v4
	v_sub_f32_e32 v4, v14, v47
	v_add_f32_e32 v3, v50, v3
	v_exp_f32_e32 v54, v4
	v_sub_f32_e32 v4, v15, v47
	v_add_f32_e32 v3, v51, v3
	v_exp_f32_e32 v55, v4
	v_sub_f32_e32 v4, v16, v47
	v_add_f32_e32 v3, v52, v3
	v_exp_f32_e32 v19, v4
	v_sub_f32_e32 v4, v17, v47
	v_add_f32_e32 v3, v53, v3
	v_exp_f32_e32 v56, v4
	v_sub_f32_e32 v4, v18, v47
	v_add_f32_e32 v3, v54, v3
	v_exp_f32_e32 v57, v4
	v_sub_f32_e32 v4, v20, v47
	v_add_f32_e32 v3, v55, v3
	v_exp_f32_e32 v60, v4
	v_sub_f32_e32 v4, v21, v47
	v_add_f32_e32 v3, v19, v3
	v_exp_f32_e32 v61, v4
	v_sub_f32_e32 v4, v22, v47
	v_add_f32_e32 v3, v56, v3
	v_exp_f32_e32 v62, v4
	v_sub_f32_e32 v4, v23, v47
	v_add_f32_e32 v3, v57, v3
	v_exp_f32_e32 v23, v4
	v_sub_f32_e32 v4, v24, v47
	v_add_f32_e32 v3, v60, v3
	v_exp_f32_e32 v63, v4
	v_sub_f32_e32 v4, v25, v47
	v_add_f32_e32 v3, v61, v3
	v_exp_f32_e32 v14, v4
	v_sub_f32_e32 v4, v26, v47
	v_add_f32_e32 v3, v62, v3
	v_exp_f32_e32 v17, v4
	v_sub_f32_e32 v4, v27, v47
	v_add_f32_e32 v3, v23, v3
	v_exp_f32_e32 v18, v4
	v_sub_f32_e32 v4, v28, v47
	v_add_f32_e32 v3, v63, v3
	v_exp_f32_e32 v22, v4
	v_sub_f32_e32 v4, v29, v47
	v_add_f32_e32 v3, v14, v3
	v_exp_f32_e32 v64, v4
	v_sub_f32_e32 v4, v30, v47
	v_add_f32_e32 v3, v17, v3
	v_exp_f32_e32 v65, v4
	v_sub_f32_e32 v4, v31, v47
	v_add_f32_e32 v3, v18, v3
	v_exp_f32_e32 v66, v4
	v_sub_f32_e32 v4, v32, v47
	v_add_f32_e32 v3, v22, v3
	v_exp_f32_e32 v67, v4
	v_sub_f32_e32 v4, v33, v47
	v_add_f32_e32 v3, v64, v3
	v_exp_f32_e32 v11, v4
	v_sub_f32_e32 v4, v34, v47
	v_add_f32_e32 v3, v65, v3
	v_exp_f32_e32 v12, v4
	v_sub_f32_e32 v4, v35, v47
	v_add_f32_e32 v3, v66, v3
	v_exp_f32_e32 v13, v4
	v_sub_f32_e32 v4, v36, v47
	v_add_f32_e32 v3, v67, v3
	v_exp_f32_e32 v15, v4
	v_sub_f32_e32 v4, v37, v47
	v_add_f32_e32 v3, v11, v3
	v_exp_f32_e32 v16, v4
	v_sub_f32_e32 v4, v38, v47
	v_add_f32_e32 v3, v12, v3
	v_exp_f32_e32 v20, v4
	v_sub_f32_e32 v4, v39, v47
	v_add_f32_e32 v3, v13, v3
	v_exp_f32_e32 v21, v4
	v_sub_f32_e32 v4, v40, v47
	v_add_f32_e32 v3, v15, v3
	v_exp_f32_e32 v68, v4
	v_add_f32_e32 v3, v16, v3
	v_add_f32_e32 v3, v20, v3
	v_add_f32_e32 v3, v21, v3
	v_add_f32_e32 v4, v68, v3
	v_sub_f32_e32 v3, v41, v47
	v_exp_f32_e32 v3, v3
	v_sub_f32_e32 v2, v2, v47
	v_sub_f32_e32 v9, v9, v47
	v_exp_f32_e32 v9, v9
	v_add_f32_e32 v5, v3, v4
	v_sub_f32_e32 v4, v42, v47
	v_exp_f32_e32 v4, v4
	v_sub_f32_e32 v10, v46, v47
	v_exp_f32_e32 v10, v10
	v_add_f32_e32 v6, v4, v5
	v_sub_f32_e32 v5, v43, v47
	v_exp_f32_e32 v5, v5
	s_nop 0
	v_add_f32_e32 v7, v5, v6
	v_sub_f32_e32 v6, v44, v47
	v_exp_f32_e32 v6, v6
	s_nop 0
	v_add_f32_e32 v8, v6, v7
	v_exp_f32_e32 v7, v2
	s_nop 0
	v_add_f32_e32 v2, v7, v8
	v_sub_f32_e32 v8, v45, v47
	v_exp_f32_e32 v8, v8
	s_nop 0
	v_add_f32_e32 v2, v8, v2
	v_add_f32_e32 v2, v9, v2
	v_add_f32_e32 v2, v10, v2
	v_mov_b32_e32 v24, v2
	s_nop 1
	v_permlane16_swap_b32_e32 v24, v2
	s_waitcnt lgkmcnt(0)
	v_add_f32_e32 v2, v2, v24
	v_mov_b32_e32 v24, v2
	s_nop 1
	v_permlane32_swap_b32_e32 v24, v2
	s_waitcnt lgkmcnt(0)
	v_add_f32_e32 v2, v2, v24
	v_fma_f32 v24, s4, v249, -v47
	v_exp_f32_e32 v24, v24
	s_nop 0
	v_add_f32_e32 v2, v24, v2
	v_cvt_pk_bf16_f32 v24, v48, v49
	v_cvt_pk_bf16_f32 v25, v50, v51
	v_cvt_pk_bf16_f32 v26, v52, v53
	v_cvt_pk_bf16_f32 v27, v54, v55
	ds_read_b64_tr_b16 v[30:31], v98 offset:39168
	ds_read_b64_tr_b16 v[28:29], v98 offset:36864
	ds_read_b64_tr_b16 v[32:33], v98 offset:36896
	ds_read_b64_tr_b16 v[34:35], v98 offset:39200
	ds_read_b64_tr_b16 v[36:37], v98 offset:36928
	ds_read_b64_tr_b16 v[38:39], v98 offset:39232
	ds_read_b64_tr_b16 v[40:41], v98 offset:36960
	ds_read_b64_tr_b16 v[42:43], v98 offset:39264
	s_waitcnt lgkmcnt(6)
	v_mfma_f32_16x16x32_bf16 v[28:31], v[28:31], v[24:27], 0
	s_waitcnt lgkmcnt(4)
	v_mfma_f32_16x16x32_bf16 v[32:35], v[32:35], v[24:27], 0
	s_waitcnt lgkmcnt(2)
	v_mfma_f32_16x16x32_bf16 v[36:39], v[36:39], v[24:27], 0
	s_waitcnt lgkmcnt(0)
	v_mfma_f32_16x16x32_bf16 v[24:27], v[40:43], v[24:27], 0
	v_cvt_pk_bf16_f32 v40, v19, v56
	v_cvt_pk_bf16_f32 v41, v57, v60
	v_cvt_pk_bf16_f32 v42, v61, v62
	v_cvt_pk_bf16_f32 v43, v23, v63
	ds_read_b64_tr_b16 v[46:47], v98 offset:43776
	ds_read_b64_tr_b16 v[44:45], v98 offset:41472
	ds_read_b64_tr_b16 v[48:49], v98 offset:41504
	s_waitcnt lgkmcnt(1)
	v_mfma_f32_16x16x32_bf16 v[28:31], v[44:47], v[40:43], v[28:31]
	ds_read_b64_tr_b16 v[50:51], v98 offset:43808
	ds_read_b64_tr_b16 v[44:45], v98 offset:41536
	ds_read_b64_tr_b16 v[46:47], v98 offset:43840
	s_waitcnt lgkmcnt(0)
	v_mfma_f32_16x16x32_bf16 v[36:39], v[44:47], v[40:43], v[36:39]
	ds_read_b64_tr_b16 v[44:45], v98 offset:41568
	ds_read_b64_tr_b16 v[46:47], v98 offset:43872
	v_mfma_f32_16x16x32_bf16 v[32:35], v[48:51], v[40:43], v[32:35]
	s_waitcnt lgkmcnt(0)
	v_mfma_f32_16x16x32_bf16 v[24:27], v[44:47], v[40:43], v[24:27]
	v_cvt_pk_bf16_f32 v40, v14, v17
	v_cvt_pk_bf16_f32 v41, v18, v22
	v_cvt_pk_bf16_f32 v42, v64, v65
	v_cvt_pk_bf16_f32 v43, v66, v67
	ds_read_b64_tr_b16 v[46:47], v98 offset:48384
	ds_read_b64_tr_b16 v[44:45], v98 offset:46080
	ds_read_b64_tr_b16 v[48:49], v98 offset:46112
	s_waitcnt lgkmcnt(1)
	v_mfma_f32_16x16x32_bf16 v[28:31], v[44:47], v[40:43], v[28:31]
	ds_read_b64_tr_b16 v[50:51], v98 offset:48416
	ds_read_b64_tr_b16 v[44:45], v98 offset:46144
	ds_read_b64_tr_b16 v[46:47], v98 offset:48448
	s_waitcnt lgkmcnt(0)
	v_mfma_f32_16x16x32_bf16 v[36:39], v[44:47], v[40:43], v[36:39]
	ds_read_b64_tr_b16 v[44:45], v98 offset:46176
	ds_read_b64_tr_b16 v[46:47], v98 offset:48480
	v_cvt_pk_bf16_f32 v12, v11, v12
	v_cvt_pk_bf16_f32 v13, v13, v15
	s_waitcnt lgkmcnt(0)
	v_mfma_f32_16x16x32_bf16 v[22:25], v[44:47], v[40:43], v[24:27]
	v_cvt_pk_bf16_f32 v14, v16, v20
	v_cvt_pk_bf16_f32 v15, v21, v68
	ds_read_b64_tr_b16 v[18:19], v98 offset:52992
	ds_read_b64_tr_b16 v[16:17], v98 offset:50688
	s_nop 0
	ds_read_b64_tr_b16 v[26:27], v98 offset:50720
	s_waitcnt lgkmcnt(1)
	v_mfma_f32_16x16x32_bf16 v[16:19], v[16:19], v[12:15], v[28:31]
	s_nop 2
	ds_read_b64_tr_b16 v[28:29], v98 offset:53024
	v_mfma_f32_16x16x32_bf16 v[32:35], v[48:51], v[40:43], v[32:35]
	s_waitcnt lgkmcnt(0)
	v_mfma_f32_16x16x32_bf16 v[26:29], v[26:29], v[12:15], v[32:35]
	ds_read_b64_tr_b16 v[30:31], v98 offset:50752
	s_nop 4
	ds_read_b64_tr_b16 v[32:33], v98 offset:53056
	s_waitcnt lgkmcnt(0)
	v_mfma_f32_16x16x32_bf16 v[30:33], v[30:33], v[12:15], v[36:39]
	ds_read_b64_tr_b16 v[34:35], v98 offset:50784
	s_nop 1
	ds_read_b64_tr_b16 v[36:37], v98 offset:53088
	v_cvt_pk_bf16_f32 v4, v3, v4
	v_cvt_pk_bf16_f32 v5, v5, v6
	s_waitcnt lgkmcnt(0)
	v_mfma_f32_16x16x32_bf16 v[12:15], v[34:37], v[12:15], v[22:25]
	v_cvt_pk_bf16_f32 v6, v7, v8
	v_cvt_pk_bf16_f32 v7, v9, v10
	ds_read_b64_tr_b16 v[10:11], v98 offset:57600
	ds_read_b64_tr_b16 v[8:9], v98 offset:55296
	ds_read_b64_tr_b16 v[20:21], v98 offset:55328
	ds_read_b64_tr_b16 v[22:23], v98 offset:57632
	s_waitcnt lgkmcnt(2)
	v_mfma_f32_16x16x32_bf16 v[8:11], v[8:11], v[4:7], v[16:19]
	v_div_scale_f32 v3, s[4:5], v2, v2, 1.0
	s_waitcnt lgkmcnt(0)
	v_mfma_f32_16x16x32_bf16 v[16:19], v[20:23], v[4:7], v[26:29]
	ds_read_b64_tr_b16 v[20:21], v98 offset:55360
	ds_read_b64_tr_b16 v[22:23], v98 offset:57664
	ds_read_b64_tr_b16 v[24:25], v98 offset:55392
	ds_read_b64_tr_b16 v[26:27], v98 offset:57696
	s_waitcnt lgkmcnt(2)
	v_mfma_f32_16x16x32_bf16 v[20:23], v[20:23], v[4:7], v[30:33]
	s_waitcnt lgkmcnt(0)
	v_mfma_f32_16x16x32_bf16 v[4:7], v[24:27], v[4:7], v[12:15]
	s_nop 2
	v_rcp_f32_e32 v12, v3
	s_nop 0
	v_fma_f32 v13, -v3, v12, 1.0
	v_fmac_f32_e32 v12, v13, v12
	v_div_scale_f32 v13, vcc, 1.0, v2, 1.0
	v_mul_f32_e32 v14, v13, v12
	v_fma_f32 v15, -v3, v14, v13
	v_fmac_f32_e32 v14, v15, v12
	v_fma_f32 v3, -v3, v14, v13
	v_div_fmas_f32 v3, v3, v12, v14
	v_div_fixup_f32 v2, v3, v2, 1.0
	v_pk_mul_f32 v[10:11], v[2:3], v[10:11] op_sel_hi:[0,1]
	v_pk_mul_f32 v[8:9], v[2:3], v[8:9] op_sel_hi:[0,1]
	v_pk_mul_f32 v[12:13], v[2:3], v[18:19] op_sel_hi:[0,1]
	v_pk_mul_f32 v[14:15], v[2:3], v[16:17] op_sel_hi:[0,1]
	v_cvt_pk_bf16_f32 v8, v8, v9
	v_cvt_pk_bf16_f32 v9, v10, v11
	v_cvt_pk_bf16_f32 v10, v14, v15
	v_cvt_pk_bf16_f32 v11, v12, v13
	v_pk_mul_f32 v[4:5], v[2:3], v[4:5] op_sel_hi:[0,1]
	global_store_dwordx4 v[58:59], v[8:11], off offset:896
	v_pk_mul_f32 v[6:7], v[2:3], v[6:7] op_sel_hi:[0,1]
	s_nop 0
	v_pk_mul_f32 v[8:9], v[2:3], v[22:23] op_sel_hi:[0,1]
	v_pk_mul_f32 v[10:11], v[2:3], v[20:21] op_sel_hi:[0,1]
	v_cvt_pk_bf16_f32 v2, v10, v11
	v_cvt_pk_bf16_f32 v3, v8, v9
	v_cvt_pk_bf16_f32 v4, v4, v5
	v_cvt_pk_bf16_f32 v5, v6, v7
	global_store_dwordx4 v[58:59], v[2:5], off offset:960
	s_barrier
	s_cbranch_scc1 .LBB0_925
.LBB0_917:
	s_and_b32 s15, s9, 1
	s_lshl_b32 s17, s15, 3
	v_or_b32_e32 v2, s17, v105
	v_lshlrev_b32_e32 v2, 2, v2
	global_load_dword v128, v2, s[12:13]
	s_ashr_i32 s14, s9, 1
	s_lshl_b32 s18, s14, 7
	s_add_i32 s23, s18, 0xffffff80
	v_readfirstlane_b32 s19, v1
	s_lshl_b32 s22, s15, 6
	v_lshlrev_b32_e32 v12, 1, v90
	v_mov_b32_e32 v13, v223
	s_lshl_b32 s80, s22, 1
	v_add_u32_e32 v3, s23, v106
	v_cmp_lt_i32_e32 vcc, -1, v3
	v_mov_b32_e32 v200, 0
	v_mov_b32_e32 v201, 0
	v_mov_b32_e32 v202, 0
	v_mov_b32_e32 v203, 0
	v_mov_b32_e32 v204, 0
	v_mov_b32_e32 v205, 0
	v_mov_b32_e32 v206, 0
	v_mov_b32_e32 v207, 0
	s_and_saveexec_b64 s[4:5], vcc
	s_cbranch_execz .Latt_kv_g0
	v_mov_b64_e32 v[204:205], s[6:7]
	v_mad_u64_u32 v[204:205], s[28:29], v3, s73, v[204:205]
	v_lshl_add_u64 v[204:205], v[204:205], 0, s[80:81]
	v_lshl_add_u64 v[204:205], v[204:205], 0, v[12:13]
	global_load_dwordx4 v[200:203], v[204:205], off offset:2048 nt
	s_nop 0
	global_load_dwordx4 v[204:207], v[204:205], off offset:2304 nt
.Latt_kv_g0:
	s_or_b64 exec, exec, s[4:5]
	v_add_u32_e32 v3, s23, v107
	v_cmp_lt_i32_e32 vcc, -1, v3
	v_mov_b32_e32 v208, 0
	v_mov_b32_e32 v209, 0
	v_mov_b32_e32 v210, 0
	v_mov_b32_e32 v211, 0
	v_mov_b32_e32 v212, 0
	v_mov_b32_e32 v213, 0
	v_mov_b32_e32 v214, 0
	v_mov_b32_e32 v215, 0
	s_and_saveexec_b64 s[4:5], vcc
	s_cbranch_execz .Latt_kv_g1
	v_mov_b64_e32 v[212:213], s[6:7]
	v_mad_u64_u32 v[212:213], s[28:29], v3, s73, v[212:213]
	v_lshl_add_u64 v[212:213], v[212:213], 0, s[80:81]
	v_lshl_add_u64 v[212:213], v[212:213], 0, v[12:13]
	global_load_dwordx4 v[208:211], v[212:213], off offset:2048 nt
	s_nop 0
	global_load_dwordx4 v[212:215], v[212:213], off offset:2304 nt
.Latt_kv_g1:
	s_or_b64 exec, exec, s[4:5]
	v_add_u32_e32 v3, s23, v108
	v_cmp_lt_i32_e32 vcc, -1, v3
	v_mov_b32_e32 v226, 0
	v_mov_b32_e32 v227, 0
	v_mov_b32_e32 v228, 0
	v_mov_b32_e32 v229, 0
	v_mov_b32_e32 v230, 0
	v_mov_b32_e32 v231, 0
	v_mov_b32_e32 v232, 0
	v_mov_b32_e32 v233, 0
	s_and_saveexec_b64 s[4:5], vcc
	s_cbranch_execz .Latt_kv_g2
	v_mov_b64_e32 v[230:231], s[6:7]
	v_mad_u64_u32 v[230:231], s[28:29], v3, s73, v[230:231]
	v_lshl_add_u64 v[230:231], v[230:231], 0, s[80:81]
	v_lshl_add_u64 v[230:231], v[230:231], 0, v[12:13]
	global_load_dwordx4 v[226:229], v[230:231], off offset:2048 nt
	s_nop 0
	global_load_dwordx4 v[230:233], v[230:231], off offset:2304 nt
.Latt_kv_g2:
	s_or_b64 exec, exec, s[4:5]
	v_add_u32_e32 v10, s23, v109
	v_cmp_lt_i32_e32 vcc, -1, v10
	v_mov_b32_e32 v2, 0
	v_mov_b32_e32 v3, 0
	v_mov_b32_e32 v4, 0
	v_mov_b32_e32 v5, 0
	v_mov_b32_e32 v6, 0
	v_mov_b32_e32 v7, 0
	v_mov_b32_e32 v8, 0
	v_mov_b32_e32 v9, 0
	s_and_saveexec_b64 s[4:5], vcc
	s_cbranch_execz .LBB0_916
	v_mov_b64_e32 v[2:3], s[6:7]
	v_mad_u64_u32 v[2:3], s[28:29], v10, s73, v[2:3]
	v_lshl_add_u64 v[2:3], v[2:3], 0, s[80:81]
	v_lshl_add_u64 v[2:3], v[2:3], 0, v[12:13]
	global_load_dwordx4 v[6:9], v[2:3], off offset:2048 nt
	s_nop 0
	global_load_dwordx4 v[2:5], v[2:3], off offset:2304 nt
	s_branch .LBB0_916
